# merge epilogue gate loads kept 5 in flight (counted waits, copies into original registers) + gemm_in q/k epilogue: 4 norm-weight loads per row group issued together
# speedup vs baseline: 1.0071x; 1.0071x over previous
; DI unsigned pk2(float a, float b) { f32x2 v = {a, b}; bfv2 r = __builtin_convertvector(v, bfv2); return __builtin_bit_cast(unsigned, r); }
; DI void phase_gemm_in(const Params& p, int l, char* lds) {
;     ...
;       } else if (kind == 2 || kind == 3) {
;         float ss = 0.f;
; #pragma unroll
;         for (int ni = 0; ni < 4; ++ni) { const f32x4 v = acc[mi][ni]; ss += v[0] * v[0] + v[1] * v[1] + v[2] * v[2] + v[3] * v[3]; }
;         ss += __shfl_xor(ss, 16); ss += __shfl_xor(ss, 32);
;         const float rstd = rsqrtf(ss * (1.0f / 64.0f) + 1e-6f);
;         const float* g = (kind == 2 ? p.qng : p.kng) + l * 64;
;         float* ko = isp ? p.out + O_KP + ((size_t)l * MP + R) * 512 : p.out + O_KS + ((size_t)l * MS + rs) * 512;
; #pragma unroll
;         for (int ni = 0; ni < 4; ++ni) {
;           const int c = colb + ni * 16; const int d = ni * 16 + quad * 4;
;           const f32x4 gv = *(const f32x4*)(g + d); f32x4 v = acc[mi][ni];
; #pragma unroll
;           for (int e = 0; e < 4; ++e) v[e] = v[e] * rstd * gv[e];
;           u32x2 o; o[0] = pk2(v[0], v[1]); o[1] = pk2(v[2], v[3]); *(u32x2*)(zrow + c) = o;
;           if (kind == 3) *(f32x4*)(ko + (c - C_K)) = v;
;         }
.LBB0_85:
	s_and_b64 vcc, exec, s[38:39]
	s_cbranch_vccz .LBB0_94
	v_mov_b32_e32 v78, v55
	v_mov_b32_e32 v79, v51
	v_mov_b32_e32 v68, v54
	v_mov_b32_e32 v69, v50
	v_pk_mul_f32 v[78:79], v[78:79], v[78:79]
	v_mov_b32_e32 v80, v63
	v_pk_fma_f32 v[68:69], v[68:69], v[68:69], v[78:79]
	v_mov_b32_e32 v78, v56
	v_mov_b32_e32 v79, v52
	v_pk_fma_f32 v[68:69], v[78:79], v[78:79], v[68:69]
	v_mov_b32_e32 v78, v57
	v_mov_b32_e32 v79, v53
	v_pk_fma_f32 v[68:69], v[78:79], v[78:79], v[68:69]
	v_mov_b32_e32 v81, v59
	v_mov_b32_e32 v78, v62
	v_mov_b32_e32 v79, v58
	v_pk_mul_f32 v[80:81], v[80:81], v[80:81]
	v_add_f32_e32 v0, v68, v69
	v_mbcnt_hi_u32_b32 v68, -1, v213
	v_pk_fma_f32 v[78:79], v[78:79], v[78:79], v[80:81]
	v_mov_b32_e32 v80, v64
	v_mov_b32_e32 v81, v60
	v_and_b32_e32 v75, 64, v68
	v_pk_fma_f32 v[78:79], v[80:81], v[80:81], v[78:79]
	v_mov_b32_e32 v80, v65
	v_mov_b32_e32 v81, v61
	v_xor_b32_e32 v69, 16, v68
	v_add_u32_e32 v75, 64, v75
	v_pk_fma_f32 v[78:79], v[80:81], v[80:81], v[78:79]
	v_cmp_lt_i32_e32 vcc, v69, v75
	v_add_f32_e32 v0, v79, v0
	v_add_f32_e32 v0, v78, v0
	v_cndmask_b32_e32 v69, v68, v69, vcc
	v_lshlrev_b32_e32 v69, 2, v69
	ds_bpermute_b32 v69, v69, v0
	s_and_b64 s[38:39], s[24:25], exec
	v_readlane_b32 s68, v252, 3
	v_readlane_b32 s38, v254, 63
	v_readlane_b32 s76, v252, 11
	s_waitcnt lgkmcnt(0)
	v_add_f32_e32 v0, v0, v69
	v_xor_b32_e32 v69, 32, v68
	v_cmp_lt_i32_e32 vcc, v69, v75
	v_readlane_b32 s77, v252, 12
	v_readlane_b32 s78, v252, 13
	v_cndmask_b32_e32 v68, v68, v69, vcc
	v_lshlrev_b32_e32 v68, 2, v68
	ds_bpermute_b32 v68, v68, v0
	v_readlane_b32 s79, v252, 14
	v_readlane_b32 s39, v255, 0
	s_cselect_b32 s21, s77, s79
	s_cselect_b32 s40, s76, s78
	s_waitcnt lgkmcnt(0)
	v_add_f32_e32 v0, v0, v68
	v_fmamk_f32 v0, v0, 0x3c800000, v249
	v_cmp_gt_f32_e32 vcc, s34, v0
	v_mul_f32_e32 v68, 0x4b800000, v0
	s_lshl_b64 s[38:39], s[38:39], 2
	v_cndmask_b32_e32 v0, v0, v68, vcc
	v_rsq_f32_e32 v0, v0
	s_add_u32 s38, s40, s38
	s_addc_u32 s39, s21, s39
	v_readlane_b32 s21, v255, 11
	v_mul_f32_e32 v68, 0x45800000, v0
	v_cndmask_b32_e32 v78, v0, v68, vcc
	v_mov_b32_e32 v0, s21
	v_mov_b32_e32 v68, s48
	v_readlane_b32 s21, v255, 10
	v_cndmask_b32_e64 v69, v0, v68, s[0:1]
	v_mov_b32_e32 v68, s47
	v_mov_b32_e32 v0, s21
	v_cndmask_b32_e64 v68, v0, v68, s[0:1]
	v_lshlrev_b64 v[66:67], 11, v[66:67]
	v_lshlrev_b32_e32 v0, 2, v72
	v_lshl_add_u64 v[82:83], v[68:69], 0, v[66:67]
	global_load_dwordx4 v[66:69], v0, s[38:39]
	global_load_dwordx4 v[112:115], v0, s[38:39] offset:64
	global_load_dwordx4 v[116:119], v0, s[38:39] offset:128
	global_load_dwordx4 v[120:123], v0, s[38:39] offset:192
	v_pk_mul_f32 v[80:81], v[54:55], v[78:79] op_sel_hi:[1,0]
	v_mov_b32_e32 v75, v1
	s_andn2_b64 vcc, exec, s[22:23]
	v_lshl_add_u64 v[82:83], v[74:75], 2, v[82:83]
	v_readlane_b32 s69, v252, 4
	v_readlane_b32 s70, v252, 5
	v_readlane_b32 s71, v252, 6
	v_readlane_b32 s72, v252, 7
	v_readlane_b32 s73, v252, 8
	v_readlane_b32 s74, v252, 9
	v_readlane_b32 s75, v252, 10
	v_readlane_b32 s80, v252, 15
	v_readlane_b32 s81, v252, 16
	v_readlane_b32 s82, v252, 17
	v_readlane_b32 s83, v252, 18
	s_waitcnt vmcnt(3)
	v_pk_mul_f32 v[66:67], v[66:67], v[80:81]
	v_pk_mul_f32 v[80:81], v[56:57], v[78:79] op_sel_hi:[1,0]
	v_cndmask_b32_e64 v79, 0, 1, s[22:23]
	v_pk_mul_f32 v[68:69], v[68:69], v[80:81]
	v_cvt_pk_bf16_f32 v84, v66, v67
	v_cvt_pk_bf16_f32 v85, v68, v69
	v_lshl_add_u64 v[80:81], v[74:75], 1, v[76:77]
	v_cmp_ne_u32_e64 s[0:1], 1, v79
	global_store_dwordx2 v[80:81], v[84:85], off
	s_cbranch_vccnz .LBB0_88
	v_add_co_u32_e32 v84, vcc, 0xffffe000, v82
	s_nop 1
	v_addc_co_u32_e32 v85, vcc, -1, v83, vcc
	global_store_dwordx4 v[84:85], v[66:69], off offset:-2560
.LBB0_88:
	v_lshl_add_u64 v[86:87], s[38:39], 0, v[0:1]
	v_mov_b32_e32 v84, v78
	v_mov_b32_e32 v85, v78
	v_mov_b32_e32 v79, v78
	v_pk_mul_f32 v[88:89], v[50:51], v[84:85]
	s_and_b64 vcc, exec, s[0:1]
	s_waitcnt vmcnt(3)
	v_mov_b32_e32 v66, v112
	v_mov_b32_e32 v67, v113
	v_mov_b32_e32 v68, v114
	v_mov_b32_e32 v69, v115
	v_pk_mul_f32 v[66:67], v[88:89], v[66:67]
	v_pk_mul_f32 v[88:89], v[52:53], v[78:79]
	s_nop 0
	v_pk_mul_f32 v[68:69], v[88:89], v[68:69]
	v_cvt_pk_bf16_f32 v88, v66, v67
	v_cvt_pk_bf16_f32 v89, v68, v69
	global_store_dwordx2 v[80:81], v[88:89], off offset:32
	s_cbranch_vccnz .LBB0_90
	v_add_co_u32_e32 v88, vcc, 0xffffe000, v82
	s_nop 1
	v_addc_co_u32_e32 v89, vcc, -1, v83, vcc
	global_store_dwordx4 v[88:89], v[66:69], off offset:-2496
.LBB0_90:
	v_pk_mul_f32 v[88:89], v[58:59], v[84:85]
	s_and_b64 vcc, exec, s[0:1]
	s_waitcnt vmcnt(3)
	v_mov_b32_e32 v66, v116
	v_mov_b32_e32 v67, v117
	v_mov_b32_e32 v68, v118
	v_mov_b32_e32 v69, v119
	v_pk_mul_f32 v[66:67], v[88:89], v[66:67]
	v_pk_mul_f32 v[88:89], v[60:61], v[78:79]
	s_nop 0
	v_pk_mul_f32 v[68:69], v[88:89], v[68:69]
	v_cvt_pk_bf16_f32 v88, v66, v67
	v_cvt_pk_bf16_f32 v89, v68, v69
	global_store_dwordx2 v[80:81], v[88:89], off offset:64
	s_cbranch_vccnz .LBB0_92
	v_add_co_u32_e32 v88, vcc, 0xffffe000, v82
	s_nop 1
	v_addc_co_u32_e32 v89, vcc, -1, v83, vcc
	global_store_dwordx4 v[88:89], v[66:69], off offset:-2432
.LBB0_92:
	v_pk_mul_f32 v[84:85], v[62:63], v[84:85]
	v_pk_mul_f32 v[78:79], v[64:65], v[78:79]
	s_and_b64 vcc, exec, s[0:1]
	s_waitcnt vmcnt(3)
	v_mov_b32_e32 v66, v120
	v_mov_b32_e32 v67, v121
	v_mov_b32_e32 v68, v122
	v_mov_b32_e32 v69, v123
	v_pk_mul_f32 v[66:67], v[84:85], v[66:67]
	v_pk_mul_f32 v[68:69], v[78:79], v[68:69]
	v_cvt_pk_bf16_f32 v78, v66, v67
	v_cvt_pk_bf16_f32 v79, v68, v69
	global_store_dwordx2 v[80:81], v[78:79], off offset:96
	s_cbranch_vccnz .LBB0_94
	v_add_co_u32_e32 v78, vcc, 0xffffe000, v82
	s_mov_b64 s[0:1], 0
	s_nop 0
	v_addc_co_u32_e32 v79, vcc, -1, v83, vcc
	global_store_dwordx4 v[78:79], v[66:69], off offset:-2368
	s_branch .LBB0_95

; DI unsigned pk2(float a, float b) { f32x2 v = {a, b}; bfv2 r = __builtin_convertvector(v, bfv2); return __builtin_bit_cast(unsigned, r); }
; DI void phase_gemm_in(const Params& p, int l, char* lds) {
;     ...
;       } else if (kind == 2 || kind == 3) {
;         float ss = 0.f;
; #pragma unroll
;         for (int ni = 0; ni < 4; ++ni) { const f32x4 v = acc[mi][ni]; ss += v[0] * v[0] + v[1] * v[1] + v[2] * v[2] + v[3] * v[3]; }
;         ss += __shfl_xor(ss, 16); ss += __shfl_xor(ss, 32);
;         const float rstd = rsqrtf(ss * (1.0f / 64.0f) + 1e-6f);
;         const float* g = (kind == 2 ? p.qng : p.kng) + l * 64;
;         float* ko = isp ? p.out + O_KP + ((size_t)l * MP + R) * 512 : p.out + O_KS + ((size_t)l * MS + rs) * 512;
; #pragma unroll
;         for (int ni = 0; ni < 4; ++ni) {
;           const int c = colb + ni * 16; const int d = ni * 16 + quad * 4;
;           const f32x4 gv = *(const f32x4*)(g + d); f32x4 v = acc[mi][ni];
; #pragma unroll
;           for (int e = 0; e < 4; ++e) v[e] = v[e] * rstd * gv[e];
;           u32x2 o; o[0] = pk2(v[0], v[1]); o[1] = pk2(v[2], v[3]); *(u32x2*)(zrow + c) = o;
;           if (kind == 3) *(f32x4*)(ko + (c - C_K)) = v;
;         }
.LBB0_108:
	s_and_b64 vcc, exec, s[30:31]
	s_cbranch_vccz .LBB0_117
	v_mov_b32_e32 v56, v47
	v_mov_b32_e32 v57, v43
	v_mov_b32_e32 v52, v46
	v_mov_b32_e32 v53, v42
	v_pk_mul_f32 v[56:57], v[56:57], v[56:57]
	v_mov_b32_e32 v58, v35
	v_pk_fma_f32 v[52:53], v[52:53], v[52:53], v[56:57]
	v_mov_b32_e32 v56, v48
	v_mov_b32_e32 v57, v44
	v_pk_fma_f32 v[52:53], v[56:57], v[56:57], v[52:53]
	v_mov_b32_e32 v56, v49
	v_mov_b32_e32 v57, v45
	v_mov_b32_e32 v59, v39
	v_pk_fma_f32 v[52:53], v[56:57], v[56:57], v[52:53]
	v_mov_b32_e32 v56, v34
	v_mov_b32_e32 v57, v38
	v_pk_mul_f32 v[58:59], v[58:59], v[58:59]
	v_add_f32_e32 v0, v52, v53
	v_pk_fma_f32 v[56:57], v[56:57], v[56:57], v[58:59]
	v_mov_b32_e32 v58, v36
	v_mov_b32_e32 v59, v40
	v_pk_fma_f32 v[56:57], v[58:59], v[58:59], v[56:57]
	v_mov_b32_e32 v58, v37
	v_mov_b32_e32 v59, v41
	v_pk_fma_f32 v[56:57], v[58:59], v[58:59], v[56:57]
	v_mbcnt_hi_u32_b32 v52, -1, v213
	v_add_f32_e32 v0, v57, v0
	v_add_f32_e32 v0, v56, v0
	v_and_b32_e32 v56, 64, v52
	v_xor_b32_e32 v53, 16, v52
	v_add_u32_e32 v56, 64, v56
	v_cmp_lt_i32_e32 vcc, v53, v56
	s_and_b64 s[30:31], s[24:25], exec
	v_readlane_b32 s68, v252, 3
	v_cndmask_b32_e32 v53, v52, v53, vcc
	v_lshlrev_b32_e32 v53, 2, v53
	ds_bpermute_b32 v53, v53, v0
	v_readlane_b32 s30, v254, 63
	v_readlane_b32 s76, v252, 11
	v_readlane_b32 s77, v252, 12
	v_readlane_b32 s78, v252, 13
	s_waitcnt lgkmcnt(0)
	v_add_f32_e32 v0, v0, v53
	v_xor_b32_e32 v53, 32, v52
	v_cmp_lt_i32_e32 vcc, v53, v56
	v_readlane_b32 s79, v252, 14
	v_readlane_b32 s31, v255, 0
	v_cndmask_b32_e32 v52, v52, v53, vcc
	v_lshlrev_b32_e32 v52, 2, v52
	ds_bpermute_b32 v52, v52, v0
	s_cselect_b32 s21, s77, s79
	s_cselect_b32 s40, s76, s78
	s_lshl_b64 s[30:31], s[30:31], 2
	s_add_u32 s30, s40, s30
	s_waitcnt lgkmcnt(0)
	v_add_f32_e32 v0, v0, v52
	v_fmamk_f32 v0, v0, 0x3c800000, v249
	v_cmp_gt_f32_e32 vcc, s34, v0
	v_mul_f32_e32 v52, 0x4b800000, v0
	s_addc_u32 s31, s21, s31
	v_cndmask_b32_e32 v0, v0, v52, vcc
	v_rsq_f32_e32 v0, v0
	v_readlane_b32 s21, v255, 11
	v_lshlrev_b64 v[50:51], 11, v[50:51]
	v_mov_b32_e32 v64, v74
	v_mul_f32_e32 v52, 0x45800000, v0
	v_cndmask_b32_e32 v56, v0, v52, vcc
	v_mov_b32_e32 v0, s21
	v_mov_b32_e32 v52, s48
	v_readlane_b32 s21, v255, 10
	v_cndmask_b32_e64 v53, v0, v52, s[0:1]
	v_mov_b32_e32 v52, s47
	v_mov_b32_e32 v0, s21
	v_cndmask_b32_e64 v52, v0, v52, s[0:1]
	v_lshlrev_b32_e32 v0, 2, v72
	v_lshl_add_u64 v[60:61], v[52:53], 0, v[50:51]
	global_load_dwordx4 v[50:53], v0, s[30:31]
	global_load_dwordx4 v[112:115], v0, s[30:31] offset:64
	global_load_dwordx4 v[116:119], v0, s[30:31] offset:128
	global_load_dwordx4 v[120:123], v0, s[30:31] offset:192
	v_pk_mul_f32 v[58:59], v[46:47], v[56:57] op_sel_hi:[1,0]
	v_mov_b32_e32 v65, v1
	s_andn2_b64 vcc, exec, s[22:23]
	v_lshl_add_u64 v[60:61], v[64:65], 2, v[60:61]
	v_readlane_b32 s69, v252, 4
	v_readlane_b32 s70, v252, 5
	v_readlane_b32 s71, v252, 6
	v_readlane_b32 s72, v252, 7
	v_readlane_b32 s73, v252, 8
	v_readlane_b32 s74, v252, 9
	v_readlane_b32 s75, v252, 10
	v_readlane_b32 s80, v252, 15
	v_readlane_b32 s81, v252, 16
	v_readlane_b32 s82, v252, 17
	v_readlane_b32 s83, v252, 18
	s_waitcnt vmcnt(3)
	v_pk_mul_f32 v[50:51], v[50:51], v[58:59]
	v_pk_mul_f32 v[58:59], v[48:49], v[56:57] op_sel_hi:[1,0]
	v_cndmask_b32_e64 v57, 0, 1, s[22:23]
	v_pk_mul_f32 v[52:53], v[52:53], v[58:59]
	v_cvt_pk_bf16_f32 v62, v50, v51
	v_cvt_pk_bf16_f32 v63, v52, v53
	v_lshl_add_u64 v[58:59], v[64:65], 1, v[54:55]
	v_cmp_ne_u32_e64 s[0:1], 1, v57
	global_store_dwordx2 v[58:59], v[62:63], off
	s_cbranch_vccnz .LBB0_111
	v_add_co_u32_e32 v62, vcc, 0xffffe000, v60
	s_nop 1
	v_addc_co_u32_e32 v63, vcc, -1, v61, vcc
	global_store_dwordx4 v[62:63], v[50:53], off offset:-2560
.LBB0_111:
	v_lshl_add_u64 v[64:65], s[30:31], 0, v[0:1]
	v_mov_b32_e32 v62, v56
	v_mov_b32_e32 v63, v56
	v_mov_b32_e32 v57, v56
	v_pk_mul_f32 v[66:67], v[42:43], v[62:63]
	s_and_b64 vcc, exec, s[0:1]
	s_waitcnt vmcnt(3)
	v_mov_b32_e32 v50, v112
	v_mov_b32_e32 v51, v113
	v_mov_b32_e32 v52, v114
	v_mov_b32_e32 v53, v115
	v_pk_mul_f32 v[50:51], v[66:67], v[50:51]
	v_pk_mul_f32 v[66:67], v[44:45], v[56:57]
	s_nop 0
	v_pk_mul_f32 v[52:53], v[66:67], v[52:53]
	v_cvt_pk_bf16_f32 v66, v50, v51
	v_cvt_pk_bf16_f32 v67, v52, v53
	global_store_dwordx2 v[58:59], v[66:67], off offset:32
	s_cbranch_vccnz .LBB0_113
	v_add_co_u32_e32 v66, vcc, 0xffffe000, v60
	s_nop 1
	v_addc_co_u32_e32 v67, vcc, -1, v61, vcc
	global_store_dwordx4 v[66:67], v[50:53], off offset:-2496
.LBB0_113:
	v_pk_mul_f32 v[66:67], v[38:39], v[62:63]
	s_and_b64 vcc, exec, s[0:1]
	s_waitcnt vmcnt(3)
	v_mov_b32_e32 v50, v116
	v_mov_b32_e32 v51, v117
	v_mov_b32_e32 v52, v118
	v_mov_b32_e32 v53, v119
	v_pk_mul_f32 v[50:51], v[66:67], v[50:51]
	v_pk_mul_f32 v[66:67], v[40:41], v[56:57]
	s_nop 0
	v_pk_mul_f32 v[52:53], v[66:67], v[52:53]
	v_cvt_pk_bf16_f32 v66, v50, v51
	v_cvt_pk_bf16_f32 v67, v52, v53
	global_store_dwordx2 v[58:59], v[66:67], off offset:64
	s_cbranch_vccnz .LBB0_115
	v_add_co_u32_e32 v66, vcc, 0xffffe000, v60
	s_nop 1
	v_addc_co_u32_e32 v67, vcc, -1, v61, vcc
	global_store_dwordx4 v[66:67], v[50:53], off offset:-2432
.LBB0_115:
	v_pk_mul_f32 v[62:63], v[34:35], v[62:63]
	v_pk_mul_f32 v[56:57], v[36:37], v[56:57]
	s_and_b64 vcc, exec, s[0:1]
	s_waitcnt vmcnt(3)
	v_mov_b32_e32 v50, v120
	v_mov_b32_e32 v51, v121
	v_mov_b32_e32 v52, v122
	v_mov_b32_e32 v53, v123
	v_pk_mul_f32 v[50:51], v[62:63], v[50:51]
	v_pk_mul_f32 v[52:53], v[56:57], v[52:53]
	v_cvt_pk_bf16_f32 v56, v50, v51
	v_cvt_pk_bf16_f32 v57, v52, v53
	global_store_dwordx2 v[58:59], v[56:57], off offset:96
	s_cbranch_vccnz .LBB0_117
	v_add_co_u32_e32 v56, vcc, 0xffffe000, v60
	s_nop 1
	v_addc_co_u32_e32 v57, vcc, -1, v61, vcc
	global_store_dwordx4 v[56:57], v[50:53], off offset:-2368

; DI unsigned pk2(float a, float b) { f32x2 v = {a, b}; bfv2 r = __builtin_convertvector(v, bfv2); return __builtin_bit_cast(unsigned, r); }
; DI void phase_gemm_in(const Params& p, int l, char* lds) {
;     ...
;       } else if (kind == 2 || kind == 3) {
;         float ss = 0.f;
; #pragma unroll
;         for (int ni = 0; ni < 4; ++ni) { const f32x4 v = acc[mi][ni]; ss += v[0] * v[0] + v[1] * v[1] + v[2] * v[2] + v[3] * v[3]; }
;         ss += __shfl_xor(ss, 16); ss += __shfl_xor(ss, 32);
;         const float rstd = rsqrtf(ss * (1.0f / 64.0f) + 1e-6f);
;         const float* g = (kind == 2 ? p.qng : p.kng) + l * 64;
;         float* ko = isp ? p.out + O_KP + ((size_t)l * MP + R) * 512 : p.out + O_KS + ((size_t)l * MS + rs) * 512;
; #pragma unroll
;         for (int ni = 0; ni < 4; ++ni) {
;           const int c = colb + ni * 16; const int d = ni * 16 + quad * 4;
;           const f32x4 gv = *(const f32x4*)(g + d); f32x4 v = acc[mi][ni];
; #pragma unroll
;           for (int e = 0; e < 4; ++e) v[e] = v[e] * rstd * gv[e];
;           u32x2 o; o[0] = pk2(v[0], v[1]); o[1] = pk2(v[2], v[3]); *(u32x2*)(zrow + c) = o;
;           if (kind == 3) *(f32x4*)(ko + (c - C_K)) = v;
;         }
.LBB0_131:
	s_and_b64 vcc, exec, s[30:31]
	s_cbranch_vccz .LBB0_140
	v_mov_b32_e32 v40, v31
	v_mov_b32_e32 v41, v23
	v_mov_b32_e32 v36, v30
	v_mov_b32_e32 v37, v22
	v_pk_mul_f32 v[40:41], v[40:41], v[40:41]
	v_mov_b32_e32 v42, v19
	v_pk_fma_f32 v[36:37], v[36:37], v[36:37], v[40:41]
	v_mov_b32_e32 v40, v32
	v_mov_b32_e32 v41, v24
	v_pk_fma_f32 v[36:37], v[40:41], v[40:41], v[36:37]
	v_mov_b32_e32 v40, v33
	v_mov_b32_e32 v41, v25
	v_mov_b32_e32 v43, v27
	v_pk_fma_f32 v[36:37], v[40:41], v[40:41], v[36:37]
	v_mov_b32_e32 v40, v18
	v_mov_b32_e32 v41, v26
	v_pk_mul_f32 v[42:43], v[42:43], v[42:43]
	v_add_f32_e32 v0, v36, v37
	v_pk_fma_f32 v[40:41], v[40:41], v[40:41], v[42:43]
	v_mov_b32_e32 v42, v20
	v_mov_b32_e32 v43, v28
	v_pk_fma_f32 v[40:41], v[42:43], v[42:43], v[40:41]
	v_mov_b32_e32 v42, v21
	v_mov_b32_e32 v43, v29
	v_pk_fma_f32 v[40:41], v[42:43], v[42:43], v[40:41]
	v_mbcnt_hi_u32_b32 v36, -1, v213
	v_add_f32_e32 v0, v41, v0
	v_add_f32_e32 v0, v40, v0
	v_and_b32_e32 v40, 64, v36
	v_xor_b32_e32 v37, 16, v36
	v_add_u32_e32 v40, 64, v40
	v_cmp_lt_i32_e32 vcc, v37, v40
	s_and_b64 s[30:31], s[24:25], exec
	v_readlane_b32 s68, v252, 3
	v_cndmask_b32_e32 v37, v36, v37, vcc
	v_lshlrev_b32_e32 v37, 2, v37
	ds_bpermute_b32 v37, v37, v0
	v_readlane_b32 s30, v254, 63
	v_readlane_b32 s76, v252, 11
	v_readlane_b32 s77, v252, 12
	v_readlane_b32 s78, v252, 13
	s_waitcnt lgkmcnt(0)
	v_add_f32_e32 v0, v0, v37
	v_xor_b32_e32 v37, 32, v36
	v_cmp_lt_i32_e32 vcc, v37, v40
	v_readlane_b32 s79, v252, 14
	v_readlane_b32 s31, v255, 0
	v_cndmask_b32_e32 v36, v36, v37, vcc
	v_lshlrev_b32_e32 v36, 2, v36
	ds_bpermute_b32 v36, v36, v0
	s_cselect_b32 s21, s77, s79
	s_cselect_b32 s40, s76, s78
	s_lshl_b64 s[30:31], s[30:31], 2
	s_add_u32 s30, s40, s30
	s_waitcnt lgkmcnt(0)
	v_add_f32_e32 v0, v0, v36
	v_fmamk_f32 v0, v0, 0x3c800000, v249
	v_cmp_gt_f32_e32 vcc, s34, v0
	v_mul_f32_e32 v36, 0x4b800000, v0
	s_addc_u32 s31, s21, s31
	v_cndmask_b32_e32 v0, v0, v36, vcc
	v_rsq_f32_e32 v0, v0
	v_readlane_b32 s21, v255, 11
	v_lshlrev_b64 v[34:35], 11, v[34:35]
	v_mov_b32_e32 v48, v74
	v_mul_f32_e32 v36, 0x45800000, v0
	v_cndmask_b32_e32 v40, v0, v36, vcc
	v_mov_b32_e32 v0, s21
	v_mov_b32_e32 v36, s48
	v_readlane_b32 s21, v255, 10
	v_cndmask_b32_e64 v37, v0, v36, s[0:1]
	v_mov_b32_e32 v36, s47
	v_mov_b32_e32 v0, s21
	v_cndmask_b32_e64 v36, v0, v36, s[0:1]
	v_lshlrev_b32_e32 v0, 2, v72
	v_lshl_add_u64 v[44:45], v[36:37], 0, v[34:35]
	global_load_dwordx4 v[34:37], v0, s[30:31]
	global_load_dwordx4 v[112:115], v0, s[30:31] offset:64
	global_load_dwordx4 v[116:119], v0, s[30:31] offset:128
	global_load_dwordx4 v[120:123], v0, s[30:31] offset:192
	v_pk_mul_f32 v[42:43], v[30:31], v[40:41] op_sel_hi:[1,0]
	v_mov_b32_e32 v49, v1
	s_andn2_b64 vcc, exec, s[22:23]
	v_lshl_add_u64 v[44:45], v[48:49], 2, v[44:45]
	v_readlane_b32 s69, v252, 4
	v_readlane_b32 s70, v252, 5
	v_readlane_b32 s71, v252, 6
	v_readlane_b32 s72, v252, 7
	v_readlane_b32 s73, v252, 8
	v_readlane_b32 s74, v252, 9
	v_readlane_b32 s75, v252, 10
	v_readlane_b32 s80, v252, 15
	v_readlane_b32 s81, v252, 16
	v_readlane_b32 s82, v252, 17
	v_readlane_b32 s83, v252, 18
	s_waitcnt vmcnt(3)
	v_pk_mul_f32 v[34:35], v[34:35], v[42:43]
	v_pk_mul_f32 v[42:43], v[32:33], v[40:41] op_sel_hi:[1,0]
	v_cndmask_b32_e64 v41, 0, 1, s[22:23]
	v_pk_mul_f32 v[36:37], v[36:37], v[42:43]
	v_cvt_pk_bf16_f32 v46, v34, v35
	v_cvt_pk_bf16_f32 v47, v36, v37
	v_lshl_add_u64 v[42:43], v[48:49], 1, v[38:39]
	v_cmp_ne_u32_e64 s[0:1], 1, v41
	global_store_dwordx2 v[42:43], v[46:47], off
	s_cbranch_vccnz .LBB0_134
	v_add_co_u32_e32 v46, vcc, 0xffffe000, v44
	s_nop 1
	v_addc_co_u32_e32 v47, vcc, -1, v45, vcc
	global_store_dwordx4 v[46:47], v[34:37], off offset:-2560
.LBB0_134:
	v_lshl_add_u64 v[48:49], s[30:31], 0, v[0:1]
	v_mov_b32_e32 v46, v40
	v_mov_b32_e32 v47, v40
	v_mov_b32_e32 v41, v40
	v_pk_mul_f32 v[50:51], v[22:23], v[46:47]
	s_and_b64 vcc, exec, s[0:1]
	s_waitcnt vmcnt(3)
	v_mov_b32_e32 v34, v112
	v_mov_b32_e32 v35, v113
	v_mov_b32_e32 v36, v114
	v_mov_b32_e32 v37, v115
	v_pk_mul_f32 v[34:35], v[50:51], v[34:35]
	v_pk_mul_f32 v[50:51], v[24:25], v[40:41]
	s_nop 0
	v_pk_mul_f32 v[36:37], v[50:51], v[36:37]
	v_cvt_pk_bf16_f32 v50, v34, v35
	v_cvt_pk_bf16_f32 v51, v36, v37
	global_store_dwordx2 v[42:43], v[50:51], off offset:32
	s_cbranch_vccnz .LBB0_136
	v_add_co_u32_e32 v50, vcc, 0xffffe000, v44
	s_nop 1
	v_addc_co_u32_e32 v51, vcc, -1, v45, vcc
	global_store_dwordx4 v[50:51], v[34:37], off offset:-2496
.LBB0_136:
	v_pk_mul_f32 v[50:51], v[26:27], v[46:47]
	s_and_b64 vcc, exec, s[0:1]
	s_waitcnt vmcnt(3)
	v_mov_b32_e32 v34, v116
	v_mov_b32_e32 v35, v117
	v_mov_b32_e32 v36, v118
	v_mov_b32_e32 v37, v119
	v_pk_mul_f32 v[34:35], v[50:51], v[34:35]
	v_pk_mul_f32 v[50:51], v[28:29], v[40:41]
	s_nop 0
	v_pk_mul_f32 v[36:37], v[50:51], v[36:37]
	v_cvt_pk_bf16_f32 v50, v34, v35
	v_cvt_pk_bf16_f32 v51, v36, v37
	global_store_dwordx2 v[42:43], v[50:51], off offset:64
	s_cbranch_vccnz .LBB0_138
	v_add_co_u32_e32 v50, vcc, 0xffffe000, v44
	s_nop 1
	v_addc_co_u32_e32 v51, vcc, -1, v45, vcc
	global_store_dwordx4 v[50:51], v[34:37], off offset:-2432
.LBB0_138:
	v_pk_mul_f32 v[46:47], v[18:19], v[46:47]
	v_pk_mul_f32 v[40:41], v[20:21], v[40:41]
	s_and_b64 vcc, exec, s[0:1]
	s_waitcnt vmcnt(3)
	v_mov_b32_e32 v34, v120
	v_mov_b32_e32 v35, v121
	v_mov_b32_e32 v36, v122
	v_mov_b32_e32 v37, v123
	v_pk_mul_f32 v[34:35], v[46:47], v[34:35]
	v_pk_mul_f32 v[36:37], v[40:41], v[36:37]
	v_cvt_pk_bf16_f32 v40, v34, v35
	v_cvt_pk_bf16_f32 v41, v36, v37
	global_store_dwordx2 v[42:43], v[40:41], off offset:96
	s_cbranch_vccnz .LBB0_140
	v_add_co_u32_e32 v40, vcc, 0xffffe000, v44
	s_nop 1
	v_addc_co_u32_e32 v41, vcc, -1, v45, vcc
	global_store_dwordx4 v[40:41], v[34:37], off offset:-2368

; DI unsigned pk2(float a, float b) { f32x2 v = {a, b}; bfv2 r = __builtin_convertvector(v, bfv2); return __builtin_bit_cast(unsigned, r); }
; DI void phase_gemm_in(const Params& p, int l, char* lds) {
;     ...
;       } else if (kind == 2 || kind == 3) {
;         float ss = 0.f;
; #pragma unroll
;         for (int ni = 0; ni < 4; ++ni) { const f32x4 v = acc[mi][ni]; ss += v[0] * v[0] + v[1] * v[1] + v[2] * v[2] + v[3] * v[3]; }
;         ss += __shfl_xor(ss, 16); ss += __shfl_xor(ss, 32);
;         const float rstd = rsqrtf(ss * (1.0f / 64.0f) + 1e-6f);
;         const float* g = (kind == 2 ? p.qng : p.kng) + l * 64;
;         float* ko = isp ? p.out + O_KP + ((size_t)l * MP + R) * 512 : p.out + O_KS + ((size_t)l * MS + rs) * 512;
; #pragma unroll
;         for (int ni = 0; ni < 4; ++ni) {
;           const int c = colb + ni * 16; const int d = ni * 16 + quad * 4;
;           const f32x4 gv = *(const f32x4*)(g + d); f32x4 v = acc[mi][ni];
; #pragma unroll
;           for (int e = 0; e < 4; ++e) v[e] = v[e] * rstd * gv[e];
;           u32x2 o; o[0] = pk2(v[0], v[1]); o[1] = pk2(v[2], v[3]); *(u32x2*)(zrow + c) = o;
;           if (kind == 3) *(f32x4*)(ko + (c - C_K)) = v;
;         }
.LBB0_154:
	s_and_b64 vcc, exec, s[30:31]
	s_cbranch_vccz .LBB0_163
	v_mov_b32_e32 v24, v15
	v_mov_b32_e32 v25, v11
	v_mov_b32_e32 v20, v14
	v_mov_b32_e32 v21, v10
	v_pk_mul_f32 v[24:25], v[24:25], v[24:25]
	v_mov_b32_e32 v26, v3
	v_pk_fma_f32 v[20:21], v[20:21], v[20:21], v[24:25]
	v_mov_b32_e32 v24, v16
	v_mov_b32_e32 v25, v12
	v_pk_fma_f32 v[20:21], v[24:25], v[24:25], v[20:21]
	v_mov_b32_e32 v24, v17
	v_mov_b32_e32 v25, v13
	v_mov_b32_e32 v27, v7
	v_pk_fma_f32 v[20:21], v[24:25], v[24:25], v[20:21]
	v_mov_b32_e32 v24, v2
	v_mov_b32_e32 v25, v6
	v_pk_mul_f32 v[26:27], v[26:27], v[26:27]
	v_add_f32_e32 v0, v20, v21
	v_pk_fma_f32 v[24:25], v[24:25], v[24:25], v[26:27]
	v_mov_b32_e32 v26, v4
	v_mov_b32_e32 v27, v8
	v_pk_fma_f32 v[24:25], v[26:27], v[26:27], v[24:25]
	v_mov_b32_e32 v26, v5
	v_mov_b32_e32 v27, v9
	v_pk_fma_f32 v[24:25], v[26:27], v[26:27], v[24:25]
	v_mbcnt_hi_u32_b32 v20, -1, v213
	v_add_f32_e32 v0, v25, v0
	v_add_f32_e32 v0, v24, v0
	v_and_b32_e32 v24, 64, v20
	v_xor_b32_e32 v21, 16, v20
	v_add_u32_e32 v24, 64, v24
	v_cmp_lt_i32_e32 vcc, v21, v24
	s_and_b64 s[20:21], s[24:25], exec
	v_readlane_b32 s68, v252, 3
	v_cndmask_b32_e32 v21, v20, v21, vcc
	v_lshlrev_b32_e32 v21, 2, v21
	ds_bpermute_b32 v21, v21, v0
	v_readlane_b32 s20, v254, 63
	v_readlane_b32 s76, v252, 11
	v_readlane_b32 s77, v252, 12
	v_readlane_b32 s78, v252, 13
	s_waitcnt lgkmcnt(0)
	v_add_f32_e32 v0, v0, v21
	v_xor_b32_e32 v21, 32, v20
	v_cmp_lt_i32_e32 vcc, v21, v24
	v_readlane_b32 s79, v252, 14
	v_readlane_b32 s21, v255, 0
	v_cndmask_b32_e32 v20, v20, v21, vcc
	v_lshlrev_b32_e32 v20, 2, v20
	ds_bpermute_b32 v20, v20, v0
	s_cselect_b32 s25, s77, s79
	s_cselect_b32 s24, s76, s78
	s_lshl_b64 s[20:21], s[20:21], 2
	s_add_u32 s24, s24, s20
	s_waitcnt lgkmcnt(0)
	v_add_f32_e32 v0, v0, v20
	v_fmamk_f32 v0, v0, 0x3c800000, v249
	v_cmp_gt_f32_e32 vcc, s34, v0
	v_mul_f32_e32 v20, 0x4b800000, v0
	v_readlane_b32 s20, v255, 11
	v_cndmask_b32_e32 v0, v0, v20, vcc
	v_rsq_f32_e32 v0, v0
	s_addc_u32 s25, s25, s21
	v_lshlrev_b64 v[18:19], 11, v[18:19]
	v_mov_b32_e32 v32, v74
	v_mul_f32_e32 v20, 0x45800000, v0
	v_cndmask_b32_e32 v24, v0, v20, vcc
	v_mov_b32_e32 v0, s20
	v_mov_b32_e32 v20, s48
	v_readlane_b32 s20, v255, 10
	v_cndmask_b32_e64 v21, v0, v20, s[0:1]
	v_mov_b32_e32 v20, s47
	v_mov_b32_e32 v0, s20
	v_cndmask_b32_e64 v20, v0, v20, s[0:1]
	v_lshlrev_b32_e32 v0, 2, v72
	v_lshl_add_u64 v[28:29], v[20:21], 0, v[18:19]
	global_load_dwordx4 v[18:21], v0, s[24:25]
	global_load_dwordx4 v[112:115], v0, s[24:25] offset:64
	global_load_dwordx4 v[116:119], v0, s[24:25] offset:128
	global_load_dwordx4 v[120:123], v0, s[24:25] offset:192
	v_pk_mul_f32 v[26:27], v[14:15], v[24:25] op_sel_hi:[1,0]
	v_mov_b32_e32 v33, v1
	s_andn2_b64 vcc, exec, s[22:23]
	v_lshl_add_u64 v[28:29], v[32:33], 2, v[28:29]
	v_readlane_b32 s69, v252, 4
	v_readlane_b32 s70, v252, 5
	v_readlane_b32 s71, v252, 6
	v_readlane_b32 s72, v252, 7
	v_readlane_b32 s73, v252, 8
	v_readlane_b32 s74, v252, 9
	v_readlane_b32 s75, v252, 10
	v_readlane_b32 s80, v252, 15
	v_readlane_b32 s81, v252, 16
	v_readlane_b32 s82, v252, 17
	v_readlane_b32 s83, v252, 18
	s_waitcnt vmcnt(3)
	v_pk_mul_f32 v[18:19], v[18:19], v[26:27]
	v_pk_mul_f32 v[26:27], v[16:17], v[24:25] op_sel_hi:[1,0]
	v_cndmask_b32_e64 v25, 0, 1, s[22:23]
	v_pk_mul_f32 v[20:21], v[20:21], v[26:27]
	v_cvt_pk_bf16_f32 v30, v18, v19
	v_cvt_pk_bf16_f32 v31, v20, v21
	v_lshl_add_u64 v[26:27], v[32:33], 1, v[22:23]
	v_cmp_ne_u32_e64 s[36:37], 1, v25
	global_store_dwordx2 v[26:27], v[30:31], off
	s_cbranch_vccnz .LBB0_157
	v_add_co_u32_e32 v30, vcc, 0xffffe000, v28
	s_nop 1
	v_addc_co_u32_e32 v31, vcc, -1, v29, vcc
	global_store_dwordx4 v[30:31], v[18:21], off offset:-2560
.LBB0_157:
	v_lshl_add_u64 v[32:33], s[24:25], 0, v[0:1]
	v_mov_b32_e32 v30, v24
	v_mov_b32_e32 v31, v24
	v_mov_b32_e32 v25, v24
	v_pk_mul_f32 v[34:35], v[10:11], v[30:31]
	s_and_b64 vcc, exec, s[36:37]
	s_waitcnt vmcnt(3)
	v_mov_b32_e32 v18, v112
	v_mov_b32_e32 v19, v113
	v_mov_b32_e32 v20, v114
	v_mov_b32_e32 v21, v115
	v_pk_mul_f32 v[18:19], v[34:35], v[18:19]
	v_pk_mul_f32 v[34:35], v[12:13], v[24:25]
	s_nop 0
	v_pk_mul_f32 v[20:21], v[34:35], v[20:21]
	v_cvt_pk_bf16_f32 v34, v18, v19
	v_cvt_pk_bf16_f32 v35, v20, v21
	global_store_dwordx2 v[26:27], v[34:35], off offset:32
	s_cbranch_vccnz .LBB0_159
	v_add_co_u32_e32 v34, vcc, 0xffffe000, v28
	s_nop 1
	v_addc_co_u32_e32 v35, vcc, -1, v29, vcc
	global_store_dwordx4 v[34:35], v[18:21], off offset:-2496
.LBB0_159:
	v_pk_mul_f32 v[34:35], v[6:7], v[30:31]
	s_and_b64 vcc, exec, s[36:37]
	s_waitcnt vmcnt(3)
	v_mov_b32_e32 v18, v116
	v_mov_b32_e32 v19, v117
	v_mov_b32_e32 v20, v118
	v_mov_b32_e32 v21, v119
	v_pk_mul_f32 v[18:19], v[34:35], v[18:19]
	v_pk_mul_f32 v[34:35], v[8:9], v[24:25]
	s_nop 0
	v_pk_mul_f32 v[20:21], v[34:35], v[20:21]
	v_cvt_pk_bf16_f32 v34, v18, v19
	v_cvt_pk_bf16_f32 v35, v20, v21
	global_store_dwordx2 v[26:27], v[34:35], off offset:64
	s_cbranch_vccnz .LBB0_161
	v_add_co_u32_e32 v34, vcc, 0xffffe000, v28
	s_nop 1
	v_addc_co_u32_e32 v35, vcc, -1, v29, vcc
	global_store_dwordx4 v[34:35], v[18:21], off offset:-2432
.LBB0_161:
	v_pk_mul_f32 v[30:31], v[2:3], v[30:31]
	v_pk_mul_f32 v[24:25], v[4:5], v[24:25]
	s_and_b64 vcc, exec, s[36:37]
	s_waitcnt vmcnt(3)
	v_mov_b32_e32 v18, v120
	v_mov_b32_e32 v19, v121
	v_mov_b32_e32 v20, v122
	v_mov_b32_e32 v21, v123
	v_pk_mul_f32 v[18:19], v[30:31], v[18:19]
	v_pk_mul_f32 v[20:21], v[24:25], v[20:21]
	v_cvt_pk_bf16_f32 v24, v18, v19
	v_cvt_pk_bf16_f32 v25, v20, v21
	global_store_dwordx2 v[26:27], v[24:25], off offset:96
	s_cbranch_vccnz .LBB0_163
	v_add_co_u32_e32 v24, vcc, 0xffffe000, v28
	s_nop 1
	v_addc_co_u32_e32 v25, vcc, -1, v29, vcc
	global_store_dwordx4 v[24:25], v[18:21], off offset:-2368

; #define LASP __attribute__((address_space(3)))
; DI void gemm_dma(f32x4 (&acc)[4][4], const bf16_t* Ap, int lda, const bf16_t* Bp, int ldb, int K, char* lds) {
;     ...
;   const int lrow = lane >> 3, lpc = lane & 7;
;   const bf16_t* ga[4]; const bf16_t* gb[4];
; #pragma unroll
;   for (int i = 0; i < 4; ++i) {
;     const int row = (wave * 4 + i) * 8 + lrow; const int q = lpc ^ (row & 7);
;     ga[i] = Ap + (size_t)row * lda + q * 8; gb[i] = Bp + (size_t)row * ldb + q * 8;
;   }
;   auto issue = [&](int kt) {
;     char* sb = lds + (kt & 1) * 32768 + wave * 4096;
; #pragma unroll
;     for (int i = 0; i < 4; ++i) {
;       __builtin_amdgcn_global_load_lds((const unsigned*)(ga[i] + kt * 64), (LASP unsigned*)(sb + i * 1024), 16, 0, 0);
;       __builtin_amdgcn_global_load_lds((const unsigned*)(gb[i] + kt * 64), (LASP unsigned*)(sb + 16384 + i * 1024), 16, 0, 0);
;     }
;   };
;   const int sw = l15 & 7;
;   const unsigned lbase = (unsigned)(size_t)(LASP char*)lds;
;   const unsigned a0 = (unsigned)((wm * 64 + l15) * 128 + ((quad ^ sw) * 16)), a1 = (unsigned)((wm * 64 + l15) * 128 + (((4 + quad) ^ sw) * 16));
;   const unsigned b0 = 16384u + (unsigned)((wn * 64 + l15) * 128 + ((quad ^ sw) * 16)), b1 = 16384u + (unsigned)((wn * 64 + l15) * 128 + (((4 + quad) ^ sw) * 16));
;   asm volatile("s_waitcnt vmcnt(0)" ::: "memory");
;   __builtin_amdgcn_s_barrier();
;   asm volatile("" ::: "memory");
;   issue(0);
;   for (int kt = 0; kt < nk; ++kt) {
;     asm volatile("s_waitcnt vmcnt(0)" ::: "memory");
;     __builtin_amdgcn_s_barrier();
;     asm volatile("" ::: "memory");
;     if (kt + 1 < nk) issue(kt + 1);
;     const unsigned sa = lbase + (unsigned)((kt & 1) * 32768);
;     bf16x8 af[4], bfr[4], ag[4], bg[4];
;     asm volatile("ds_read_b128 %0, %8\n\tds_read_b128 %1, %8 offset:2048\n\tds_read_b128 %2, %8 offset:4096\n\tds_read_b128 %3, %8 offset:6144\n\t"
;                  "ds_read_b128 %4, %9\n\tds_read_b128 %5, %9 offset:2048\n\tds_read_b128 %6, %9 offset:4096\n\tds_read_b128 %7, %9 offset:6144"
;                  : "=&v"(af[0]), "=&v"(af[1]), "=&v"(af[2]), "=&v"(af[3]), "=&v"(bfr[0]), "=&v"(bfr[1]), "=&v"(bfr[2]), "=&v"(bfr[3])
;                  : "v"(sa + a0), "v"(sa + b0) : "memory");
.LBB0_722:
	s_and_b32 s1, s0, 63
	s_lshr_b32 s0, s0, 3
	s_and_b32 s0, s0, 0xffffff8
	s_sub_i32 s2, 0x80, s0
	s_min_i32 s2, s2, 8
	s_abs_i32 s20, s2
	v_cvt_f32_u32_e32 v0, s20
	s_sub_i32 s21, 0, s20
	s_ashr_i32 s3, s2, 31
	v_mov_b32_e32 v10, v212
	v_rcp_iflag_f32_e32 v0, v0
	s_waitcnt vmcnt(0)
	s_barrier
	v_mul_f32_e32 v0, 0x4f7ffffe, v0
	v_cvt_u32_f32_e32 v0, v0
	v_bfe_u32 v11, v10, 4, 2
	v_and_b32_e32 v12, 7, v10
	v_readfirstlane_b32 s22, v0
	s_mul_i32 s21, s21, s22
	s_mul_hi_u32 s21, s22, s21
	s_add_i32 s22, s22, s21
	s_mul_hi_u32 s21, s1, s22
	s_mul_i32 s22, s21, s20
	s_sub_i32 s22, s1, s22
	s_add_i32 s23, s21, 1
	s_sub_i32 s24, s22, s20
	s_cmp_ge_u32 s22, s20
	s_cselect_b32 s21, s23, s21
	s_cselect_b32 s22, s24, s22
	s_add_i32 s23, s21, 1
	s_cmp_ge_u32 s22, s20
	s_cselect_b32 s20, s23, s21
	s_xor_b32 s20, s20, s3
	s_sub_i32 s22, s20, s3
	s_mul_i32 s2, s22, s2
	s_add_i32 s0, s0, s1
	s_sub_i32 s24, s0, s2
	s_ashr_i32 s25, s24, 31
	s_lshl_b64 s[0:1], s[24:25], 17
	s_add_u32 s26, s52, s0
	s_addc_u32 s27, s53, s1
	s_ashr_i32 s23, s22, 31
	s_lshl_b64 s[2:3], s[22:23], 17
	s_add_u32 s30, s74, s2
	v_readfirstlane_b32 s21, v10
	s_addc_u32 s31, s75, s3
	s_ashr_i32 s20, s21, 6
	v_bfe_u32 v0, v10, 3, 3
	v_lshl_or_b32 v2, s20, 5, v0
	v_bitop3_b32 v0, v0, v10, 7 bitop3:0x78
	v_lshlrev_b32_e32 v0, 4, v0
	v_ashrrev_i32_e32 v3, 31, v2
	v_lshl_add_u64 v[4:5], s[26:27], 0, v[0:1]
	v_lshl_add_u64 v[6:7], s[30:31], 0, v[0:1]
	v_lshlrev_b64 v[8:9], 10, v[2:3]
	v_lshl_add_u64 v[80:81], v[4:5], 0, v[8:9]
	v_lshl_add_u64 v[78:79], v[6:7], 0, v[8:9]
	v_or_b32_e32 v8, 8, v2
	v_ashrrev_i32_e32 v9, 31, v8
	s_lshl_b32 s40, s20, 12
	v_lshlrev_b64 v[8:9], 10, v[8:9]
	s_add_i32 s41, s40, 0x4000
	s_mov_b32 m0, s40
	v_lshl_add_u64 v[76:77], v[4:5], 0, v[8:9]
	v_lshl_add_u64 v[74:75], v[6:7], 0, v[8:9]
	v_or_b32_e32 v8, 16, v2
	global_load_lds_dwordx4 v[80:81], off
	s_mov_b32 m0, s41
	s_or_b32 s44, s40, 0x400
	v_ashrrev_i32_e32 v9, 31, v8
	global_load_lds_dwordx4 v[78:79], off
	s_mov_b32 m0, s44
	s_add_i32 s45, s40, 0x4400
	v_lshlrev_b64 v[8:9], 10, v[8:9]
	v_or_b32_e32 v2, 24, v2
	global_load_lds_dwordx4 v[76:77], off
	s_mov_b32 m0, s45
	s_or_b32 s46, s40, 0x800
	v_lshl_add_u64 v[72:73], v[4:5], 0, v[8:9]
	v_ashrrev_i32_e32 v3, 31, v2
	global_load_lds_dwordx4 v[74:75], off
	s_mov_b32 m0, s46
	s_add_i32 s42, s40, 0x4800
	v_lshl_add_u64 v[70:71], v[6:7], 0, v[8:9]
	v_lshlrev_b64 v[2:3], 10, v[2:3]
	s_lshr_b32 s23, s21, 1
	global_load_lds_dwordx4 v[72:73], off
	s_mov_b32 m0, s42
	s_or_b32 s43, s40, 0xc00
	v_lshl_add_u64 v[68:69], v[4:5], 0, v[2:3]
	v_lshl_add_u64 v[66:67], v[6:7], 0, v[2:3]
	v_and_b32_e32 v2, 15, v10
	s_and_b32 s23, s23, 0x1ffffc0
	global_load_lds_dwordx4 v[70:71], off
	s_mov_b32 m0, s43
	s_add_i32 s31, s40, 0x4c00
	v_or_b32_e32 v0, s23, v2
	v_bitop3_b32 v3, v11, v10, 7 bitop3:0x78
	v_bitop3_b32 v4, v11, v12, 4 bitop3:0x36
	v_and_or_b32 v2, s21, 64, v2
	global_load_lds_dwordx4 v[68:69], off
	s_mov_b32 m0, s31
	v_lshlrev_b32_e32 v0, 7, v0
	v_lshlrev_b32_e32 v3, 4, v3
	v_lshlrev_b32_e32 v4, 4, v4
	v_lshlrev_b32_e32 v2, 7, v2
	global_load_lds_dwordx4 v[66:67], off
	s_add_i32 s21, s40, 0x8000
	v_or_b32_e32 v82, v0, v3
	v_or_b32_e32 v86, v2, v3
	v_or_b32_e32 v87, v2, v4
	s_waitcnt vmcnt(0)
	s_barrier
	s_add_i32 s20, s40, 0xc000
	v_lshl_add_u64 v[2:3], v[80:81], 0, s[28:29]
	s_mov_b32 m0, s21
	s_add_i32 s23, s40, 0x8400
	global_load_lds_dwordx4 v[2:3], off
	v_lshl_add_u64 v[2:3], v[78:79], 0, s[28:29]
	s_mov_b32 m0, s20
	s_add_i32 s25, s40, 0xc400
	global_load_lds_dwordx4 v[2:3], off
	v_lshl_add_u64 v[2:3], v[76:77], 0, s[28:29]
	s_mov_b32 m0, s23
	s_add_i32 s26, s40, 0x8800
	global_load_lds_dwordx4 v[2:3], off
	v_lshl_add_u64 v[2:3], v[74:75], 0, s[28:29]
	s_mov_b32 m0, s25
	s_add_i32 s27, s40, 0xc800
	global_load_lds_dwordx4 v[2:3], off
	v_lshl_add_u64 v[2:3], v[72:73], 0, s[28:29]
	s_mov_b32 m0, s26
	s_add_i32 s30, s40, 0x8c00
	global_load_lds_dwordx4 v[2:3], off
	v_lshl_add_u64 v[2:3], v[70:71], 0, s[28:29]
	s_mov_b32 m0, s27
	s_add_i32 s47, s40, 0xcc00
	global_load_lds_dwordx4 v[2:3], off
	v_lshl_add_u64 v[2:3], v[68:69], 0, s[28:29]
	s_mov_b32 m0, s30
	v_or_b32_e32 v0, v0, v4
	global_load_lds_dwordx4 v[2:3], off
	v_lshl_add_u64 v[2:3], v[66:67], 0, s[28:29]
	s_mov_b32 m0, s47
	v_or_b32_e32 v84, 0x4000, v86
	global_load_lds_dwordx4 v[2:3], off
	ds_read_b128 v[2:5], v82
	ds_read_b128 v[6:9], v82 offset:2048
	ds_read_b128 v[10:13], v82 offset:4096
	ds_read_b128 v[14:17], v82 offset:6144
	ds_read_b128 v[18:21], v84
	ds_read_b128 v[22:25], v84 offset:2048
	ds_read_b128 v[26:29], v84 offset:4096
	ds_read_b128 v[30:33], v84 offset:6144
	v_or_b32_e32 v83, 0x4000, v87
	ds_read_b128 v[34:37], v0
	ds_read_b128 v[38:41], v0 offset:2048
	ds_read_b128 v[46:49], v0 offset:4096
	ds_read_b128 v[62:65], v0 offset:6144
	ds_read_b128 v[50:53], v83
	ds_read_b128 v[54:57], v83 offset:2048
	ds_read_b128 v[58:61], v83 offset:4096
	ds_read_b128 v[88:91], v83 offset:6144
	s_waitcnt lgkmcnt(8)
	s_mov_b32 m0, s40
	v_mfma_f32_16x16x32_bf16 v[42:45], v[18:21], v[2:5], 0
	s_waitcnt lgkmcnt(0)
	s_waitcnt vmcnt(0)
	s_barrier
; DI void gemm_dma(f32x4 (&acc)[4][4], const bf16_t* Ap, int lda, const bf16_t* Bp, int ldb, int K, char* lds) {
;     ...
;   for (int kt = 0; kt < nk; ++kt) {
;     asm volatile("s_waitcnt vmcnt(0)" ::: "memory");
;     __builtin_amdgcn_s_barrier();
;     asm volatile("" ::: "memory");
;     if (kt + 1 < nk) issue(kt + 1);
;     const unsigned sa = lbase + (unsigned)((kt & 1) * 32768);
;     bf16x8 af[4], bfr[4], ag[4], bg[4];
;     asm volatile("ds_read_b128 %0, %8\n\tds_read_b128 %1, %8 offset:2048\n\tds_read_b128 %2, %8 offset:4096\n\tds_read_b128 %3, %8 offset:6144\n\t"
;                  "ds_read_b128 %4, %9\n\tds_read_b128 %5, %9 offset:2048\n\tds_read_b128 %6, %9 offset:4096\n\tds_read_b128 %7, %9 offset:6144"
;                  : "=&v"(af[0]), "=&v"(af[1]), "=&v"(af[2]), "=&v"(af[3]), "=&v"(bfr[0]), "=&v"(bfr[1]), "=&v"(bfr[2]), "=&v"(bfr[3])
;                  : "v"(sa + a0), "v"(sa + b0) : "memory");
;     asm volatile("ds_read_b128 %0, %16\n\tds_read_b128 %1, %16 offset:2048\n\tds_read_b128 %2, %16 offset:4096\n\tds_read_b128 %3, %16 offset:6144\n\t"
;                  "ds_read_b128 %4, %17\n\tds_read_b128 %5, %17 offset:2048\n\tds_read_b128 %6, %17 offset:4096\n\tds_read_b128 %7, %17 offset:6144\n\t"
;                  "s_waitcnt lgkmcnt(8)"
;                  : "=&v"(ag[0]), "=&v"(ag[1]), "=&v"(ag[2]), "=&v"(ag[3]), "=&v"(bg[0]), "=&v"(bg[1]), "=&v"(bg[2]), "=&v"(bg[3]),
;                    "+v"(af[0]), "+v"(af[1]), "+v"(af[2]), "+v"(af[3]), "+v"(bfr[0]), "+v"(bfr[1]), "+v"(bfr[2]), "+v"(bfr[3])
;                  : "v"(sa + a1), "v"(sa + b1) : "memory");
; #pragma unroll
;     for (int mi = 0; mi < 4; ++mi)
; #pragma unroll
;       for (int ni = 0; ni < 4; ++ni) acc[mi][ni] = __builtin_amdgcn_mfma_f32_16x16x32_bf16(bfr[ni], af[mi], acc[mi][ni], 0, 0, 0);
;     asm volatile("s_waitcnt lgkmcnt(0)" : "+v"(ag[0]), "+v"(ag[1]), "+v"(ag[2]), "+v"(ag[3]), "+v"(bg[0]), "+v"(bg[1]), "+v"(bg[2]), "+v"(bg[3]) :: "memory");
; #pragma unroll
;     for (int mi = 0; mi < 4; ++mi)
; #pragma unroll
;       for (int ni = 0; ni < 4; ++ni) acc[mi][ni] = __builtin_amdgcn_mfma_f32_16x16x32_bf16(bg[ni], ag[mi], acc[mi][ni], 0, 0, 0);
	v_mfma_f32_16x16x32_bf16 v[92:95], v[22:25], v[2:5], 0
	v_add_u32_e32 v85, 0x8000, v82
	v_or_b32_e32 v87, 0xc000, v87
	v_mfma_f32_16x16x32_bf16 v[96:99], v[26:29], v[2:5], 0
	s_add_u32 s0, s54, s0
	s_addc_u32 s1, s55, s1
	s_add_u32 s2, s76, s2
	v_mfma_f32_16x16x32_bf16 v[100:103], v[30:33], v[2:5], 0
	s_addc_u32 s3, s77, s3
	s_add_i32 s38, s38, 1
	s_add_i32 s39, s39, s49
	v_mfma_f32_16x16x32_bf16 v[108:111], v[18:21], v[6:9], 0
	v_mfma_f32_16x16x32_bf16 v[112:115], v[22:25], v[6:9], 0
	v_mfma_f32_16x16x32_bf16 v[116:119], v[26:29], v[6:9], 0
	v_mfma_f32_16x16x32_bf16 v[120:123], v[30:33], v[6:9], 0
	v_mfma_f32_16x16x32_bf16 v[124:127], v[18:21], v[10:13], 0
	v_mfma_f32_16x16x32_bf16 v[128:131], v[22:25], v[10:13], 0
	v_mfma_f32_16x16x32_bf16 v[132:135], v[26:29], v[10:13], 0
	s_waitcnt vmcnt(0)
	v_mfma_f32_16x16x32_bf16 v[140:143], v[30:33], v[10:13], 0
	v_mfma_f32_16x16x32_bf16 v[144:147], v[18:21], v[14:17], 0
	v_mfma_f32_16x16x32_bf16 v[148:151], v[22:25], v[14:17], 0
	v_mfma_f32_16x16x32_bf16 v[152:155], v[26:29], v[14:17], 0
	v_mfma_f32_16x16x32_bf16 v[156:159], v[30:33], v[14:17], 0
	v_mfma_f32_16x16x32_bf16 v[2:5], v[50:53], v[34:37], v[42:45]
	v_mfma_f32_16x16x32_bf16 v[6:9], v[54:57], v[34:37], v[92:95]
	v_mfma_f32_16x16x32_bf16 v[10:13], v[58:61], v[34:37], v[96:99]
	v_mfma_f32_16x16x32_bf16 v[14:17], v[88:91], v[34:37], v[100:103]
	v_mfma_f32_16x16x32_bf16 v[18:21], v[50:53], v[38:41], v[108:111]
	v_mfma_f32_16x16x32_bf16 v[22:25], v[54:57], v[38:41], v[112:115]
	v_mfma_f32_16x16x32_bf16 v[26:29], v[58:61], v[38:41], v[116:119]
	v_mfma_f32_16x16x32_bf16 v[30:33], v[88:91], v[38:41], v[120:123]
	v_mfma_f32_16x16x32_bf16 v[34:37], v[50:53], v[46:49], v[124:127]
	v_mfma_f32_16x16x32_bf16 v[38:41], v[54:57], v[46:49], v[128:131]
	v_mfma_f32_16x16x32_bf16 v[42:45], v[58:61], v[46:49], v[132:135]
	v_mfma_f32_16x16x32_bf16 v[46:49], v[88:91], v[46:49], v[140:143]
	v_mfma_f32_16x16x32_bf16 v[50:53], v[50:53], v[62:65], v[144:147]
	v_mfma_f32_16x16x32_bf16 v[54:57], v[54:57], v[62:65], v[148:151]
	v_mfma_f32_16x16x32_bf16 v[58:61], v[58:61], v[62:65], v[152:155]
	v_mfma_f32_16x16x32_bf16 v[62:65], v[88:91], v[62:65], v[156:159]
	v_lshl_add_u64 v[88:89], v[80:81], 0, s[70:71]
	global_load_lds_dwordx4 v[88:89], off
	v_lshl_add_u64 v[88:89], v[78:79], 0, s[70:71]
	s_mov_b32 m0, s41
	s_nop 0
	global_load_lds_dwordx4 v[88:89], off
	v_lshl_add_u64 v[88:89], v[76:77], 0, s[70:71]
	s_mov_b32 m0, s44
	s_nop 0
	global_load_lds_dwordx4 v[88:89], off
	v_lshl_add_u64 v[88:89], v[74:75], 0, s[70:71]
	s_mov_b32 m0, s45
	s_nop 0
	global_load_lds_dwordx4 v[88:89], off
	v_lshl_add_u64 v[88:89], v[72:73], 0, s[70:71]
	s_mov_b32 m0, s46
	s_nop 0
	global_load_lds_dwordx4 v[88:89], off
	v_lshl_add_u64 v[88:89], v[70:71], 0, s[70:71]
	s_mov_b32 m0, s42
	s_nop 0
	global_load_lds_dwordx4 v[88:89], off
	v_lshl_add_u64 v[88:89], v[68:69], 0, s[70:71]
	s_mov_b32 m0, s43
	s_nop 0
	global_load_lds_dwordx4 v[88:89], off
	v_lshl_add_u64 v[88:89], v[66:67], 0, s[70:71]
	s_mov_b32 m0, s31
	s_nop 0
	global_load_lds_dwordx4 v[88:89], off
	v_or_b32_e32 v88, 0xc000, v86
	ds_read_b128 v[90:93], v85
	ds_read_b128 v[94:97], v85 offset:2048
	ds_read_b128 v[98:101], v85 offset:4096
	ds_read_b128 v[102:105], v85 offset:6144
	ds_read_b128 v[108:111], v88
	ds_read_b128 v[112:115], v88 offset:2048
	ds_read_b128 v[116:119], v88 offset:4096
	ds_read_b128 v[120:123], v88 offset:6144
	v_add_u32_e32 v86, 0x8000, v0
	ds_read_b128 v[124:127], v86
	ds_read_b128 v[128:131], v86 offset:2048
	ds_read_b128 v[132:135], v86 offset:4096
	ds_read_b128 v[140:143], v86 offset:6144
	ds_read_b128 v[144:147], v87
	ds_read_b128 v[148:151], v87 offset:2048
	ds_read_b128 v[152:155], v87 offset:4096
	ds_read_b128 v[156:159], v87 offset:6144
	s_waitcnt lgkmcnt(8)
	s_mov_b32 m0, s21
	s_waitcnt lgkmcnt(0)
	v_mfma_f32_16x16x32_bf16 v[2:5], v[108:111], v[90:93], v[2:5]
	s_waitcnt vmcnt(0)
	s_barrier
	v_mfma_f32_16x16x32_bf16 v[6:9], v[112:115], v[90:93], v[6:9]
	v_mfma_f32_16x16x32_bf16 v[10:13], v[116:119], v[90:93], v[10:13]
	v_mfma_f32_16x16x32_bf16 v[14:17], v[120:123], v[90:93], v[14:17]
	v_lshl_add_u64 v[90:91], v[80:81], 0, s[72:73]
	global_load_lds_dwordx4 v[90:91], off
	v_lshl_add_u64 v[90:91], v[78:79], 0, s[72:73]
	s_mov_b32 m0, s20
	v_mfma_f32_16x16x32_bf16 v[18:21], v[108:111], v[94:97], v[18:21]
	global_load_lds_dwordx4 v[90:91], off
	v_lshl_add_u64 v[90:91], v[76:77], 0, s[72:73]
	s_mov_b32 m0, s23
	v_mfma_f32_16x16x32_bf16 v[22:25], v[112:115], v[94:97], v[22:25]
	global_load_lds_dwordx4 v[90:91], off
	v_lshl_add_u64 v[90:91], v[74:75], 0, s[72:73]
	s_mov_b32 m0, s25
	v_mfma_f32_16x16x32_bf16 v[26:29], v[116:119], v[94:97], v[26:29]
	global_load_lds_dwordx4 v[90:91], off
	v_lshl_add_u64 v[90:91], v[72:73], 0, s[72:73]
	s_mov_b32 m0, s26
	v_mfma_f32_16x16x32_bf16 v[30:33], v[120:123], v[94:97], v[30:33]
	global_load_lds_dwordx4 v[90:91], off
	v_lshl_add_u64 v[90:91], v[70:71], 0, s[72:73]
	s_mov_b32 m0, s27
	v_mfma_f32_16x16x32_bf16 v[34:37], v[108:111], v[98:101], v[34:37]
	global_load_lds_dwordx4 v[90:91], off
	v_lshl_add_u64 v[90:91], v[68:69], 0, s[72:73]
	v_mfma_f32_16x16x32_bf16 v[38:41], v[112:115], v[98:101], v[38:41]
	s_mov_b32 m0, s30
	s_nop 0
	global_load_lds_dwordx4 v[90:91], off
	v_mfma_f32_16x16x32_bf16 v[42:45], v[116:119], v[98:101], v[42:45]
	v_lshl_add_u64 v[90:91], v[66:67], 0, s[72:73]
	s_mov_b32 m0, s47
	v_mfma_f32_16x16x32_bf16 v[46:49], v[120:123], v[98:101], v[46:49]
	global_load_lds_dwordx4 v[90:91], off
	s_mov_b32 m0, s40
	v_mfma_f32_16x16x32_bf16 v[50:53], v[108:111], v[102:105], v[50:53]
	v_mfma_f32_16x16x32_bf16 v[54:57], v[112:115], v[102:105], v[54:57]
; DI void gemm_dma(f32x4 (&acc)[4][4], const bf16_t* Ap, int lda, const bf16_t* Bp, int ldb, int K, char* lds) {
;     ...
;   for (int kt = 0; kt < nk; ++kt) {
;     asm volatile("s_waitcnt vmcnt(0)" ::: "memory");
;     __builtin_amdgcn_s_barrier();
;     asm volatile("" ::: "memory");
;     if (kt + 1 < nk) issue(kt + 1);
;     const unsigned sa = lbase + (unsigned)((kt & 1) * 32768);
;     bf16x8 af[4], bfr[4], ag[4], bg[4];
;     asm volatile("ds_read_b128 %0, %8\n\tds_read_b128 %1, %8 offset:2048\n\tds_read_b128 %2, %8 offset:4096\n\tds_read_b128 %3, %8 offset:6144\n\t"
;                  "ds_read_b128 %4, %9\n\tds_read_b128 %5, %9 offset:2048\n\tds_read_b128 %6, %9 offset:4096\n\tds_read_b128 %7, %9 offset:6144"
;                  : "=&v"(af[0]), "=&v"(af[1]), "=&v"(af[2]), "=&v"(af[3]), "=&v"(bfr[0]), "=&v"(bfr[1]), "=&v"(bfr[2]), "=&v"(bfr[3])
;                  : "v"(sa + a0), "v"(sa + b0) : "memory");
;     asm volatile("ds_read_b128 %0, %16\n\tds_read_b128 %1, %16 offset:2048\n\tds_read_b128 %2, %16 offset:4096\n\tds_read_b128 %3, %16 offset:6144\n\t"
;                  "ds_read_b128 %4, %17\n\tds_read_b128 %5, %17 offset:2048\n\tds_read_b128 %6, %17 offset:4096\n\tds_read_b128 %7, %17 offset:6144\n\t"
;                  "s_waitcnt lgkmcnt(8)"
;                  : "=&v"(ag[0]), "=&v"(ag[1]), "=&v"(ag[2]), "=&v"(ag[3]), "=&v"(bg[0]), "=&v"(bg[1]), "=&v"(bg[2]), "=&v"(bg[3]),
;                    "+v"(af[0]), "+v"(af[1]), "+v"(af[2]), "+v"(af[3]), "+v"(bfr[0]), "+v"(bfr[1]), "+v"(bfr[2]), "+v"(bfr[3])
;                  : "v"(sa + a1), "v"(sa + b1) : "memory");
; #pragma unroll
;     for (int mi = 0; mi < 4; ++mi)
; #pragma unroll
;       for (int ni = 0; ni < 4; ++ni) acc[mi][ni] = __builtin_amdgcn_mfma_f32_16x16x32_bf16(bfr[ni], af[mi], acc[mi][ni], 0, 0, 0);
;     asm volatile("s_waitcnt lgkmcnt(0)" : "+v"(ag[0]), "+v"(ag[1]), "+v"(ag[2]), "+v"(ag[3]), "+v"(bg[0]), "+v"(bg[1]), "+v"(bg[2]), "+v"(bg[3]) :: "memory");
; #pragma unroll
;     for (int mi = 0; mi < 4; ++mi)
; #pragma unroll
;       for (int ni = 0; ni < 4; ++ni) acc[mi][ni] = __builtin_amdgcn_mfma_f32_16x16x32_bf16(bg[ni], ag[mi], acc[mi][ni], 0, 0, 0);
	v_mfma_f32_16x16x32_bf16 v[58:61], v[116:119], v[102:105], v[58:61]
	v_mfma_f32_16x16x32_bf16 v[62:65], v[120:123], v[102:105], v[62:65]
	ds_read_b128 v[90:93], v82
	ds_read_b128 v[94:97], v82 offset:2048
	ds_read_b128 v[98:101], v82 offset:4096
	ds_read_b128 v[102:105], v82 offset:6144
	ds_read_b128 v[108:111], v84
	ds_read_b128 v[112:115], v84 offset:2048
	ds_read_b128 v[116:119], v84 offset:4096
	ds_read_b128 v[120:123], v84 offset:6144
	v_mfma_f32_16x16x32_bf16 v[2:5], v[144:147], v[124:127], v[2:5]
	v_mfma_f32_16x16x32_bf16 v[6:9], v[148:151], v[124:127], v[6:9]
	v_mfma_f32_16x16x32_bf16 v[10:13], v[152:155], v[124:127], v[10:13]
	v_mfma_f32_16x16x32_bf16 v[14:17], v[156:159], v[124:127], v[14:17]
	v_mfma_f32_16x16x32_bf16 v[18:21], v[144:147], v[128:131], v[18:21]
	v_mfma_f32_16x16x32_bf16 v[22:25], v[148:151], v[128:131], v[22:25]
	v_mfma_f32_16x16x32_bf16 v[26:29], v[152:155], v[128:131], v[26:29]
	v_mfma_f32_16x16x32_bf16 v[30:33], v[156:159], v[128:131], v[30:33]
	v_mfma_f32_16x16x32_bf16 v[34:37], v[144:147], v[132:135], v[34:37]
	v_mfma_f32_16x16x32_bf16 v[38:41], v[148:151], v[132:135], v[38:41]
	v_mfma_f32_16x16x32_bf16 v[42:45], v[152:155], v[132:135], v[42:45]
	v_mfma_f32_16x16x32_bf16 v[46:49], v[156:159], v[132:135], v[46:49]
	v_mfma_f32_16x16x32_bf16 v[50:53], v[144:147], v[140:143], v[50:53]
	v_mfma_f32_16x16x32_bf16 v[54:57], v[148:151], v[140:143], v[54:57]
	v_mfma_f32_16x16x32_bf16 v[58:61], v[152:155], v[140:143], v[58:61]
	v_mfma_f32_16x16x32_bf16 v[62:65], v[156:159], v[140:143], v[62:65]
	ds_read_b128 v[124:127], v0
	ds_read_b128 v[128:131], v0 offset:2048
	ds_read_b128 v[132:135], v0 offset:4096
	ds_read_b128 v[140:143], v0 offset:6144
	ds_read_b128 v[144:147], v83
	ds_read_b128 v[148:151], v83 offset:2048
	ds_read_b128 v[152:155], v83 offset:4096
	ds_read_b128 v[156:159], v83 offset:6144
	s_waitcnt lgkmcnt(8)
	s_nop 0
	s_waitcnt lgkmcnt(0)
	v_mfma_f32_16x16x32_bf16 v[2:5], v[108:111], v[90:93], v[2:5]
	s_waitcnt vmcnt(0)
	s_barrier
	v_mfma_f32_16x16x32_bf16 v[6:9], v[112:115], v[90:93], v[6:9]
	v_mfma_f32_16x16x32_bf16 v[10:13], v[116:119], v[90:93], v[10:13]
	v_mfma_f32_16x16x32_bf16 v[14:17], v[120:123], v[90:93], v[14:17]
	v_lshl_add_u64 v[90:91], v[80:81], 0, s[68:69]
	global_load_lds_dwordx4 v[90:91], off
	v_lshl_add_u64 v[90:91], v[78:79], 0, s[68:69]
	s_mov_b32 m0, s41
	v_mfma_f32_16x16x32_bf16 v[18:21], v[108:111], v[94:97], v[18:21]
	global_load_lds_dwordx4 v[90:91], off
	v_lshl_add_u64 v[90:91], v[76:77], 0, s[68:69]
	s_mov_b32 m0, s44
	v_mfma_f32_16x16x32_bf16 v[22:25], v[112:115], v[94:97], v[22:25]
	global_load_lds_dwordx4 v[90:91], off
	v_lshl_add_u64 v[90:91], v[74:75], 0, s[68:69]
	s_mov_b32 m0, s45
	v_mfma_f32_16x16x32_bf16 v[26:29], v[116:119], v[94:97], v[26:29]
	global_load_lds_dwordx4 v[90:91], off
	v_lshl_add_u64 v[90:91], v[72:73], 0, s[68:69]
	s_mov_b32 m0, s46
	v_mfma_f32_16x16x32_bf16 v[30:33], v[120:123], v[94:97], v[30:33]
	global_load_lds_dwordx4 v[90:91], off
	v_lshl_add_u64 v[90:91], v[70:71], 0, s[68:69]
	s_mov_b32 m0, s42
	v_mfma_f32_16x16x32_bf16 v[34:37], v[108:111], v[98:101], v[34:37]
	global_load_lds_dwordx4 v[90:91], off
	v_lshl_add_u64 v[90:91], v[68:69], 0, s[68:69]
	v_mfma_f32_16x16x32_bf16 v[38:41], v[112:115], v[98:101], v[38:41]
	s_mov_b32 m0, s43
	s_nop 0
	global_load_lds_dwordx4 v[90:91], off
	v_mfma_f32_16x16x32_bf16 v[42:45], v[116:119], v[98:101], v[42:45]
	v_lshl_add_u64 v[90:91], v[66:67], 0, s[68:69]
	s_mov_b32 m0, s31
	v_mfma_f32_16x16x32_bf16 v[46:49], v[120:123], v[98:101], v[46:49]
	global_load_lds_dwordx4 v[90:91], off
	s_mov_b32 m0, s21
	v_mfma_f32_16x16x32_bf16 v[50:53], v[108:111], v[102:105], v[50:53]
	v_mfma_f32_16x16x32_bf16 v[54:57], v[112:115], v[102:105], v[54:57]
	v_mfma_f32_16x16x32_bf16 v[58:61], v[116:119], v[102:105], v[58:61]
	v_mfma_f32_16x16x32_bf16 v[62:65], v[120:123], v[102:105], v[62:65]
	ds_read_b128 v[90:93], v85
	ds_read_b128 v[94:97], v85 offset:2048
	ds_read_b128 v[98:101], v85 offset:4096
	ds_read_b128 v[102:105], v85 offset:6144
	ds_read_b128 v[108:111], v88
	ds_read_b128 v[112:115], v88 offset:2048
	ds_read_b128 v[116:119], v88 offset:4096
	ds_read_b128 v[120:123], v88 offset:6144
	v_mfma_f32_16x16x32_bf16 v[2:5], v[144:147], v[124:127], v[2:5]
	v_mfma_f32_16x16x32_bf16 v[6:9], v[148:151], v[124:127], v[6:9]
	v_mfma_f32_16x16x32_bf16 v[10:13], v[152:155], v[124:127], v[10:13]
	v_mfma_f32_16x16x32_bf16 v[14:17], v[156:159], v[124:127], v[14:17]
	v_mfma_f32_16x16x32_bf16 v[18:21], v[144:147], v[128:131], v[18:21]
	v_mfma_f32_16x16x32_bf16 v[22:25], v[148:151], v[128:131], v[22:25]
	v_mfma_f32_16x16x32_bf16 v[26:29], v[152:155], v[128:131], v[26:29]
	v_mfma_f32_16x16x32_bf16 v[30:33], v[156:159], v[128:131], v[30:33]
	v_mfma_f32_16x16x32_bf16 v[34:37], v[144:147], v[132:135], v[34:37]
	v_mfma_f32_16x16x32_bf16 v[38:41], v[148:151], v[132:135], v[38:41]
	v_mfma_f32_16x16x32_bf16 v[42:45], v[152:155], v[132:135], v[42:45]
	v_mfma_f32_16x16x32_bf16 v[46:49], v[156:159], v[132:135], v[46:49]
	v_mfma_f32_16x16x32_bf16 v[50:53], v[144:147], v[140:143], v[50:53]
	v_mfma_f32_16x16x32_bf16 v[54:57], v[148:151], v[140:143], v[54:57]
	v_mfma_f32_16x16x32_bf16 v[58:61], v[152:155], v[140:143], v[58:61]
	v_mfma_f32_16x16x32_bf16 v[62:65], v[156:159], v[140:143], v[62:65]
	ds_read_b128 v[124:127], v86
	ds_read_b128 v[128:131], v86 offset:2048
	ds_read_b128 v[132:135], v86 offset:4096
	ds_read_b128 v[140:143], v86 offset:6144
	ds_read_b128 v[144:147], v87
	ds_read_b128 v[148:151], v87 offset:2048
	ds_read_b128 v[152:155], v87 offset:4096
	ds_read_b128 v[156:159], v87 offset:6144
	s_waitcnt lgkmcnt(8)
	s_nop 0
	s_waitcnt lgkmcnt(0)
	v_mfma_f32_16x16x32_bf16 v[2:5], v[108:111], v[90:93], v[2:5]
	s_waitcnt vmcnt(0)
	s_barrier
; DI void gemm_dma(f32x4 (&acc)[4][4], const bf16_t* Ap, int lda, const bf16_t* Bp, int ldb, int K, char* lds) {
;     ...
;   for (int kt = 0; kt < nk; ++kt) {
;     asm volatile("s_waitcnt vmcnt(0)" ::: "memory");
;     __builtin_amdgcn_s_barrier();
;     asm volatile("" ::: "memory");
;     if (kt + 1 < nk) issue(kt + 1);
;     const unsigned sa = lbase + (unsigned)((kt & 1) * 32768);
;     bf16x8 af[4], bfr[4], ag[4], bg[4];
;     asm volatile("ds_read_b128 %0, %8\n\tds_read_b128 %1, %8 offset:2048\n\tds_read_b128 %2, %8 offset:4096\n\tds_read_b128 %3, %8 offset:6144\n\t"
;                  "ds_read_b128 %4, %9\n\tds_read_b128 %5, %9 offset:2048\n\tds_read_b128 %6, %9 offset:4096\n\tds_read_b128 %7, %9 offset:6144"
;                  : "=&v"(af[0]), "=&v"(af[1]), "=&v"(af[2]), "=&v"(af[3]), "=&v"(bfr[0]), "=&v"(bfr[1]), "=&v"(bfr[2]), "=&v"(bfr[3])
;                  : "v"(sa + a0), "v"(sa + b0) : "memory");
;     asm volatile("ds_read_b128 %0, %16\n\tds_read_b128 %1, %16 offset:2048\n\tds_read_b128 %2, %16 offset:4096\n\tds_read_b128 %3, %16 offset:6144\n\t"
;                  "ds_read_b128 %4, %17\n\tds_read_b128 %5, %17 offset:2048\n\tds_read_b128 %6, %17 offset:4096\n\tds_read_b128 %7, %17 offset:6144\n\t"
;                  "s_waitcnt lgkmcnt(8)"
;                  : "=&v"(ag[0]), "=&v"(ag[1]), "=&v"(ag[2]), "=&v"(ag[3]), "=&v"(bg[0]), "=&v"(bg[1]), "=&v"(bg[2]), "=&v"(bg[3]),
;                    "+v"(af[0]), "+v"(af[1]), "+v"(af[2]), "+v"(af[3]), "+v"(bfr[0]), "+v"(bfr[1]), "+v"(bfr[2]), "+v"(bfr[3])
;                  : "v"(sa + a1), "v"(sa + b1) : "memory");
; #pragma unroll
;     for (int mi = 0; mi < 4; ++mi)
; #pragma unroll
;       for (int ni = 0; ni < 4; ++ni) acc[mi][ni] = __builtin_amdgcn_mfma_f32_16x16x32_bf16(bfr[ni], af[mi], acc[mi][ni], 0, 0, 0);
;     asm volatile("s_waitcnt lgkmcnt(0)" : "+v"(ag[0]), "+v"(ag[1]), "+v"(ag[2]), "+v"(ag[3]), "+v"(bg[0]), "+v"(bg[1]), "+v"(bg[2]), "+v"(bg[3]) :: "memory");
; #pragma unroll
;     for (int mi = 0; mi < 4; ++mi)
; #pragma unroll
;       for (int ni = 0; ni < 4; ++ni) acc[mi][ni] = __builtin_amdgcn_mfma_f32_16x16x32_bf16(bg[ni], ag[mi], acc[mi][ni], 0, 0, 0);
	v_mfma_f32_16x16x32_bf16 v[6:9], v[112:115], v[90:93], v[6:9]
	v_mfma_f32_16x16x32_bf16 v[10:13], v[116:119], v[90:93], v[10:13]
	v_mfma_f32_16x16x32_bf16 v[14:17], v[120:123], v[90:93], v[14:17]
	v_lshl_add_u64 v[90:91], v[80:81], 0, s[78:79]
	global_load_lds_dwordx4 v[90:91], off
	v_lshl_add_u64 v[90:91], v[78:79], 0, s[78:79]
	s_mov_b32 m0, s20
	v_mfma_f32_16x16x32_bf16 v[18:21], v[108:111], v[94:97], v[18:21]
	global_load_lds_dwordx4 v[90:91], off
	v_lshl_add_u64 v[90:91], v[76:77], 0, s[78:79]
	s_mov_b32 m0, s23
	v_mfma_f32_16x16x32_bf16 v[22:25], v[112:115], v[94:97], v[22:25]
	global_load_lds_dwordx4 v[90:91], off
	v_lshl_add_u64 v[90:91], v[74:75], 0, s[78:79]
	s_mov_b32 m0, s25
	v_mfma_f32_16x16x32_bf16 v[26:29], v[116:119], v[94:97], v[26:29]
	global_load_lds_dwordx4 v[90:91], off
	v_lshl_add_u64 v[90:91], v[72:73], 0, s[78:79]
	s_mov_b32 m0, s26
	v_mfma_f32_16x16x32_bf16 v[30:33], v[120:123], v[94:97], v[30:33]
	global_load_lds_dwordx4 v[90:91], off
	v_lshl_add_u64 v[90:91], v[70:71], 0, s[78:79]
	s_mov_b32 m0, s27
	v_mfma_f32_16x16x32_bf16 v[34:37], v[108:111], v[98:101], v[34:37]
	global_load_lds_dwordx4 v[90:91], off
	v_lshl_add_u64 v[90:91], v[68:69], 0, s[78:79]
	v_mfma_f32_16x16x32_bf16 v[38:41], v[112:115], v[98:101], v[38:41]
	s_mov_b32 m0, s30
	s_nop 0
	global_load_lds_dwordx4 v[90:91], off
	v_mfma_f32_16x16x32_bf16 v[42:45], v[116:119], v[98:101], v[42:45]
	v_lshl_add_u64 v[90:91], v[66:67], 0, s[78:79]
	s_mov_b32 m0, s47
	v_mfma_f32_16x16x32_bf16 v[46:49], v[120:123], v[98:101], v[46:49]
	global_load_lds_dwordx4 v[90:91], off
	s_mov_b32 m0, s40
	v_mfma_f32_16x16x32_bf16 v[50:53], v[108:111], v[102:105], v[50:53]
	v_mfma_f32_16x16x32_bf16 v[54:57], v[112:115], v[102:105], v[54:57]
	v_mfma_f32_16x16x32_bf16 v[58:61], v[116:119], v[102:105], v[58:61]
	v_mfma_f32_16x16x32_bf16 v[62:65], v[120:123], v[102:105], v[62:65]
	ds_read_b128 v[90:93], v82
	ds_read_b128 v[94:97], v82 offset:2048
	ds_read_b128 v[98:101], v82 offset:4096
	ds_read_b128 v[102:105], v82 offset:6144
	ds_read_b128 v[108:111], v84
	ds_read_b128 v[112:115], v84 offset:2048
	ds_read_b128 v[116:119], v84 offset:4096
	ds_read_b128 v[120:123], v84 offset:6144
	v_mfma_f32_16x16x32_bf16 v[2:5], v[144:147], v[124:127], v[2:5]
	v_mfma_f32_16x16x32_bf16 v[6:9], v[148:151], v[124:127], v[6:9]
	v_mfma_f32_16x16x32_bf16 v[10:13], v[152:155], v[124:127], v[10:13]
	v_mfma_f32_16x16x32_bf16 v[14:17], v[156:159], v[124:127], v[14:17]
	v_mfma_f32_16x16x32_bf16 v[18:21], v[144:147], v[128:131], v[18:21]
	v_mfma_f32_16x16x32_bf16 v[22:25], v[148:151], v[128:131], v[22:25]
	v_mfma_f32_16x16x32_bf16 v[26:29], v[152:155], v[128:131], v[26:29]
	v_mfma_f32_16x16x32_bf16 v[30:33], v[156:159], v[128:131], v[30:33]
	v_mfma_f32_16x16x32_bf16 v[34:37], v[144:147], v[132:135], v[34:37]
	v_mfma_f32_16x16x32_bf16 v[38:41], v[148:151], v[132:135], v[38:41]
	v_mfma_f32_16x16x32_bf16 v[42:45], v[152:155], v[132:135], v[42:45]
	v_mfma_f32_16x16x32_bf16 v[46:49], v[156:159], v[132:135], v[46:49]
	v_mfma_f32_16x16x32_bf16 v[50:53], v[144:147], v[140:143], v[50:53]
	v_mfma_f32_16x16x32_bf16 v[54:57], v[148:151], v[140:143], v[54:57]
	v_mfma_f32_16x16x32_bf16 v[58:61], v[152:155], v[140:143], v[58:61]
	v_mfma_f32_16x16x32_bf16 v[62:65], v[156:159], v[140:143], v[62:65]
	ds_read_b128 v[124:127], v0
	ds_read_b128 v[128:131], v0 offset:2048
	ds_read_b128 v[132:135], v0 offset:4096
	ds_read_b128 v[140:143], v0 offset:6144
	ds_read_b128 v[144:147], v83
	ds_read_b128 v[148:151], v83 offset:2048
	ds_read_b128 v[152:155], v83 offset:4096
	ds_read_b128 v[156:159], v83 offset:6144
	s_waitcnt lgkmcnt(8)
	s_nop 0
	s_waitcnt lgkmcnt(0)
	v_mfma_f32_16x16x32_bf16 v[2:5], v[108:111], v[90:93], v[2:5]
	s_waitcnt vmcnt(0)
	s_barrier
	v_mfma_f32_16x16x32_bf16 v[6:9], v[112:115], v[90:93], v[6:9]
	v_mfma_f32_16x16x32_bf16 v[10:13], v[116:119], v[90:93], v[10:13]
	v_mfma_f32_16x16x32_bf16 v[14:17], v[120:123], v[90:93], v[14:17]
	v_lshl_add_u64 v[90:91], v[80:81], 0, s[80:81]
	global_load_lds_dwordx4 v[90:91], off
	v_lshl_add_u64 v[90:91], v[78:79], 0, s[80:81]
	s_mov_b32 m0, s41
	v_mfma_f32_16x16x32_bf16 v[18:21], v[108:111], v[94:97], v[18:21]
	global_load_lds_dwordx4 v[90:91], off
	v_lshl_add_u64 v[90:91], v[76:77], 0, s[80:81]
	s_mov_b32 m0, s44
	v_mfma_f32_16x16x32_bf16 v[22:25], v[112:115], v[94:97], v[22:25]
	global_load_lds_dwordx4 v[90:91], off
	v_lshl_add_u64 v[90:91], v[74:75], 0, s[80:81]
	s_mov_b32 m0, s45
	v_mfma_f32_16x16x32_bf16 v[26:29], v[116:119], v[94:97], v[26:29]
	global_load_lds_dwordx4 v[90:91], off
	v_lshl_add_u64 v[90:91], v[72:73], 0, s[80:81]
	s_mov_b32 m0, s46
	v_mfma_f32_16x16x32_bf16 v[30:33], v[120:123], v[94:97], v[30:33]
	global_load_lds_dwordx4 v[90:91], off
	v_lshl_add_u64 v[90:91], v[70:71], 0, s[80:81]
	s_mov_b32 m0, s42
	v_mfma_f32_16x16x32_bf16 v[34:37], v[108:111], v[98:101], v[34:37]
	global_load_lds_dwordx4 v[90:91], off
	v_lshl_add_u64 v[90:91], v[68:69], 0, s[80:81]
	v_mfma_f32_16x16x32_bf16 v[38:41], v[112:115], v[98:101], v[38:41]
	s_mov_b32 m0, s43
	v_lshl_add_u64 v[80:81], v[80:81], 0, s[88:89]
	global_load_lds_dwordx4 v[90:91], off
	v_mfma_f32_16x16x32_bf16 v[42:45], v[116:119], v[98:101], v[42:45]
	v_lshl_add_u64 v[90:91], v[66:67], 0, s[80:81]
	s_mov_b32 m0, s31
	v_lshl_add_u64 v[78:79], v[78:79], 0, s[88:89]
	v_mfma_f32_16x16x32_bf16 v[46:49], v[120:123], v[98:101], v[46:49]
	global_load_lds_dwordx4 v[90:91], off
	s_mov_b32 m0, s21
	v_mfma_f32_16x16x32_bf16 v[50:53], v[108:111], v[102:105], v[50:53]
	v_lshl_add_u64 v[76:77], v[76:77], 0, s[88:89]
	v_lshl_add_u64 v[74:75], v[74:75], 0, s[88:89]
	v_lshl_add_u64 v[72:73], v[72:73], 0, s[88:89]
; DI void gemm_dma(f32x4 (&acc)[4][4], const bf16_t* Ap, int lda, const bf16_t* Bp, int ldb, int K, char* lds) {
;     ...
;   for (int kt = 0; kt < nk; ++kt) {
;     asm volatile("s_waitcnt vmcnt(0)" ::: "memory");
;     __builtin_amdgcn_s_barrier();
;     asm volatile("" ::: "memory");
;     if (kt + 1 < nk) issue(kt + 1);
;     const unsigned sa = lbase + (unsigned)((kt & 1) * 32768);
;     bf16x8 af[4], bfr[4], ag[4], bg[4];
;     asm volatile("ds_read_b128 %0, %8\n\tds_read_b128 %1, %8 offset:2048\n\tds_read_b128 %2, %8 offset:4096\n\tds_read_b128 %3, %8 offset:6144\n\t"
;                  "ds_read_b128 %4, %9\n\tds_read_b128 %5, %9 offset:2048\n\tds_read_b128 %6, %9 offset:4096\n\tds_read_b128 %7, %9 offset:6144"
;                  : "=&v"(af[0]), "=&v"(af[1]), "=&v"(af[2]), "=&v"(af[3]), "=&v"(bfr[0]), "=&v"(bfr[1]), "=&v"(bfr[2]), "=&v"(bfr[3])
;                  : "v"(sa + a0), "v"(sa + b0) : "memory");
;     asm volatile("ds_read_b128 %0, %16\n\tds_read_b128 %1, %16 offset:2048\n\tds_read_b128 %2, %16 offset:4096\n\tds_read_b128 %3, %16 offset:6144\n\t"
;                  "ds_read_b128 %4, %17\n\tds_read_b128 %5, %17 offset:2048\n\tds_read_b128 %6, %17 offset:4096\n\tds_read_b128 %7, %17 offset:6144\n\t"
;                  "s_waitcnt lgkmcnt(8)"
;                  : "=&v"(ag[0]), "=&v"(ag[1]), "=&v"(ag[2]), "=&v"(ag[3]), "=&v"(bg[0]), "=&v"(bg[1]), "=&v"(bg[2]), "=&v"(bg[3]),
;                    "+v"(af[0]), "+v"(af[1]), "+v"(af[2]), "+v"(af[3]), "+v"(bfr[0]), "+v"(bfr[1]), "+v"(bfr[2]), "+v"(bfr[3])
;                  : "v"(sa + a1), "v"(sa + b1) : "memory");
; #pragma unroll
;     for (int mi = 0; mi < 4; ++mi)
; #pragma unroll
;       for (int ni = 0; ni < 4; ++ni) acc[mi][ni] = __builtin_amdgcn_mfma_f32_16x16x32_bf16(bfr[ni], af[mi], acc[mi][ni], 0, 0, 0);
;     asm volatile("s_waitcnt lgkmcnt(0)" : "+v"(ag[0]), "+v"(ag[1]), "+v"(ag[2]), "+v"(ag[3]), "+v"(bg[0]), "+v"(bg[1]), "+v"(bg[2]), "+v"(bg[3]) :: "memory");
; #pragma unroll
;     for (int mi = 0; mi < 4; ++mi)
; #pragma unroll
;       for (int ni = 0; ni < 4; ++ni) acc[mi][ni] = __builtin_amdgcn_mfma_f32_16x16x32_bf16(bg[ni], ag[mi], acc[mi][ni], 0, 0, 0);
	v_mfma_f32_16x16x32_bf16 v[54:57], v[112:115], v[102:105], v[54:57]
	v_lshl_add_u64 v[70:71], v[70:71], 0, s[88:89]
	v_lshl_add_u64 v[68:69], v[68:69], 0, s[88:89]
	v_lshl_add_u64 v[66:67], v[66:67], 0, s[88:89]
	v_mfma_f32_16x16x32_bf16 v[58:61], v[116:119], v[102:105], v[58:61]
	v_mfma_f32_16x16x32_bf16 v[62:65], v[120:123], v[102:105], v[62:65]
	ds_read_b128 v[90:93], v85
	ds_read_b128 v[94:97], v85 offset:2048
	ds_read_b128 v[98:101], v85 offset:4096
	ds_read_b128 v[102:105], v85 offset:6144
	ds_read_b128 v[108:111], v88
	ds_read_b128 v[112:115], v88 offset:2048
	ds_read_b128 v[116:119], v88 offset:4096
	ds_read_b128 v[120:123], v88 offset:6144
	v_mfma_f32_16x16x32_bf16 v[2:5], v[144:147], v[124:127], v[2:5]
	v_mfma_f32_16x16x32_bf16 v[6:9], v[148:151], v[124:127], v[6:9]
	v_mfma_f32_16x16x32_bf16 v[10:13], v[152:155], v[124:127], v[10:13]
	v_mfma_f32_16x16x32_bf16 v[14:17], v[156:159], v[124:127], v[14:17]
	v_mfma_f32_16x16x32_bf16 v[18:21], v[144:147], v[128:131], v[18:21]
	v_mfma_f32_16x16x32_bf16 v[22:25], v[148:151], v[128:131], v[22:25]
	v_mfma_f32_16x16x32_bf16 v[26:29], v[152:155], v[128:131], v[26:29]
	v_mfma_f32_16x16x32_bf16 v[30:33], v[156:159], v[128:131], v[30:33]
	v_mfma_f32_16x16x32_bf16 v[34:37], v[144:147], v[132:135], v[34:37]
	v_mfma_f32_16x16x32_bf16 v[38:41], v[148:151], v[132:135], v[38:41]
	v_mfma_f32_16x16x32_bf16 v[42:45], v[152:155], v[132:135], v[42:45]
	v_mfma_f32_16x16x32_bf16 v[46:49], v[156:159], v[132:135], v[46:49]
	v_mfma_f32_16x16x32_bf16 v[50:53], v[144:147], v[140:143], v[50:53]
	v_mfma_f32_16x16x32_bf16 v[54:57], v[148:151], v[140:143], v[54:57]
	v_mfma_f32_16x16x32_bf16 v[58:61], v[152:155], v[140:143], v[58:61]
	v_mfma_f32_16x16x32_bf16 v[62:65], v[156:159], v[140:143], v[62:65]
	ds_read_b128 v[124:127], v86
	ds_read_b128 v[128:131], v86 offset:2048
	ds_read_b128 v[132:135], v86 offset:4096
	ds_read_b128 v[140:143], v86 offset:6144
	ds_read_b128 v[144:147], v87
	ds_read_b128 v[148:151], v87 offset:2048
	ds_read_b128 v[152:155], v87 offset:4096
	ds_read_b128 v[156:159], v87 offset:6144
	s_waitcnt lgkmcnt(8)
	s_nop 0
	s_waitcnt lgkmcnt(0)
	s_waitcnt vmcnt(0)
	s_barrier
	global_load_lds_dwordx4 v[80:81], off
	s_mov_b32 m0, s20
	v_mfma_f32_16x16x32_bf16 v[26:29], v[116:119], v[94:97], v[26:29]
	global_load_lds_dwordx4 v[78:79], off
	s_mov_b32 m0, s23
	v_mfma_f32_16x16x32_bf16 v[38:41], v[112:115], v[98:101], v[38:41]
	global_load_lds_dwordx4 v[76:77], off
	s_mov_b32 m0, s25
	v_mfma_f32_16x16x32_bf16 v[22:25], v[112:115], v[94:97], v[22:25]
	global_load_lds_dwordx4 v[74:75], off
	s_mov_b32 m0, s26
	v_mfma_f32_16x16x32_bf16 v[42:45], v[116:119], v[98:101], v[42:45]
	global_load_lds_dwordx4 v[72:73], off
	s_mov_b32 m0, s27
	v_mfma_f32_16x16x32_bf16 v[2:5], v[108:111], v[90:93], v[2:5]
	global_load_lds_dwordx4 v[70:71], off
	s_mov_b32 m0, s30
	v_mfma_f32_16x16x32_bf16 v[6:9], v[112:115], v[90:93], v[6:9]
	global_load_lds_dwordx4 v[68:69], off
	s_mov_b32 m0, s47
	v_mfma_f32_16x16x32_bf16 v[10:13], v[116:119], v[90:93], v[10:13]
	global_load_lds_dwordx4 v[66:67], off
	v_mfma_f32_16x16x32_bf16 v[14:17], v[120:123], v[90:93], v[14:17]
	v_mfma_f32_16x16x32_bf16 v[18:21], v[108:111], v[94:97], v[18:21]
	v_mfma_f32_16x16x32_bf16 v[30:33], v[120:123], v[94:97], v[30:33]
	v_mfma_f32_16x16x32_bf16 v[34:37], v[108:111], v[98:101], v[34:37]
	v_mfma_f32_16x16x32_bf16 v[46:49], v[120:123], v[98:101], v[46:49]
	v_mfma_f32_16x16x32_bf16 v[50:53], v[108:111], v[102:105], v[50:53]
	v_mfma_f32_16x16x32_bf16 v[54:57], v[112:115], v[102:105], v[54:57]
	v_mfma_f32_16x16x32_bf16 v[58:61], v[116:119], v[102:105], v[58:61]
	v_mfma_f32_16x16x32_bf16 v[62:65], v[120:123], v[102:105], v[62:65]
	ds_read_b128 v[66:69], v82
	ds_read_b128 v[70:73], v82 offset:2048
	ds_read_b128 v[74:77], v82 offset:4096
	ds_read_b128 v[78:81], v82 offset:6144
	ds_read_b128 v[90:93], v84
	ds_read_b128 v[94:97], v84 offset:2048
	ds_read_b128 v[98:101], v84 offset:4096
	ds_read_b128 v[102:105], v84 offset:6144
	v_mfma_f32_16x16x32_bf16 v[26:29], v[152:155], v[128:131], v[26:29]
	v_mfma_f32_16x16x32_bf16 v[38:41], v[148:151], v[132:135], v[38:41]
	v_mfma_f32_16x16x32_bf16 v[22:25], v[148:151], v[128:131], v[22:25]
	v_mfma_f32_16x16x32_bf16 v[42:45], v[152:155], v[132:135], v[42:45]
	v_mfma_f32_16x16x32_bf16 v[2:5], v[144:147], v[124:127], v[2:5]
	v_mfma_f32_16x16x32_bf16 v[6:9], v[148:151], v[124:127], v[6:9]
	v_mfma_f32_16x16x32_bf16 v[10:13], v[152:155], v[124:127], v[10:13]
	v_mfma_f32_16x16x32_bf16 v[14:17], v[156:159], v[124:127], v[14:17]
	v_mfma_f32_16x16x32_bf16 v[18:21], v[144:147], v[128:131], v[18:21]
	v_mfma_f32_16x16x32_bf16 v[30:33], v[156:159], v[128:131], v[30:33]
	v_mfma_f32_16x16x32_bf16 v[34:37], v[144:147], v[132:135], v[34:37]
	v_mfma_f32_16x16x32_bf16 v[46:49], v[156:159], v[132:135], v[46:49]
	v_mfma_f32_16x16x32_bf16 v[50:53], v[144:147], v[140:143], v[50:53]
	v_mfma_f32_16x16x32_bf16 v[54:57], v[148:151], v[140:143], v[54:57]
	v_mfma_f32_16x16x32_bf16 v[58:61], v[152:155], v[140:143], v[58:61]
	v_mfma_f32_16x16x32_bf16 v[62:65], v[156:159], v[140:143], v[62:65]
	ds_read_b128 v[108:111], v0
	ds_read_b128 v[112:115], v0 offset:2048
	ds_read_b128 v[116:119], v0 offset:4096
	ds_read_b128 v[120:123], v0 offset:6144
	ds_read_b128 v[124:127], v83
	ds_read_b128 v[128:131], v83 offset:2048
	ds_read_b128 v[132:135], v83 offset:4096
	ds_read_b128 v[140:143], v83 offset:6144
	s_waitcnt lgkmcnt(8)
	s_nop 0
	s_waitcnt lgkmcnt(0)
	v_mfma_f32_16x16x32_bf16 v[26:29], v[98:101], v[70:73], v[26:29]
	s_waitcnt vmcnt(0)
	s_barrier
; DI unsigned pk2(float a, float b) { f32x2 v = {a, b}; bfv2 r = __builtin_convertvector(v, bfv2); return __builtin_bit_cast(unsigned, r); }
; DI float bf_lo(unsigned u) { return __uint_as_float(u << 16); }
; DI float bf_hi(unsigned u) { return __uint_as_float(u & 0xffff0000u); }
; DI void gemm_dma(f32x4 (&acc)[4][4], const bf16_t* Ap, int lda, const bf16_t* Bp, int ldb, int K, char* lds) {
;     ...
;     for (int mi = 0; mi < 4; ++mi)
; #pragma unroll
;       for (int ni = 0; ni < 4; ++ni) acc[mi][ni] = __builtin_amdgcn_mfma_f32_16x16x32_bf16(bfr[ni], af[mi], acc[mi][ni], 0, 0, 0);
;     asm volatile("s_waitcnt lgkmcnt(0)" : "+v"(ag[0]), "+v"(ag[1]), "+v"(ag[2]), "+v"(ag[3]), "+v"(bg[0]), "+v"(bg[1]), "+v"(bg[2]), "+v"(bg[3]) :: "memory");
; #pragma unroll
;     for (int mi = 0; mi < 4; ++mi)
; #pragma unroll
;       for (int ni = 0; ni < 4; ++ni) acc[mi][ni] = __builtin_amdgcn_mfma_f32_16x16x32_bf16(bg[ni], ag[mi], acc[mi][ni], 0, 0, 0);
; DI void phase_merge(const Params& p, int l, char* lds) {
;     ...
;     for (int mi = 0; mi < 4; ++mi) {
;       const int R = mt * 128 + wm * 64 + mi * 16 + l15;
; #pragma unroll
;       for (int ni = 0; ni < 4; ++ni) {
;         const int c = nt * 128 + wn * 64 + ni * 16 + quad * 4;
;         const u32x2 g1 = *(const u32x2*)(p.z + (size_t)R * NZ + C_MR + c);
;         const f32x4 v1 = a1[mi][ni];
;         pk[mi][ni][0] = pk2(bf_lo(g1[0]) * v1[0], bf_hi(g1[0]) * v1[1]);
;         pk[mi][ni][1] = pk2(bf_lo(g1[1]) * v1[2], bf_hi(g1[1]) * v1[3]);
	v_mfma_f32_16x16x32_bf16 v[38:41], v[94:97], v[74:77], v[38:41]
	v_mfma_f32_16x16x32_bf16 v[22:25], v[94:97], v[70:73], v[22:25]
	v_mfma_f32_16x16x32_bf16 v[42:45], v[98:101], v[74:77], v[42:45]
	v_mfma_f32_16x16x32_bf16 v[2:5], v[90:93], v[66:69], v[2:5]
	v_mfma_f32_16x16x32_bf16 v[6:9], v[94:97], v[66:69], v[6:9]
	v_mfma_f32_16x16x32_bf16 v[10:13], v[98:101], v[66:69], v[10:13]
	v_mfma_f32_16x16x32_bf16 v[14:17], v[102:105], v[66:69], v[14:17]
	v_mfma_f32_16x16x32_bf16 v[18:21], v[90:93], v[70:73], v[18:21]
	v_mfma_f32_16x16x32_bf16 v[30:33], v[102:105], v[70:73], v[30:33]
	v_mfma_f32_16x16x32_bf16 v[34:37], v[90:93], v[74:77], v[34:37]
	v_mfma_f32_16x16x32_bf16 v[46:49], v[102:105], v[74:77], v[46:49]
	v_mfma_f32_16x16x32_bf16 v[50:53], v[90:93], v[78:81], v[50:53]
	v_mfma_f32_16x16x32_bf16 v[54:57], v[94:97], v[78:81], v[54:57]
	v_mfma_f32_16x16x32_bf16 v[58:61], v[98:101], v[78:81], v[58:61]
	v_mfma_f32_16x16x32_bf16 v[62:65], v[102:105], v[78:81], v[62:65]
	ds_read_b128 v[66:69], v85
	ds_read_b128 v[70:73], v85 offset:2048
	ds_read_b128 v[74:77], v85 offset:4096
	ds_read_b128 v[78:81], v85 offset:6144
	ds_read_b128 v[90:93], v88
	ds_read_b128 v[94:97], v88 offset:2048
	ds_read_b128 v[98:101], v88 offset:4096
	ds_read_b128 v[102:105], v88 offset:6144
	v_lshl_add_u32 v88, s24, 7, v106
	v_ashrrev_i32_e32 v89, 31, v88
	v_mfma_f32_16x16x32_bf16 v[26:29], v[132:135], v[112:115], v[26:29]
	v_mfma_f32_16x16x32_bf16 v[38:41], v[128:131], v[116:119], v[38:41]
	v_mfma_f32_16x16x32_bf16 v[22:25], v[128:131], v[112:115], v[22:25]
	v_mfma_f32_16x16x32_bf16 v[42:45], v[132:135], v[116:119], v[42:45]
	v_mfma_f32_16x16x32_bf16 v[2:5], v[124:127], v[108:111], v[2:5]
	v_mfma_f32_16x16x32_bf16 v[6:9], v[128:131], v[108:111], v[6:9]
	v_mfma_f32_16x16x32_bf16 v[10:13], v[132:135], v[108:111], v[10:13]
	v_mfma_f32_16x16x32_bf16 v[14:17], v[140:143], v[108:111], v[14:17]
	v_mfma_f32_16x16x32_bf16 v[18:21], v[124:127], v[112:115], v[18:21]
	v_mfma_f32_16x16x32_bf16 v[30:33], v[140:143], v[112:115], v[30:33]
	v_mfma_f32_16x16x32_bf16 v[34:37], v[124:127], v[116:119], v[34:37]
	v_mfma_f32_16x16x32_bf16 v[46:49], v[140:143], v[116:119], v[46:49]
	v_mfma_f32_16x16x32_bf16 v[50:53], v[124:127], v[120:123], v[50:53]
	v_mfma_f32_16x16x32_bf16 v[54:57], v[128:131], v[120:123], v[54:57]
	v_mfma_f32_16x16x32_bf16 v[58:61], v[132:135], v[120:123], v[58:61]
	v_mfma_f32_16x16x32_bf16 v[62:65], v[140:143], v[120:123], v[62:65]
	ds_read_b128 v[82:85], v86
	ds_read_b128 v[108:111], v86 offset:2048
	ds_read_b128 v[112:115], v86 offset:4096
	ds_read_b128 v[116:119], v86 offset:6144
	ds_read_b128 v[120:123], v87
	ds_read_b128 v[124:127], v87 offset:2048
	ds_read_b128 v[128:131], v87 offset:4096
	ds_read_b128 v[132:135], v87 offset:6144
	s_waitcnt lgkmcnt(8)
	s_nop 0
	s_waitcnt lgkmcnt(0)
	v_mfma_f32_16x16x32_bf16 v[26:29], v[98:101], v[70:73], v[26:29]
	s_barrier
	v_mfma_f32_16x16x32_bf16 v[38:41], v[94:97], v[74:77], v[38:41]
	v_mfma_f32_16x16x32_bf16 v[22:25], v[94:97], v[70:73], v[22:25]
	v_mfma_f32_16x16x32_bf16 v[42:45], v[98:101], v[74:77], v[42:45]
	v_mfma_f32_16x16x32_bf16 v[10:13], v[98:101], v[66:69], v[10:13]
	v_mfma_f32_16x16x32_bf16 v[58:61], v[98:101], v[78:81], v[58:61]
	v_mfma_f32_16x16x32_bf16 v[98:101], v[128:131], v[108:111], v[26:29]
	v_mfma_f32_16x16x32_bf16 v[26:29], v[124:127], v[112:115], v[38:41]
	s_nop 2
	v_lshl_or_b32 v38, s22, 7, v107
	v_mov_b64_e32 v[40:41], s[10:11]
	v_ashrrev_i32_e32 v39, 31, v38
	v_mad_i64_i32 v[86:87], s[20:21], v88, s94, v[40:41]
	v_mfma_f32_16x16x32_bf16 v[6:9], v[94:97], v[66:69], v[6:9]
	v_mfma_f32_16x16x32_bf16 v[18:21], v[90:93], v[70:73], v[18:21]
	v_mfma_f32_16x16x32_bf16 v[30:33], v[102:105], v[70:73], v[30:33]
	v_lshlrev_b64 v[70:71], 1, v[38:39]
	v_mfma_f32_16x16x32_bf16 v[54:57], v[94:97], v[78:81], v[54:57]
	v_mfma_f32_16x16x32_bf16 v[94:97], v[124:127], v[108:111], v[22:25]
	v_mfma_f32_16x16x32_bf16 v[22:25], v[128:131], v[112:115], v[42:45]
	s_nop 2
	v_lshl_add_u64 v[42:43], v[86:87], 0, s[82:83]
	v_lshl_add_u64 v[44:45], v[42:43], 0, v[70:71]
	global_load_dwordx2 v[44:45], v[44:45], off
	v_mfma_f32_16x16x32_bf16 v[2:5], v[90:93], v[66:69], v[2:5]
	v_lshl_add_u64 v[86:87], v[86:87], 0, s[36:37]
	v_mfma_f32_16x16x32_bf16 v[46:49], v[102:105], v[74:77], v[46:49]
	v_mfma_f32_16x16x32_bf16 v[14:17], v[102:105], v[66:69], v[14:17]
	v_mfma_f32_16x16x32_bf16 v[66:69], v[120:123], v[82:85], v[2:5]
	v_mfma_f32_16x16x32_bf16 v[34:37], v[90:93], v[74:77], v[34:37]
	v_mfma_f32_16x16x32_bf16 v[50:53], v[90:93], v[78:81], v[50:53]
	v_mfma_f32_16x16x32_bf16 v[90:93], v[120:123], v[108:111], v[18:21]
	v_mfma_f32_16x16x32_bf16 v[18:21], v[132:135], v[112:115], v[46:49]
	v_mfma_f32_16x16x32_bf16 v[74:77], v[124:127], v[82:85], v[6:9]
	s_waitcnt vmcnt(0)
	s_nop 0
	v_lshlrev_b32_e32 v46, 16, v44
	v_and_b32_e32 v47, 0xffff0000, v44
	v_lshlrev_b32_e32 v44, 16, v45
	v_and_b32_e32 v45, 0xffff0000, v45
	v_pk_mul_f32 v[44:45], v[68:69], v[44:45]
	v_pk_mul_f32 v[46:47], v[66:67], v[46:47]
	v_cvt_pk_bf16_f32 v141, v44, v45
	v_or_b32_e32 v44, 16, v38
	v_ashrrev_i32_e32 v45, 31, v44
	v_lshlrev_b64 v[72:73], 1, v[44:45]
	v_lshl_add_u64 v[44:45], v[42:43], 0, v[72:73]
	global_load_dwordx2 v[44:45], v[44:45], off
	v_cvt_pk_bf16_f32 v142, v46, v47
	v_mfma_f32_16x16x32_bf16 v[62:65], v[102:105], v[78:81], v[62:65]
	s_waitcnt vmcnt(0)
; DI unsigned pk2(float a, float b) { f32x2 v = {a, b}; bfv2 r = __builtin_convertvector(v, bfv2); return __builtin_bit_cast(unsigned, r); }
; DI float bf_lo(unsigned u) { return __uint_as_float(u << 16); }
; DI float bf_hi(unsigned u) { return __uint_as_float(u & 0xffff0000u); }
; DI void phase_merge(const Params& p, int l, char* lds) {
;     ...
;     for (int mi = 0; mi < 4; ++mi) {
;       const int R = mt * 128 + wm * 64 + mi * 16 + l15;
; #pragma unroll
;       for (int ni = 0; ni < 4; ++ni) {
;         const int c = nt * 128 + wn * 64 + ni * 16 + quad * 4;
;         const u32x2 g1 = *(const u32x2*)(p.z + (size_t)R * NZ + C_MR + c);
;         const f32x4 v1 = a1[mi][ni];
;         pk[mi][ni][0] = pk2(bf_lo(g1[0]) * v1[0], bf_hi(g1[0]) * v1[1]);
;         pk[mi][ni][1] = pk2(bf_lo(g1[1]) * v1[2], bf_hi(g1[1]) * v1[3]);
;       }
;     }
	v_lshlrev_b32_e32 v46, 16, v44
	v_and_b32_e32 v47, 0xffff0000, v44
	v_lshlrev_b32_e32 v44, 16, v45
	v_and_b32_e32 v45, 0xffff0000, v45
	v_pk_mul_f32 v[44:45], v[76:77], v[44:45]
	v_mfma_f32_16x16x32_bf16 v[78:81], v[128:131], v[82:85], v[10:13]
	v_cvt_pk_bf16_f32 v139, v44, v45
	v_or_b32_e32 v44, 32, v38
	v_or_b32_e32 v38, 48, v38
	v_ashrrev_i32_e32 v45, 31, v44
	v_ashrrev_i32_e32 v39, 31, v38
	v_lshlrev_b64 v[68:69], 1, v[44:45]
	v_lshlrev_b64 v[66:67], 1, v[38:39]
	v_lshl_add_u64 v[44:45], v[42:43], 0, v[68:69]
	v_lshl_add_u64 v[38:39], v[42:43], 0, v[66:67]
	global_load_dwordx2 v[44:45], v[44:45], off
	v_mfma_f32_16x16x32_bf16 v[82:85], v[132:135], v[82:85], v[14:17]
	global_load_dwordx2 v[38:39], v[38:39], off
	v_pk_mul_f32 v[46:47], v[74:75], v[46:47]
	v_or_b32_e32 v76, 48, v88
	v_mfma_f32_16x16x32_bf16 v[30:33], v[132:135], v[108:111], v[30:33]
	v_cvt_pk_bf16_f32 v140, v46, v47
	v_mad_i64_i32 v[74:75], s[20:21], v76, s94, v[40:41]
	v_mfma_f32_16x16x32_bf16 v[2:5], v[132:135], v[116:119], v[62:65]
	v_ashrrev_i32_e32 v77, 31, v76
	s_waitcnt vmcnt(0)
	v_lshlrev_b32_e32 v46, 16, v44
	v_and_b32_e32 v47, 0xffff0000, v44
	v_lshlrev_b32_e32 v42, 16, v38
	v_and_b32_e32 v43, 0xffff0000, v38
	v_lshlrev_b32_e32 v38, 16, v39
	v_and_b32_e32 v39, 0xffff0000, v39
	v_pk_mul_f32 v[38:39], v[84:85], v[38:39]
	v_or_b32_e32 v84, 16, v88
	v_pk_mul_f32 v[42:43], v[82:83], v[42:43]
	v_mad_i64_i32 v[82:83], s[20:21], v84, s94, v[40:41]
	v_cvt_pk_bf16_f32 v132, v38, v39
	v_lshl_add_u64 v[38:39], v[82:83], 0, s[82:83]
	v_cvt_pk_bf16_f32 v133, v42, v43
	v_lshl_add_u64 v[42:43], v[38:39], 0, v[70:71]
	global_load_dwordx2 v[42:43], v[42:43], off
	v_lshlrev_b32_e32 v44, 16, v45
	v_and_b32_e32 v45, 0xffff0000, v45
	v_pk_mul_f32 v[44:45], v[80:81], v[44:45]
	v_mfma_f32_16x16x32_bf16 v[6:9], v[128:131], v[116:119], v[58:61]
	v_cvt_pk_bf16_f32 v134, v44, v45
	v_or_b32_e32 v80, 32, v88
	v_pk_mul_f32 v[46:47], v[78:79], v[46:47]
	v_mfma_f32_16x16x32_bf16 v[10:13], v[124:127], v[116:119], v[54:57]
	v_mad_i64_i32 v[78:79], s[20:21], v80, s94, v[40:41]
	v_lshl_add_u64 v[186:187], v[78:79], 0, s[82:83]
	v_lshl_add_u64 v[188:189], v[74:75], 0, s[82:83]
	v_lshl_add_u64 v[184:185], v[38:39], 0, v[72:73]
	global_load_dwordx2 v[162:163], v[184:185], off
	v_lshl_add_u64 v[190:191], v[38:39], 0, v[68:69]
	global_load_dwordx2 v[164:165], v[190:191], off
	v_lshl_add_u64 v[184:185], v[38:39], 0, v[66:67]
	global_load_dwordx2 v[166:167], v[184:185], off
	v_lshl_add_u64 v[190:191], v[186:187], 0, v[70:71]
	global_load_dwordx2 v[168:169], v[190:191], off
	v_lshl_add_u64 v[184:185], v[186:187], 0, v[72:73]
	global_load_dwordx2 v[170:171], v[184:185], off
	v_lshl_add_u64 v[190:191], v[186:187], 0, v[68:69]
	global_load_dwordx2 v[172:173], v[190:191], off
	v_lshl_add_u64 v[184:185], v[186:187], 0, v[66:67]
	global_load_dwordx2 v[174:175], v[184:185], off
	v_lshl_add_u64 v[190:191], v[188:189], 0, v[70:71]
	global_load_dwordx2 v[176:177], v[190:191], off
	v_lshl_add_u64 v[184:185], v[188:189], 0, v[72:73]
	global_load_dwordx2 v[178:179], v[184:185], off
	v_lshl_add_u64 v[190:191], v[188:189], 0, v[68:69]
	global_load_dwordx2 v[180:181], v[190:191], off
	v_lshl_add_u64 v[184:185], v[188:189], 0, v[66:67]
	global_load_dwordx2 v[182:183], v[184:185], off
	v_cvt_pk_bf16_f32 v135, v46, v47
	v_mfma_f32_16x16x32_bf16 v[34:37], v[120:123], v[112:115], v[34:37]
	v_lshlrev_b64 v[88:89], 11, v[88:89]
	v_ashrrev_i32_e32 v85, 31, v84
	v_ashrrev_i32_e32 v81, 31, v80
	v_mfma_f32_16x16x32_bf16 v[14:17], v[120:123], v[116:119], v[50:53]
	s_waitcnt vmcnt(11)
	v_lshlrev_b32_e32 v44, 16, v42
	v_and_b32_e32 v45, 0xffff0000, v42
	v_lshlrev_b32_e32 v42, 16, v43
	v_and_b32_e32 v43, 0xffff0000, v43
	v_pk_mul_f32 v[42:43], v[92:93], v[42:43]
	v_pk_mul_f32 v[44:45], v[90:91], v[44:45]
	v_cvt_pk_bf16_f32 v130, v42, v43
	v_cvt_pk_bf16_f32 v131, v44, v45
	s_waitcnt vmcnt(10)
	v_mov_b32_e32 v42, v162
	v_mov_b32_e32 v43, v163
	v_lshlrev_b32_e32 v44, 16, v42
	v_and_b32_e32 v45, 0xffff0000, v42
	v_lshlrev_b32_e32 v42, 16, v43
	v_and_b32_e32 v43, 0xffff0000, v43
	v_pk_mul_f32 v[42:43], v[96:97], v[42:43]
	v_pk_mul_f32 v[44:45], v[94:95], v[44:45]
	v_cvt_pk_bf16_f32 v128, v42, v43
	v_cvt_pk_bf16_f32 v129, v44, v45
	s_waitcnt vmcnt(8)
	v_mov_b32_e32 v42, v164
	v_mov_b32_e32 v43, v165
	v_mov_b32_e32 v38, v166
	v_mov_b32_e32 v39, v167
	v_lshlrev_b32_e32 v44, 16, v42
	v_and_b32_e32 v45, 0xffff0000, v42
	v_lshlrev_b32_e32 v42, 16, v43
	v_and_b32_e32 v43, 0xffff0000, v43
	v_pk_mul_f32 v[42:43], v[100:101], v[42:43]
	v_pk_mul_f32 v[44:45], v[98:99], v[44:45]
	v_cvt_pk_bf16_f32 v126, v42, v43
	v_lshlrev_b32_e32 v42, 16, v38
	v_and_b32_e32 v43, 0xffff0000, v38
	v_pk_mul_f32 v[30:31], v[30:31], v[42:43]
	v_cvt_pk_bf16_f32 v127, v44, v45
	v_cvt_pk_bf16_f32 v125, v30, v31
	v_lshlrev_b32_e32 v30, 16, v39
	v_and_b32_e32 v31, 0xffff0000, v39
	v_pk_mul_f32 v[30:31], v[32:33], v[30:31]
	s_nop 0
	v_cvt_pk_bf16_f32 v124, v30, v31
	v_lshl_add_u64 v[30:31], v[78:79], 0, s[82:83]
	s_waitcnt vmcnt(7)
	v_mov_b32_e32 v32, v168
	v_mov_b32_e32 v33, v169
	v_lshlrev_b32_e32 v38, 16, v32
	v_and_b32_e32 v39, 0xffff0000, v32
	v_lshlrev_b32_e32 v32, 16, v33
	v_and_b32_e32 v33, 0xffff0000, v33
	v_pk_mul_f32 v[32:33], v[36:37], v[32:33]
	v_pk_mul_f32 v[34:35], v[34:35], v[38:39]
	v_cvt_pk_bf16_f32 v122, v32, v33
	v_cvt_pk_bf16_f32 v123, v34, v35
	s_waitcnt vmcnt(6)
	v_mov_b32_e32 v32, v170
	v_mov_b32_e32 v33, v171
	v_lshlrev_b32_e32 v34, 16, v32
	v_and_b32_e32 v35, 0xffff0000, v32
	v_pk_mul_f32 v[26:27], v[26:27], v[34:35]
	s_nop 0
	v_cvt_pk_bf16_f32 v121, v26, v27
	v_lshlrev_b32_e32 v26, 16, v33
	v_and_b32_e32 v27, 0xffff0000, v33
	v_pk_mul_f32 v[26:27], v[28:29], v[26:27]
	s_nop 0
	v_cvt_pk_bf16_f32 v120, v26, v27
	s_waitcnt vmcnt(5)
; DI void gemm_dma(f32x4 (&acc)[4][4], const bf16_t* Ap, int lda, const bf16_t* Bp, int ldb, int K, char* lds) {
;     ...
;   const int lrow = lane >> 3, lpc = lane & 7;
;   const bf16_t* ga[4]; const bf16_t* gb[4];
; #pragma unroll
;   for (int i = 0; i < 4; ++i) {
;     const int row = (wave * 4 + i) * 8 + lrow; const int q = lpc ^ (row & 7);
;     ga[i] = Ap + (size_t)row * lda + q * 8; gb[i] = Bp + (size_t)row * ldb + q * 8;
;   }
;   auto issue = [&](int kt) {
;     char* sb = lds + (kt & 1) * 32768 + wave * 4096;
; #pragma unroll
;     for (int i = 0; i < 4; ++i) {
;       __builtin_amdgcn_global_load_lds((const unsigned*)(ga[i] + kt * 64), (LASP unsigned*)(sb + i * 1024), 16, 0, 0);
;       __builtin_amdgcn_global_load_lds((const unsigned*)(gb[i] + kt * 64), (LASP unsigned*)(sb + 16384 + i * 1024), 16, 0, 0);
;     }
;   };
;   const int sw = l15 & 7;
;   const unsigned lbase = (unsigned)(size_t)(LASP char*)lds;
;   const unsigned a0 = (unsigned)((wm * 64 + l15) * 128 + ((quad ^ sw) * 16)), a1 = (unsigned)((wm * 64 + l15) * 128 + (((4 + quad) ^ sw) * 16));
;   const unsigned b0 = 16384u + (unsigned)((wn * 64 + l15) * 128 + ((quad ^ sw) * 16)), b1 = 16384u + (unsigned)((wn * 64 + l15) * 128 + (((4 + quad) ^ sw) * 16));
;   asm volatile("s_waitcnt vmcnt(0)" ::: "memory");
;   __builtin_amdgcn_s_barrier();
;   asm volatile("" ::: "memory");
;   issue(0);
;   for (int kt = 0; kt < nk; ++kt) {
;     asm volatile("s_waitcnt vmcnt(0)" ::: "memory");
;     __builtin_amdgcn_s_barrier();
;     asm volatile("" ::: "memory");
;     if (kt + 1 < nk) issue(kt + 1);
;     const unsigned sa = lbase + (unsigned)((kt & 1) * 32768);
;     bf16x8 af[4], bfr[4], ag[4], bg[4];
;     asm volatile("ds_read_b128 %0, %8\n\tds_read_b128 %1, %8 offset:2048\n\tds_read_b128 %2, %8 offset:4096\n\tds_read_b128 %3, %8 offset:6144\n\t"
; DI void phase_merge(const Params& p, int l, char* lds) {
;     ...
;     for (int mi = 0; mi < 4; ++mi) {
;       const int R = mt * 128 + wm * 64 + mi * 16 + l15;
; #pragma unroll
;       for (int ni = 0; ni < 4; ++ni) {
;         const int c = nt * 128 + wn * 64 + ni * 16 + quad * 4;
;         const u32x2 g1 = *(const u32x2*)(p.z + (size_t)R * NZ + C_MR + c);
;         const f32x4 v1 = a1[mi][ni];
;         pk[mi][ni][0] = pk2(bf_lo(g1[0]) * v1[0], bf_hi(g1[0]) * v1[1]);
;         pk[mi][ni][1] = pk2(bf_lo(g1[1]) * v1[2], bf_hi(g1[1]) * v1[3]);
;       }
;     }
	v_mov_b32_e32 v26, v172
	v_mov_b32_e32 v27, v173
	v_lshlrev_b32_e32 v28, 16, v26
	v_and_b32_e32 v29, 0xffff0000, v26
	v_pk_mul_f32 v[22:23], v[22:23], v[28:29]
	s_nop 0
	v_cvt_pk_bf16_f32 v119, v22, v23
	v_lshlrev_b32_e32 v22, 16, v27
	v_and_b32_e32 v23, 0xffff0000, v27
	v_pk_mul_f32 v[22:23], v[24:25], v[22:23]
	s_nop 0
	v_cvt_pk_bf16_f32 v118, v22, v23
	s_waitcnt vmcnt(4)
	v_mov_b32_e32 v22, v174
	v_mov_b32_e32 v23, v175
	v_lshlrev_b32_e32 v24, 16, v22
	v_and_b32_e32 v25, 0xffff0000, v22
	v_pk_mul_f32 v[18:19], v[18:19], v[24:25]
	s_nop 0
	v_cvt_pk_bf16_f32 v117, v18, v19
	v_lshlrev_b32_e32 v18, 16, v23
	v_and_b32_e32 v19, 0xffff0000, v23
	v_pk_mul_f32 v[18:19], v[20:21], v[18:19]
	s_nop 0
	v_cvt_pk_bf16_f32 v116, v18, v19
	v_lshl_add_u64 v[18:19], v[74:75], 0, s[82:83]
	s_waitcnt vmcnt(3)
	v_mov_b32_e32 v20, v176
	v_mov_b32_e32 v21, v177
	v_lshlrev_b32_e32 v22, 16, v20
	v_and_b32_e32 v23, 0xffff0000, v20
	v_pk_mul_f32 v[14:15], v[14:15], v[22:23]
	s_nop 0
	v_cvt_pk_bf16_f32 v115, v14, v15
	v_lshlrev_b32_e32 v14, 16, v21
	v_and_b32_e32 v15, 0xffff0000, v21
	v_pk_mul_f32 v[14:15], v[16:17], v[14:15]
	s_nop 0
	v_cvt_pk_bf16_f32 v114, v14, v15
	s_waitcnt vmcnt(2)
	v_mov_b32_e32 v14, v178
	v_mov_b32_e32 v15, v179
	v_lshlrev_b32_e32 v16, 16, v14
	v_and_b32_e32 v17, 0xffff0000, v14
	v_pk_mul_f32 v[10:11], v[10:11], v[16:17]
	s_nop 0
	v_cvt_pk_bf16_f32 v113, v10, v11
	v_lshlrev_b32_e32 v10, 16, v15
	v_and_b32_e32 v11, 0xffff0000, v15
	v_pk_mul_f32 v[10:11], v[12:13], v[10:11]
	s_nop 0
	v_cvt_pk_bf16_f32 v112, v10, v11
	s_waitcnt vmcnt(1)
	v_mov_b32_e32 v10, v180
	v_mov_b32_e32 v11, v181
	v_lshlrev_b32_e32 v12, 16, v10
	v_and_b32_e32 v13, 0xffff0000, v10
	v_pk_mul_f32 v[6:7], v[6:7], v[12:13]
	v_mov_b32_e32 v10, v212
	v_cvt_pk_bf16_f32 v111, v6, v7
	v_lshlrev_b32_e32 v6, 16, v11
	v_and_b32_e32 v7, 0xffff0000, v11
	v_pk_mul_f32 v[6:7], v[8:9], v[6:7]
	s_nop 0
	v_cvt_pk_bf16_f32 v110, v6, v7
	s_waitcnt vmcnt(0)
	v_mov_b32_e32 v6, v182
	v_mov_b32_e32 v7, v183
	s_barrier
	v_readfirstlane_b32 s21, v10
	s_ashr_i32 s20, s21, 6
	v_bfe_u32 v0, v10, 3, 3
	s_lshl_b32 s25, s20, 12
	s_add_i32 s27, s25, 0x4000
	s_mov_b32 m0, s25
	s_or_b32 s41, s25, 0x400
	s_add_i32 s40, s25, 0x4400
	s_or_b32 s31, s25, 0x800
	s_add_i32 s30, s25, 0x4800
	s_or_b32 s26, s25, 0xc00
	v_bfe_u32 v11, v10, 4, 2
	v_and_b32_e32 v12, 7, v10
	s_add_i32 s24, s25, 0x4c00
	s_add_i32 s22, s25, 0x8c00
	s_add_i32 s23, s25, 0xcc00
	s_waitcnt vmcnt(0)
	v_lshlrev_b32_e32 v8, 16, v6
	v_and_b32_e32 v9, 0xffff0000, v6
	v_pk_mul_f32 v[2:3], v[2:3], v[8:9]
	s_nop 0
	v_cvt_pk_bf16_f32 v109, v2, v3
	v_lshlrev_b32_e32 v2, 16, v7
	v_and_b32_e32 v3, 0xffff0000, v7
	v_pk_mul_f32 v[2:3], v[4:5], v[2:3]
	s_nop 0
	v_cvt_pk_bf16_f32 v108, v2, v3
	v_lshl_or_b32 v2, s20, 5, v0
	v_bitop3_b32 v0, v0, v10, 7 bitop3:0x78
	v_lshlrev_b32_e32 v0, 4, v0
	v_ashrrev_i32_e32 v3, 31, v2
	v_lshl_add_u64 v[4:5], s[0:1], 0, v[0:1]
	v_lshl_add_u64 v[6:7], s[2:3], 0, v[0:1]
	v_lshlrev_b64 v[8:9], 10, v[2:3]
	v_lshl_add_u64 v[104:105], v[4:5], 0, v[8:9]
	v_lshl_add_u64 v[98:99], v[6:7], 0, v[8:9]
	v_or_b32_e32 v8, 8, v2
	v_ashrrev_i32_e32 v9, 31, v8
	v_lshlrev_b64 v[8:9], 10, v[8:9]
	v_lshl_add_u64 v[102:103], v[4:5], 0, v[8:9]
	v_lshl_add_u64 v[94:95], v[6:7], 0, v[8:9]
	v_or_b32_e32 v8, 16, v2
	global_load_lds_dwordx4 v[104:105], off
	s_mov_b32 m0, s27
	v_ashrrev_i32_e32 v9, 31, v8
	v_or_b32_e32 v2, 24, v2
	global_load_lds_dwordx4 v[98:99], off
	s_mov_b32 m0, s41
	v_lshlrev_b64 v[8:9], 10, v[8:9]
	v_ashrrev_i32_e32 v3, 31, v2
	global_load_lds_dwordx4 v[102:103], off
	s_mov_b32 m0, s40
	v_lshl_add_u64 v[100:101], v[4:5], 0, v[8:9]
	v_lshlrev_b64 v[2:3], 10, v[2:3]
	s_lshr_b32 s0, s21, 1
	global_load_lds_dwordx4 v[94:95], off
	s_mov_b32 m0, s31
	v_lshl_add_u64 v[92:93], v[6:7], 0, v[8:9]
	v_lshl_add_u64 v[96:97], v[4:5], 0, v[2:3]
	v_lshl_add_u64 v[90:91], v[6:7], 0, v[2:3]
	v_and_b32_e32 v2, 15, v10
	s_and_b32 s0, s0, 0x1ffffc0
	global_load_lds_dwordx4 v[100:101], off
	s_mov_b32 m0, s30
	v_or_b32_e32 v0, s0, v2
	global_load_lds_dwordx4 v[92:93], off
	s_mov_b32 m0, s26
	v_lshlrev_b32_e32 v3, 7, v0
	v_bitop3_b32 v0, v11, v10, 7 bitop3:0x78
	v_bitop3_b32 v5, v11, v12, 4 bitop3:0x36
	v_and_or_b32 v2, s21, 64, v2
	global_load_lds_dwordx4 v[96:97], off
	s_mov_b32 m0, s24
	v_lshlrev_b32_e32 v4, 4, v0
	v_lshlrev_b32_e32 v5, 4, v5
	v_lshlrev_b32_e32 v2, 7, v2
	global_load_lds_dwordx4 v[90:91], off
	s_add_i32 s1, s25, 0x8000
	v_or_b32_e32 v0, v3, v4
	v_or_b32_e32 v143, v3, v5
	v_or_b32_e32 v147, v2, v4
	v_or_b32_e32 v149, v2, v5
	s_waitcnt vmcnt(0)
	s_barrier
	s_add_i32 s0, s25, 0xc000
	v_lshl_add_u64 v[2:3], v[104:105], 0, s[28:29]
	s_mov_b32 m0, s1
	s_add_i32 s2, s25, 0x8400
	global_load_lds_dwordx4 v[2:3], off
	v_lshl_add_u64 v[2:3], v[98:99], 0, s[28:29]
	s_mov_b32 m0, s0
	s_add_i32 s3, s25, 0xc400
	global_load_lds_dwordx4 v[2:3], off
	v_lshl_add_u64 v[2:3], v[102:103], 0, s[28:29]
	s_mov_b32 m0, s2
	s_add_i32 s20, s25, 0x8800
	global_load_lds_dwordx4 v[2:3], off
	v_lshl_add_u64 v[2:3], v[94:95], 0, s[28:29]
	s_mov_b32 m0, s3
	s_add_i32 s21, s25, 0xc800
	global_load_lds_dwordx4 v[2:3], off
	v_lshl_add_u64 v[2:3], v[100:101], 0, s[28:29]
	s_mov_b32 m0, s20
	v_or_b32_e32 v144, 0x4000, v147
	global_load_lds_dwordx4 v[2:3], off
	v_lshl_add_u64 v[2:3], v[92:93], 0, s[28:29]
	s_mov_b32 m0, s21
	v_or_b32_e32 v145, 0x4000, v149
	global_load_lds_dwordx4 v[2:3], off
	v_lshl_add_u64 v[2:3], v[96:97], 0, s[28:29]
	s_mov_b32 m0, s22
	v_add_u32_e32 v146, 0x8000, v0
	global_load_lds_dwordx4 v[2:3], off
	v_lshl_add_u64 v[2:3], v[90:91], 0, s[28:29]
	s_mov_b32 m0, s23
	v_or_b32_e32 v147, 0xc000, v147
	global_load_lds_dwordx4 v[2:3], off
	ds_read_b128 v[2:5], v0
	ds_read_b128 v[6:9], v0 offset:2048
	ds_read_b128 v[10:13], v0 offset:4096
	ds_read_b128 v[14:17], v0 offset:6144
	ds_read_b128 v[18:21], v144
	ds_read_b128 v[22:25], v144 offset:2048
	ds_read_b128 v[26:29], v144 offset:4096
	ds_read_b128 v[30:33], v144 offset:6144
	s_mov_b32 m0, s25
	ds_read_b128 v[34:37], v143
	ds_read_b128 v[38:41], v143 offset:2048
	ds_read_b128 v[46:49], v143 offset:4096
	ds_read_b128 v[62:65], v143 offset:6144
	ds_read_b128 v[50:53], v145
	ds_read_b128 v[54:57], v145 offset:2048
	ds_read_b128 v[58:61], v145 offset:4096
	ds_read_b128 v[150:153], v145 offset:6144
	s_waitcnt lgkmcnt(8)
	v_add_u32_e32 v148, 0x8000, v143
	v_mfma_f32_16x16x32_bf16 v[42:45], v[18:21], v[2:5], 0
	s_waitcnt lgkmcnt(0)
	s_waitcnt vmcnt(0)
	s_barrier
; DI void gemm_dma(f32x4 (&acc)[4][4], const bf16_t* Ap, int lda, const bf16_t* Bp, int ldb, int K, char* lds) {
;     ...
;   for (int kt = 0; kt < nk; ++kt) {
;     asm volatile("s_waitcnt vmcnt(0)" ::: "memory");
;     __builtin_amdgcn_s_barrier();
;     asm volatile("" ::: "memory");
;     if (kt + 1 < nk) issue(kt + 1);
;     const unsigned sa = lbase + (unsigned)((kt & 1) * 32768);
;     bf16x8 af[4], bfr[4], ag[4], bg[4];
;     asm volatile("ds_read_b128 %0, %8\n\tds_read_b128 %1, %8 offset:2048\n\tds_read_b128 %2, %8 offset:4096\n\tds_read_b128 %3, %8 offset:6144\n\t"
;                  "ds_read_b128 %4, %9\n\tds_read_b128 %5, %9 offset:2048\n\tds_read_b128 %6, %9 offset:4096\n\tds_read_b128 %7, %9 offset:6144"
;                  : "=&v"(af[0]), "=&v"(af[1]), "=&v"(af[2]), "=&v"(af[3]), "=&v"(bfr[0]), "=&v"(bfr[1]), "=&v"(bfr[2]), "=&v"(bfr[3])
;                  : "v"(sa + a0), "v"(sa + b0) : "memory");
;     asm volatile("ds_read_b128 %0, %16\n\tds_read_b128 %1, %16 offset:2048\n\tds_read_b128 %2, %16 offset:4096\n\tds_read_b128 %3, %16 offset:6144\n\t"
;                  "ds_read_b128 %4, %17\n\tds_read_b128 %5, %17 offset:2048\n\tds_read_b128 %6, %17 offset:4096\n\tds_read_b128 %7, %17 offset:6144\n\t"
;                  "s_waitcnt lgkmcnt(8)"
;                  : "=&v"(ag[0]), "=&v"(ag[1]), "=&v"(ag[2]), "=&v"(ag[3]), "=&v"(bg[0]), "=&v"(bg[1]), "=&v"(bg[2]), "=&v"(bg[3]),
;                    "+v"(af[0]), "+v"(af[1]), "+v"(af[2]), "+v"(af[3]), "+v"(bfr[0]), "+v"(bfr[1]), "+v"(bfr[2]), "+v"(bfr[3])
;                  : "v"(sa + a1), "v"(sa + b1) : "memory");
; #pragma unroll
;     for (int mi = 0; mi < 4; ++mi)
; #pragma unroll
;       for (int ni = 0; ni < 4; ++ni) acc[mi][ni] = __builtin_amdgcn_mfma_f32_16x16x32_bf16(bfr[ni], af[mi], acc[mi][ni], 0, 0, 0);
;     asm volatile("s_waitcnt lgkmcnt(0)" : "+v"(ag[0]), "+v"(ag[1]), "+v"(ag[2]), "+v"(ag[3]), "+v"(bg[0]), "+v"(bg[1]), "+v"(bg[2]), "+v"(bg[3]) :: "memory");
; #pragma unroll
;     for (int mi = 0; mi < 4; ++mi)
; #pragma unroll
;       for (int ni = 0; ni < 4; ++ni) acc[mi][ni] = __builtin_amdgcn_mfma_f32_16x16x32_bf16(bg[ni], ag[mi], acc[mi][ni], 0, 0, 0);
;   }
	v_mfma_f32_16x16x32_bf16 v[154:157], v[22:25], v[2:5], 0
	v_or_b32_e32 v149, 0xc000, v149
	v_mfma_f32_16x16x32_bf16 v[162:165], v[26:29], v[2:5], 0
	v_mfma_f32_16x16x32_bf16 v[166:169], v[30:33], v[2:5], 0
	v_mfma_f32_16x16x32_bf16 v[170:173], v[18:21], v[6:9], 0
	v_mfma_f32_16x16x32_bf16 v[174:177], v[22:25], v[6:9], 0
	v_mfma_f32_16x16x32_bf16 v[178:181], v[26:29], v[6:9], 0
	v_mfma_f32_16x16x32_bf16 v[182:185], v[30:33], v[6:9], 0
	v_mfma_f32_16x16x32_bf16 v[186:189], v[18:21], v[10:13], 0
	v_mfma_f32_16x16x32_bf16 v[190:193], v[22:25], v[10:13], 0
	v_mfma_f32_16x16x32_bf16 v[194:197], v[26:29], v[10:13], 0
	v_mfma_f32_16x16x32_bf16 v[198:201], v[30:33], v[10:13], 0
	v_mfma_f32_16x16x32_bf16 v[202:205], v[18:21], v[14:17], 0
	v_mfma_f32_16x16x32_bf16 v[206:209], v[22:25], v[14:17], 0
	v_mfma_f32_16x16x32_bf16 v[232:235], v[26:29], v[14:17], 0
	v_mfma_f32_16x16x32_bf16 v[236:239], v[30:33], v[14:17], 0
	v_mfma_f32_16x16x32_bf16 v[2:5], v[50:53], v[34:37], v[42:45]
	v_mfma_f32_16x16x32_bf16 v[6:9], v[54:57], v[34:37], v[154:157]
	v_mfma_f32_16x16x32_bf16 v[10:13], v[58:61], v[34:37], v[162:165]
	v_mfma_f32_16x16x32_bf16 v[14:17], v[150:153], v[34:37], v[166:169]
	v_mfma_f32_16x16x32_bf16 v[18:21], v[50:53], v[38:41], v[170:173]
	v_mfma_f32_16x16x32_bf16 v[22:25], v[54:57], v[38:41], v[174:177]
	v_mfma_f32_16x16x32_bf16 v[26:29], v[58:61], v[38:41], v[178:181]
	v_mfma_f32_16x16x32_bf16 v[30:33], v[150:153], v[38:41], v[182:185]
	v_mfma_f32_16x16x32_bf16 v[34:37], v[50:53], v[46:49], v[186:189]
	v_mfma_f32_16x16x32_bf16 v[38:41], v[54:57], v[46:49], v[190:193]
	v_mfma_f32_16x16x32_bf16 v[42:45], v[58:61], v[46:49], v[194:197]
	v_mfma_f32_16x16x32_bf16 v[46:49], v[150:153], v[46:49], v[198:201]
	v_mfma_f32_16x16x32_bf16 v[50:53], v[50:53], v[62:65], v[202:205]
	v_mfma_f32_16x16x32_bf16 v[54:57], v[54:57], v[62:65], v[206:209]
	v_mfma_f32_16x16x32_bf16 v[58:61], v[58:61], v[62:65], v[232:235]
	v_mfma_f32_16x16x32_bf16 v[62:65], v[150:153], v[62:65], v[236:239]
	v_lshl_add_u64 v[150:151], v[104:105], 0, s[70:71]
	global_load_lds_dwordx4 v[150:151], off
	v_lshl_add_u64 v[150:151], v[98:99], 0, s[70:71]
	s_mov_b32 m0, s27
	s_nop 0
	global_load_lds_dwordx4 v[150:151], off
	v_lshl_add_u64 v[150:151], v[102:103], 0, s[70:71]
	s_mov_b32 m0, s41
	s_nop 0
	global_load_lds_dwordx4 v[150:151], off
	v_lshl_add_u64 v[150:151], v[94:95], 0, s[70:71]
	s_mov_b32 m0, s40
	s_nop 0
	global_load_lds_dwordx4 v[150:151], off
	v_lshl_add_u64 v[150:151], v[100:101], 0, s[70:71]
	s_mov_b32 m0, s31
	s_nop 0
	global_load_lds_dwordx4 v[150:151], off
	v_lshl_add_u64 v[150:151], v[92:93], 0, s[70:71]
	s_mov_b32 m0, s30
	s_nop 0
	global_load_lds_dwordx4 v[150:151], off
	v_lshl_add_u64 v[150:151], v[96:97], 0, s[70:71]
	s_mov_b32 m0, s26
	s_nop 0
	global_load_lds_dwordx4 v[150:151], off
	v_lshl_add_u64 v[150:151], v[90:91], 0, s[70:71]
	s_mov_b32 m0, s24
	s_nop 0
	global_load_lds_dwordx4 v[150:151], off
	ds_read_b128 v[150:153], v146
	ds_read_b128 v[154:157], v146 offset:2048
	ds_read_b128 v[162:165], v146 offset:4096
	ds_read_b128 v[166:169], v146 offset:6144
	ds_read_b128 v[170:173], v147
	ds_read_b128 v[174:177], v147 offset:2048
	ds_read_b128 v[178:181], v147 offset:4096
	ds_read_b128 v[182:185], v147 offset:6144
	s_mov_b32 m0, s1
	ds_read_b128 v[186:189], v148
	ds_read_b128 v[190:193], v148 offset:2048
	ds_read_b128 v[194:197], v148 offset:4096
	ds_read_b128 v[198:201], v148 offset:6144
	ds_read_b128 v[202:205], v149
	ds_read_b128 v[206:209], v149 offset:2048
	ds_read_b128 v[232:235], v149 offset:4096
	ds_read_b128 v[236:239], v149 offset:6144
	s_waitcnt lgkmcnt(8)
	s_nop 0
	s_waitcnt lgkmcnt(0)
	v_mfma_f32_16x16x32_bf16 v[2:5], v[170:173], v[150:153], v[2:5]
	s_waitcnt vmcnt(0)
	s_barrier
	v_mfma_f32_16x16x32_bf16 v[6:9], v[174:177], v[150:153], v[6:9]
	v_mfma_f32_16x16x32_bf16 v[10:13], v[178:181], v[150:153], v[10:13]
	v_mfma_f32_16x16x32_bf16 v[14:17], v[182:185], v[150:153], v[14:17]
	v_lshl_add_u64 v[150:151], v[104:105], 0, s[72:73]
	global_load_lds_dwordx4 v[150:151], off
	v_lshl_add_u64 v[150:151], v[98:99], 0, s[72:73]
	s_mov_b32 m0, s0
	v_mfma_f32_16x16x32_bf16 v[18:21], v[170:173], v[154:157], v[18:21]
	global_load_lds_dwordx4 v[150:151], off
	v_lshl_add_u64 v[150:151], v[102:103], 0, s[72:73]
	s_mov_b32 m0, s2
	v_mfma_f32_16x16x32_bf16 v[22:25], v[174:177], v[154:157], v[22:25]
	global_load_lds_dwordx4 v[150:151], off
	v_lshl_add_u64 v[150:151], v[94:95], 0, s[72:73]
	s_mov_b32 m0, s3
	v_mfma_f32_16x16x32_bf16 v[26:29], v[178:181], v[154:157], v[26:29]
	global_load_lds_dwordx4 v[150:151], off
	v_lshl_add_u64 v[150:151], v[100:101], 0, s[72:73]
	s_mov_b32 m0, s20
	v_mfma_f32_16x16x32_bf16 v[30:33], v[182:185], v[154:157], v[30:33]
	global_load_lds_dwordx4 v[150:151], off
	v_lshl_add_u64 v[150:151], v[92:93], 0, s[72:73]
	s_mov_b32 m0, s21
	v_mfma_f32_16x16x32_bf16 v[34:37], v[170:173], v[162:165], v[34:37]
	global_load_lds_dwordx4 v[150:151], off
	v_lshl_add_u64 v[150:151], v[96:97], 0, s[72:73]
	v_mfma_f32_16x16x32_bf16 v[38:41], v[174:177], v[162:165], v[38:41]
	s_mov_b32 m0, s22
	s_nop 0
	global_load_lds_dwordx4 v[150:151], off
	v_mfma_f32_16x16x32_bf16 v[42:45], v[178:181], v[162:165], v[42:45]
	v_lshl_add_u64 v[150:151], v[90:91], 0, s[72:73]
	s_mov_b32 m0, s23
	v_mfma_f32_16x16x32_bf16 v[46:49], v[182:185], v[162:165], v[46:49]
	global_load_lds_dwordx4 v[150:151], off
	s_mov_b32 m0, s25
	v_mfma_f32_16x16x32_bf16 v[50:53], v[170:173], v[166:169], v[50:53]
	v_mfma_f32_16x16x32_bf16 v[54:57], v[174:177], v[166:169], v[54:57]
	v_mfma_f32_16x16x32_bf16 v[58:61], v[178:181], v[166:169], v[58:61]
	v_mfma_f32_16x16x32_bf16 v[62:65], v[182:185], v[166:169], v[62:65]
; DI void gemm_dma(f32x4 (&acc)[4][4], const bf16_t* Ap, int lda, const bf16_t* Bp, int ldb, int K, char* lds) {
;     ...
;   for (int kt = 0; kt < nk; ++kt) {
;     asm volatile("s_waitcnt vmcnt(0)" ::: "memory");
;     __builtin_amdgcn_s_barrier();
;     asm volatile("" ::: "memory");
;     if (kt + 1 < nk) issue(kt + 1);
;     const unsigned sa = lbase + (unsigned)((kt & 1) * 32768);
;     bf16x8 af[4], bfr[4], ag[4], bg[4];
;     asm volatile("ds_read_b128 %0, %8\n\tds_read_b128 %1, %8 offset:2048\n\tds_read_b128 %2, %8 offset:4096\n\tds_read_b128 %3, %8 offset:6144\n\t"
;                  "ds_read_b128 %4, %9\n\tds_read_b128 %5, %9 offset:2048\n\tds_read_b128 %6, %9 offset:4096\n\tds_read_b128 %7, %9 offset:6144"
;                  : "=&v"(af[0]), "=&v"(af[1]), "=&v"(af[2]), "=&v"(af[3]), "=&v"(bfr[0]), "=&v"(bfr[1]), "=&v"(bfr[2]), "=&v"(bfr[3])
;                  : "v"(sa + a0), "v"(sa + b0) : "memory");
;     asm volatile("ds_read_b128 %0, %16\n\tds_read_b128 %1, %16 offset:2048\n\tds_read_b128 %2, %16 offset:4096\n\tds_read_b128 %3, %16 offset:6144\n\t"
;                  "ds_read_b128 %4, %17\n\tds_read_b128 %5, %17 offset:2048\n\tds_read_b128 %6, %17 offset:4096\n\tds_read_b128 %7, %17 offset:6144\n\t"
;                  "s_waitcnt lgkmcnt(8)"
;                  : "=&v"(ag[0]), "=&v"(ag[1]), "=&v"(ag[2]), "=&v"(ag[3]), "=&v"(bg[0]), "=&v"(bg[1]), "=&v"(bg[2]), "=&v"(bg[3]),
;                    "+v"(af[0]), "+v"(af[1]), "+v"(af[2]), "+v"(af[3]), "+v"(bfr[0]), "+v"(bfr[1]), "+v"(bfr[2]), "+v"(bfr[3])
;                  : "v"(sa + a1), "v"(sa + b1) : "memory");
; #pragma unroll
;     for (int mi = 0; mi < 4; ++mi)
; #pragma unroll
;       for (int ni = 0; ni < 4; ++ni) acc[mi][ni] = __builtin_amdgcn_mfma_f32_16x16x32_bf16(bfr[ni], af[mi], acc[mi][ni], 0, 0, 0);
;     asm volatile("s_waitcnt lgkmcnt(0)" : "+v"(ag[0]), "+v"(ag[1]), "+v"(ag[2]), "+v"(ag[3]), "+v"(bg[0]), "+v"(bg[1]), "+v"(bg[2]), "+v"(bg[3]) :: "memory");
; #pragma unroll
;     for (int mi = 0; mi < 4; ++mi)
; #pragma unroll
;       for (int ni = 0; ni < 4; ++ni) acc[mi][ni] = __builtin_amdgcn_mfma_f32_16x16x32_bf16(bg[ni], ag[mi], acc[mi][ni], 0, 0, 0);
;   }
	ds_read_b128 v[150:153], v0
	ds_read_b128 v[154:157], v0 offset:2048
	ds_read_b128 v[162:165], v0 offset:4096
	ds_read_b128 v[166:169], v0 offset:6144
	ds_read_b128 v[170:173], v144
	ds_read_b128 v[174:177], v144 offset:2048
	ds_read_b128 v[178:181], v144 offset:4096
	ds_read_b128 v[182:185], v144 offset:6144
	v_mfma_f32_16x16x32_bf16 v[2:5], v[202:205], v[186:189], v[2:5]
	v_mfma_f32_16x16x32_bf16 v[6:9], v[206:209], v[186:189], v[6:9]
	v_mfma_f32_16x16x32_bf16 v[10:13], v[232:235], v[186:189], v[10:13]
	v_mfma_f32_16x16x32_bf16 v[14:17], v[236:239], v[186:189], v[14:17]
	v_mfma_f32_16x16x32_bf16 v[18:21], v[202:205], v[190:193], v[18:21]
	v_mfma_f32_16x16x32_bf16 v[22:25], v[206:209], v[190:193], v[22:25]
	v_mfma_f32_16x16x32_bf16 v[26:29], v[232:235], v[190:193], v[26:29]
	v_mfma_f32_16x16x32_bf16 v[30:33], v[236:239], v[190:193], v[30:33]
	v_mfma_f32_16x16x32_bf16 v[34:37], v[202:205], v[194:197], v[34:37]
	v_mfma_f32_16x16x32_bf16 v[38:41], v[206:209], v[194:197], v[38:41]
	v_mfma_f32_16x16x32_bf16 v[42:45], v[232:235], v[194:197], v[42:45]
	v_mfma_f32_16x16x32_bf16 v[46:49], v[236:239], v[194:197], v[46:49]
	v_mfma_f32_16x16x32_bf16 v[50:53], v[202:205], v[198:201], v[50:53]
	v_mfma_f32_16x16x32_bf16 v[54:57], v[206:209], v[198:201], v[54:57]
	v_mfma_f32_16x16x32_bf16 v[58:61], v[232:235], v[198:201], v[58:61]
	v_mfma_f32_16x16x32_bf16 v[62:65], v[236:239], v[198:201], v[62:65]
	ds_read_b128 v[186:189], v143
	ds_read_b128 v[190:193], v143 offset:2048
	ds_read_b128 v[194:197], v143 offset:4096
	ds_read_b128 v[198:201], v143 offset:6144
	ds_read_b128 v[202:205], v145
	ds_read_b128 v[206:209], v145 offset:2048
	ds_read_b128 v[232:235], v145 offset:4096
	ds_read_b128 v[236:239], v145 offset:6144
	s_waitcnt lgkmcnt(8)
	s_nop 0
	s_waitcnt lgkmcnt(0)
	v_mfma_f32_16x16x32_bf16 v[2:5], v[170:173], v[150:153], v[2:5]
	s_waitcnt vmcnt(0)
	s_barrier
	v_mfma_f32_16x16x32_bf16 v[6:9], v[174:177], v[150:153], v[6:9]
	v_mfma_f32_16x16x32_bf16 v[10:13], v[178:181], v[150:153], v[10:13]
	v_mfma_f32_16x16x32_bf16 v[14:17], v[182:185], v[150:153], v[14:17]
	v_lshl_add_u64 v[150:151], v[104:105], 0, s[68:69]
	global_load_lds_dwordx4 v[150:151], off
	v_lshl_add_u64 v[150:151], v[98:99], 0, s[68:69]
	s_mov_b32 m0, s27
	v_mfma_f32_16x16x32_bf16 v[18:21], v[170:173], v[154:157], v[18:21]
	global_load_lds_dwordx4 v[150:151], off
	v_lshl_add_u64 v[150:151], v[102:103], 0, s[68:69]
	s_mov_b32 m0, s41
	v_mfma_f32_16x16x32_bf16 v[22:25], v[174:177], v[154:157], v[22:25]
	global_load_lds_dwordx4 v[150:151], off
	v_lshl_add_u64 v[150:151], v[94:95], 0, s[68:69]
	s_mov_b32 m0, s40
	v_mfma_f32_16x16x32_bf16 v[26:29], v[178:181], v[154:157], v[26:29]
	global_load_lds_dwordx4 v[150:151], off
	v_lshl_add_u64 v[150:151], v[100:101], 0, s[68:69]
	s_mov_b32 m0, s31
	v_mfma_f32_16x16x32_bf16 v[30:33], v[182:185], v[154:157], v[30:33]
	global_load_lds_dwordx4 v[150:151], off
	v_lshl_add_u64 v[150:151], v[92:93], 0, s[68:69]
	s_mov_b32 m0, s30
	v_mfma_f32_16x16x32_bf16 v[34:37], v[170:173], v[162:165], v[34:37]
	global_load_lds_dwordx4 v[150:151], off
	v_lshl_add_u64 v[150:151], v[96:97], 0, s[68:69]
	v_mfma_f32_16x16x32_bf16 v[38:41], v[174:177], v[162:165], v[38:41]
	s_mov_b32 m0, s26
	s_nop 0
	global_load_lds_dwordx4 v[150:151], off
	v_mfma_f32_16x16x32_bf16 v[42:45], v[178:181], v[162:165], v[42:45]
	v_lshl_add_u64 v[150:151], v[90:91], 0, s[68:69]
	s_mov_b32 m0, s24
	v_mfma_f32_16x16x32_bf16 v[46:49], v[182:185], v[162:165], v[46:49]
	global_load_lds_dwordx4 v[150:151], off
	s_mov_b32 m0, s1
	v_mfma_f32_16x16x32_bf16 v[50:53], v[170:173], v[166:169], v[50:53]
	v_mfma_f32_16x16x32_bf16 v[54:57], v[174:177], v[166:169], v[54:57]
	v_mfma_f32_16x16x32_bf16 v[58:61], v[178:181], v[166:169], v[58:61]
	v_mfma_f32_16x16x32_bf16 v[62:65], v[182:185], v[166:169], v[62:65]
	ds_read_b128 v[150:153], v146
	ds_read_b128 v[154:157], v146 offset:2048
	ds_read_b128 v[162:165], v146 offset:4096
	ds_read_b128 v[166:169], v146 offset:6144
	ds_read_b128 v[170:173], v147
	ds_read_b128 v[174:177], v147 offset:2048
	ds_read_b128 v[178:181], v147 offset:4096
	ds_read_b128 v[182:185], v147 offset:6144
	v_mfma_f32_16x16x32_bf16 v[2:5], v[202:205], v[186:189], v[2:5]
	v_mfma_f32_16x16x32_bf16 v[6:9], v[206:209], v[186:189], v[6:9]
	v_mfma_f32_16x16x32_bf16 v[10:13], v[232:235], v[186:189], v[10:13]
	v_mfma_f32_16x16x32_bf16 v[14:17], v[236:239], v[186:189], v[14:17]
	v_mfma_f32_16x16x32_bf16 v[18:21], v[202:205], v[190:193], v[18:21]
	v_mfma_f32_16x16x32_bf16 v[22:25], v[206:209], v[190:193], v[22:25]
	v_mfma_f32_16x16x32_bf16 v[26:29], v[232:235], v[190:193], v[26:29]
	v_mfma_f32_16x16x32_bf16 v[30:33], v[236:239], v[190:193], v[30:33]
	v_mfma_f32_16x16x32_bf16 v[34:37], v[202:205], v[194:197], v[34:37]
	v_mfma_f32_16x16x32_bf16 v[38:41], v[206:209], v[194:197], v[38:41]
	v_mfma_f32_16x16x32_bf16 v[42:45], v[232:235], v[194:197], v[42:45]
	v_mfma_f32_16x16x32_bf16 v[46:49], v[236:239], v[194:197], v[46:49]
	v_mfma_f32_16x16x32_bf16 v[50:53], v[202:205], v[198:201], v[50:53]
	v_mfma_f32_16x16x32_bf16 v[54:57], v[206:209], v[198:201], v[54:57]
	v_mfma_f32_16x16x32_bf16 v[58:61], v[232:235], v[198:201], v[58:61]
	v_mfma_f32_16x16x32_bf16 v[62:65], v[236:239], v[198:201], v[62:65]
	ds_read_b128 v[186:189], v148
	ds_read_b128 v[190:193], v148 offset:2048
	ds_read_b128 v[194:197], v148 offset:4096
	ds_read_b128 v[198:201], v148 offset:6144
	ds_read_b128 v[202:205], v149
	ds_read_b128 v[206:209], v149 offset:2048
	ds_read_b128 v[232:235], v149 offset:4096
	ds_read_b128 v[236:239], v149 offset:6144
	s_waitcnt lgkmcnt(8)
	s_nop 0
	s_waitcnt lgkmcnt(0)
	v_mfma_f32_16x16x32_bf16 v[2:5], v[170:173], v[150:153], v[2:5]
	s_waitcnt vmcnt(0)
	s_barrier
; DI void gemm_dma(f32x4 (&acc)[4][4], const bf16_t* Ap, int lda, const bf16_t* Bp, int ldb, int K, char* lds) {
;     ...
;   for (int kt = 0; kt < nk; ++kt) {
;     asm volatile("s_waitcnt vmcnt(0)" ::: "memory");
;     __builtin_amdgcn_s_barrier();
;     asm volatile("" ::: "memory");
;     if (kt + 1 < nk) issue(kt + 1);
;     const unsigned sa = lbase + (unsigned)((kt & 1) * 32768);
;     bf16x8 af[4], bfr[4], ag[4], bg[4];
;     asm volatile("ds_read_b128 %0, %8\n\tds_read_b128 %1, %8 offset:2048\n\tds_read_b128 %2, %8 offset:4096\n\tds_read_b128 %3, %8 offset:6144\n\t"
;                  "ds_read_b128 %4, %9\n\tds_read_b128 %5, %9 offset:2048\n\tds_read_b128 %6, %9 offset:4096\n\tds_read_b128 %7, %9 offset:6144"
;                  : "=&v"(af[0]), "=&v"(af[1]), "=&v"(af[2]), "=&v"(af[3]), "=&v"(bfr[0]), "=&v"(bfr[1]), "=&v"(bfr[2]), "=&v"(bfr[3])
;                  : "v"(sa + a0), "v"(sa + b0) : "memory");
;     asm volatile("ds_read_b128 %0, %16\n\tds_read_b128 %1, %16 offset:2048\n\tds_read_b128 %2, %16 offset:4096\n\tds_read_b128 %3, %16 offset:6144\n\t"
;                  "ds_read_b128 %4, %17\n\tds_read_b128 %5, %17 offset:2048\n\tds_read_b128 %6, %17 offset:4096\n\tds_read_b128 %7, %17 offset:6144\n\t"
;                  "s_waitcnt lgkmcnt(8)"
;                  : "=&v"(ag[0]), "=&v"(ag[1]), "=&v"(ag[2]), "=&v"(ag[3]), "=&v"(bg[0]), "=&v"(bg[1]), "=&v"(bg[2]), "=&v"(bg[3]),
;                    "+v"(af[0]), "+v"(af[1]), "+v"(af[2]), "+v"(af[3]), "+v"(bfr[0]), "+v"(bfr[1]), "+v"(bfr[2]), "+v"(bfr[3])
;                  : "v"(sa + a1), "v"(sa + b1) : "memory");
; #pragma unroll
;     for (int mi = 0; mi < 4; ++mi)
; #pragma unroll
;       for (int ni = 0; ni < 4; ++ni) acc[mi][ni] = __builtin_amdgcn_mfma_f32_16x16x32_bf16(bfr[ni], af[mi], acc[mi][ni], 0, 0, 0);
;     asm volatile("s_waitcnt lgkmcnt(0)" : "+v"(ag[0]), "+v"(ag[1]), "+v"(ag[2]), "+v"(ag[3]), "+v"(bg[0]), "+v"(bg[1]), "+v"(bg[2]), "+v"(bg[3]) :: "memory");
; #pragma unroll
;     for (int mi = 0; mi < 4; ++mi)
; #pragma unroll
;       for (int ni = 0; ni < 4; ++ni) acc[mi][ni] = __builtin_amdgcn_mfma_f32_16x16x32_bf16(bg[ni], ag[mi], acc[mi][ni], 0, 0, 0);
;   }
	v_mfma_f32_16x16x32_bf16 v[6:9], v[174:177], v[150:153], v[6:9]
	v_mfma_f32_16x16x32_bf16 v[10:13], v[178:181], v[150:153], v[10:13]
	v_mfma_f32_16x16x32_bf16 v[14:17], v[182:185], v[150:153], v[14:17]
	v_lshl_add_u64 v[150:151], v[104:105], 0, s[78:79]
	global_load_lds_dwordx4 v[150:151], off
	v_lshl_add_u64 v[150:151], v[98:99], 0, s[78:79]
	s_mov_b32 m0, s0
	v_mfma_f32_16x16x32_bf16 v[18:21], v[170:173], v[154:157], v[18:21]
	global_load_lds_dwordx4 v[150:151], off
	v_lshl_add_u64 v[150:151], v[102:103], 0, s[78:79]
	s_mov_b32 m0, s2
	v_mfma_f32_16x16x32_bf16 v[22:25], v[174:177], v[154:157], v[22:25]
	global_load_lds_dwordx4 v[150:151], off
	v_lshl_add_u64 v[150:151], v[94:95], 0, s[78:79]
	s_mov_b32 m0, s3
	v_mfma_f32_16x16x32_bf16 v[26:29], v[178:181], v[154:157], v[26:29]
	global_load_lds_dwordx4 v[150:151], off
	v_lshl_add_u64 v[150:151], v[100:101], 0, s[78:79]
	s_mov_b32 m0, s20
	v_mfma_f32_16x16x32_bf16 v[30:33], v[182:185], v[154:157], v[30:33]
	global_load_lds_dwordx4 v[150:151], off
	v_lshl_add_u64 v[150:151], v[92:93], 0, s[78:79]
	s_mov_b32 m0, s21
	v_mfma_f32_16x16x32_bf16 v[34:37], v[170:173], v[162:165], v[34:37]
	global_load_lds_dwordx4 v[150:151], off
	v_lshl_add_u64 v[150:151], v[96:97], 0, s[78:79]
	v_mfma_f32_16x16x32_bf16 v[38:41], v[174:177], v[162:165], v[38:41]
	s_mov_b32 m0, s22
	s_nop 0
	global_load_lds_dwordx4 v[150:151], off
	v_mfma_f32_16x16x32_bf16 v[42:45], v[178:181], v[162:165], v[42:45]
	v_lshl_add_u64 v[150:151], v[90:91], 0, s[78:79]
	s_mov_b32 m0, s23
	v_mfma_f32_16x16x32_bf16 v[46:49], v[182:185], v[162:165], v[46:49]
	global_load_lds_dwordx4 v[150:151], off
	s_mov_b32 m0, s25
	v_mfma_f32_16x16x32_bf16 v[50:53], v[170:173], v[166:169], v[50:53]
	v_mfma_f32_16x16x32_bf16 v[54:57], v[174:177], v[166:169], v[54:57]
	v_mfma_f32_16x16x32_bf16 v[58:61], v[178:181], v[166:169], v[58:61]
	v_mfma_f32_16x16x32_bf16 v[62:65], v[182:185], v[166:169], v[62:65]
	ds_read_b128 v[150:153], v0
	ds_read_b128 v[154:157], v0 offset:2048
	ds_read_b128 v[162:165], v0 offset:4096
	ds_read_b128 v[166:169], v0 offset:6144
	ds_read_b128 v[170:173], v144
	ds_read_b128 v[174:177], v144 offset:2048
	ds_read_b128 v[178:181], v144 offset:4096
	ds_read_b128 v[182:185], v144 offset:6144
	v_mfma_f32_16x16x32_bf16 v[2:5], v[202:205], v[186:189], v[2:5]
	v_mfma_f32_16x16x32_bf16 v[6:9], v[206:209], v[186:189], v[6:9]
	v_mfma_f32_16x16x32_bf16 v[10:13], v[232:235], v[186:189], v[10:13]
	v_mfma_f32_16x16x32_bf16 v[14:17], v[236:239], v[186:189], v[14:17]
	v_mfma_f32_16x16x32_bf16 v[18:21], v[202:205], v[190:193], v[18:21]
	v_mfma_f32_16x16x32_bf16 v[22:25], v[206:209], v[190:193], v[22:25]
	v_mfma_f32_16x16x32_bf16 v[26:29], v[232:235], v[190:193], v[26:29]
	v_mfma_f32_16x16x32_bf16 v[30:33], v[236:239], v[190:193], v[30:33]
	v_mfma_f32_16x16x32_bf16 v[34:37], v[202:205], v[194:197], v[34:37]
	v_mfma_f32_16x16x32_bf16 v[38:41], v[206:209], v[194:197], v[38:41]
	v_mfma_f32_16x16x32_bf16 v[42:45], v[232:235], v[194:197], v[42:45]
	v_mfma_f32_16x16x32_bf16 v[46:49], v[236:239], v[194:197], v[46:49]
	v_mfma_f32_16x16x32_bf16 v[50:53], v[202:205], v[198:201], v[50:53]
	v_mfma_f32_16x16x32_bf16 v[54:57], v[206:209], v[198:201], v[54:57]
	v_mfma_f32_16x16x32_bf16 v[58:61], v[232:235], v[198:201], v[58:61]
	v_mfma_f32_16x16x32_bf16 v[62:65], v[236:239], v[198:201], v[62:65]
	ds_read_b128 v[186:189], v143
	ds_read_b128 v[190:193], v143 offset:2048
	ds_read_b128 v[194:197], v143 offset:4096
	ds_read_b128 v[198:201], v143 offset:6144
	ds_read_b128 v[202:205], v145
	ds_read_b128 v[206:209], v145 offset:2048
	ds_read_b128 v[232:235], v145 offset:4096
	ds_read_b128 v[236:239], v145 offset:6144
	s_waitcnt lgkmcnt(8)
	s_nop 0
	s_waitcnt lgkmcnt(0)
	v_mfma_f32_16x16x32_bf16 v[2:5], v[170:173], v[150:153], v[2:5]
	s_waitcnt vmcnt(0)
	s_barrier
	v_mfma_f32_16x16x32_bf16 v[6:9], v[174:177], v[150:153], v[6:9]
	v_mfma_f32_16x16x32_bf16 v[10:13], v[178:181], v[150:153], v[10:13]
	v_mfma_f32_16x16x32_bf16 v[14:17], v[182:185], v[150:153], v[14:17]
	v_lshl_add_u64 v[150:151], v[104:105], 0, s[80:81]
	global_load_lds_dwordx4 v[150:151], off
	v_lshl_add_u64 v[150:151], v[98:99], 0, s[80:81]
	s_mov_b32 m0, s27
	v_mfma_f32_16x16x32_bf16 v[18:21], v[170:173], v[154:157], v[18:21]
	global_load_lds_dwordx4 v[150:151], off
	v_lshl_add_u64 v[150:151], v[102:103], 0, s[80:81]
	s_mov_b32 m0, s41
	v_mfma_f32_16x16x32_bf16 v[22:25], v[174:177], v[154:157], v[22:25]
	global_load_lds_dwordx4 v[150:151], off
	v_lshl_add_u64 v[150:151], v[94:95], 0, s[80:81]
	s_mov_b32 m0, s40
	v_mfma_f32_16x16x32_bf16 v[26:29], v[178:181], v[154:157], v[26:29]
	global_load_lds_dwordx4 v[150:151], off
	v_lshl_add_u64 v[150:151], v[100:101], 0, s[80:81]
	s_mov_b32 m0, s31
	v_mfma_f32_16x16x32_bf16 v[30:33], v[182:185], v[154:157], v[30:33]
	global_load_lds_dwordx4 v[150:151], off
	v_lshl_add_u64 v[150:151], v[92:93], 0, s[80:81]
	s_mov_b32 m0, s30
	v_mfma_f32_16x16x32_bf16 v[34:37], v[170:173], v[162:165], v[34:37]
	global_load_lds_dwordx4 v[150:151], off
	v_lshl_add_u64 v[150:151], v[96:97], 0, s[80:81]
	v_mfma_f32_16x16x32_bf16 v[38:41], v[174:177], v[162:165], v[38:41]
	s_mov_b32 m0, s26
	v_lshl_add_u64 v[104:105], v[104:105], 0, s[88:89]
	global_load_lds_dwordx4 v[150:151], off
	v_mfma_f32_16x16x32_bf16 v[42:45], v[178:181], v[162:165], v[42:45]
	v_lshl_add_u64 v[150:151], v[90:91], 0, s[80:81]
	s_mov_b32 m0, s24
	v_lshl_add_u64 v[98:99], v[98:99], 0, s[88:89]
	v_mfma_f32_16x16x32_bf16 v[46:49], v[182:185], v[162:165], v[46:49]
	global_load_lds_dwordx4 v[150:151], off
	s_mov_b32 m0, s1
	v_mfma_f32_16x16x32_bf16 v[50:53], v[170:173], v[166:169], v[50:53]
	v_lshl_add_u64 v[94:95], v[94:95], 0, s[88:89]
; DI void gemm_dma(f32x4 (&acc)[4][4], const bf16_t* Ap, int lda, const bf16_t* Bp, int ldb, int K, char* lds) {
;     ...
;   for (int kt = 0; kt < nk; ++kt) {
;     asm volatile("s_waitcnt vmcnt(0)" ::: "memory");
;     __builtin_amdgcn_s_barrier();
;     asm volatile("" ::: "memory");
;     if (kt + 1 < nk) issue(kt + 1);
;     const unsigned sa = lbase + (unsigned)((kt & 1) * 32768);
;     bf16x8 af[4], bfr[4], ag[4], bg[4];
;     asm volatile("ds_read_b128 %0, %8\n\tds_read_b128 %1, %8 offset:2048\n\tds_read_b128 %2, %8 offset:4096\n\tds_read_b128 %3, %8 offset:6144\n\t"
;                  "ds_read_b128 %4, %9\n\tds_read_b128 %5, %9 offset:2048\n\tds_read_b128 %6, %9 offset:4096\n\tds_read_b128 %7, %9 offset:6144"
;                  : "=&v"(af[0]), "=&v"(af[1]), "=&v"(af[2]), "=&v"(af[3]), "=&v"(bfr[0]), "=&v"(bfr[1]), "=&v"(bfr[2]), "=&v"(bfr[3])
;                  : "v"(sa + a0), "v"(sa + b0) : "memory");
;     asm volatile("ds_read_b128 %0, %16\n\tds_read_b128 %1, %16 offset:2048\n\tds_read_b128 %2, %16 offset:4096\n\tds_read_b128 %3, %16 offset:6144\n\t"
;                  "ds_read_b128 %4, %17\n\tds_read_b128 %5, %17 offset:2048\n\tds_read_b128 %6, %17 offset:4096\n\tds_read_b128 %7, %17 offset:6144\n\t"
;                  "s_waitcnt lgkmcnt(8)"
;                  : "=&v"(ag[0]), "=&v"(ag[1]), "=&v"(ag[2]), "=&v"(ag[3]), "=&v"(bg[0]), "=&v"(bg[1]), "=&v"(bg[2]), "=&v"(bg[3]),
;                    "+v"(af[0]), "+v"(af[1]), "+v"(af[2]), "+v"(af[3]), "+v"(bfr[0]), "+v"(bfr[1]), "+v"(bfr[2]), "+v"(bfr[3])
;                  : "v"(sa + a1), "v"(sa + b1) : "memory");
; #pragma unroll
;     for (int mi = 0; mi < 4; ++mi)
; #pragma unroll
;       for (int ni = 0; ni < 4; ++ni) acc[mi][ni] = __builtin_amdgcn_mfma_f32_16x16x32_bf16(bfr[ni], af[mi], acc[mi][ni], 0, 0, 0);
;     asm volatile("s_waitcnt lgkmcnt(0)" : "+v"(ag[0]), "+v"(ag[1]), "+v"(ag[2]), "+v"(ag[3]), "+v"(bg[0]), "+v"(bg[1]), "+v"(bg[2]), "+v"(bg[3]) :: "memory");
; #pragma unroll
;     for (int mi = 0; mi < 4; ++mi)
; #pragma unroll
;       for (int ni = 0; ni < 4; ++ni) acc[mi][ni] = __builtin_amdgcn_mfma_f32_16x16x32_bf16(bg[ni], ag[mi], acc[mi][ni], 0, 0, 0);
;   }
	v_lshl_add_u64 v[92:93], v[92:93], 0, s[88:89]
	v_lshl_add_u64 v[90:91], v[90:91], 0, s[88:89]
	v_mfma_f32_16x16x32_bf16 v[54:57], v[174:177], v[166:169], v[54:57]
	v_mfma_f32_16x16x32_bf16 v[58:61], v[178:181], v[166:169], v[58:61]
	v_mfma_f32_16x16x32_bf16 v[62:65], v[182:185], v[166:169], v[62:65]
	ds_read_b128 v[150:153], v146
	ds_read_b128 v[154:157], v146 offset:2048
	ds_read_b128 v[162:165], v146 offset:4096
	ds_read_b128 v[166:169], v146 offset:6144
	ds_read_b128 v[170:173], v147
	ds_read_b128 v[174:177], v147 offset:2048
	ds_read_b128 v[178:181], v147 offset:4096
	ds_read_b128 v[182:185], v147 offset:6144
	v_mfma_f32_16x16x32_bf16 v[2:5], v[202:205], v[186:189], v[2:5]
	v_mfma_f32_16x16x32_bf16 v[6:9], v[206:209], v[186:189], v[6:9]
	v_mfma_f32_16x16x32_bf16 v[10:13], v[232:235], v[186:189], v[10:13]
	v_mfma_f32_16x16x32_bf16 v[14:17], v[236:239], v[186:189], v[14:17]
	v_mfma_f32_16x16x32_bf16 v[18:21], v[202:205], v[190:193], v[18:21]
	v_mfma_f32_16x16x32_bf16 v[22:25], v[206:209], v[190:193], v[22:25]
	v_mfma_f32_16x16x32_bf16 v[26:29], v[232:235], v[190:193], v[26:29]
	v_mfma_f32_16x16x32_bf16 v[30:33], v[236:239], v[190:193], v[30:33]
	v_mfma_f32_16x16x32_bf16 v[34:37], v[202:205], v[194:197], v[34:37]
	v_mfma_f32_16x16x32_bf16 v[38:41], v[206:209], v[194:197], v[38:41]
	v_mfma_f32_16x16x32_bf16 v[42:45], v[232:235], v[194:197], v[42:45]
	v_mfma_f32_16x16x32_bf16 v[46:49], v[236:239], v[194:197], v[46:49]
	v_mfma_f32_16x16x32_bf16 v[50:53], v[202:205], v[198:201], v[50:53]
	v_mfma_f32_16x16x32_bf16 v[54:57], v[206:209], v[198:201], v[54:57]
	v_mfma_f32_16x16x32_bf16 v[58:61], v[232:235], v[198:201], v[58:61]
	v_mfma_f32_16x16x32_bf16 v[62:65], v[236:239], v[198:201], v[62:65]
	ds_read_b128 v[186:189], v148
	ds_read_b128 v[190:193], v148 offset:2048
	ds_read_b128 v[194:197], v148 offset:4096
	ds_read_b128 v[198:201], v148 offset:6144
	ds_read_b128 v[202:205], v149
	ds_read_b128 v[206:209], v149 offset:2048
	ds_read_b128 v[232:235], v149 offset:4096
	ds_read_b128 v[236:239], v149 offset:6144
	s_waitcnt lgkmcnt(8)
	s_nop 0
	s_waitcnt lgkmcnt(0)
	s_waitcnt vmcnt(0)
	s_barrier
	global_load_lds_dwordx4 v[104:105], off
	s_mov_b32 m0, s0
	v_mfma_f32_16x16x32_bf16 v[2:5], v[170:173], v[150:153], v[2:5]
	global_load_lds_dwordx4 v[98:99], off
	v_lshl_add_u64 v[98:99], v[102:103], 0, s[88:89]
	v_mfma_f32_16x16x32_bf16 v[6:9], v[174:177], v[150:153], v[6:9]
	s_mov_b32 m0, s2
	s_mul_i32 s0, s38, s49
	global_load_lds_dwordx4 v[98:99], off
	v_mfma_f32_16x16x32_bf16 v[10:13], v[178:181], v[150:153], v[10:13]
	s_mov_b32 m0, s3
	s_add_i32 s0, s0, s87
	global_load_lds_dwordx4 v[94:95], off
	v_mfma_f32_16x16x32_bf16 v[14:17], v[182:185], v[150:153], v[14:17]
	v_lshl_add_u64 v[94:95], v[100:101], 0, s[88:89]
	s_mov_b32 m0, s20
	s_cmp_ge_u32 s39, s48
	v_mfma_f32_16x16x32_bf16 v[30:33], v[182:185], v[154:157], v[30:33]
	global_load_lds_dwordx4 v[94:95], off
	s_mov_b32 m0, s21
	v_mfma_f32_16x16x32_bf16 v[34:37], v[170:173], v[162:165], v[34:37]
	global_load_lds_dwordx4 v[92:93], off
	v_lshl_add_u64 v[92:93], v[96:97], 0, s[88:89]
	v_mfma_f32_16x16x32_bf16 v[18:21], v[170:173], v[154:157], v[18:21]
	s_mov_b32 m0, s22
	s_nop 0
	global_load_lds_dwordx4 v[92:93], off
	v_mfma_f32_16x16x32_bf16 v[22:25], v[174:177], v[154:157], v[22:25]
	s_mov_b32 m0, s23
	s_nop 0
	global_load_lds_dwordx4 v[90:91], off
	v_mfma_f32_16x16x32_bf16 v[26:29], v[178:181], v[154:157], v[26:29]
	v_mfma_f32_16x16x32_bf16 v[38:41], v[174:177], v[162:165], v[38:41]
	v_mfma_f32_16x16x32_bf16 v[42:45], v[178:181], v[162:165], v[42:45]
	v_mfma_f32_16x16x32_bf16 v[46:49], v[182:185], v[162:165], v[46:49]
	v_mfma_f32_16x16x32_bf16 v[50:53], v[170:173], v[166:169], v[50:53]
	v_mfma_f32_16x16x32_bf16 v[54:57], v[174:177], v[166:169], v[54:57]
	v_mfma_f32_16x16x32_bf16 v[58:61], v[178:181], v[166:169], v[58:61]
	v_mfma_f32_16x16x32_bf16 v[62:65], v[182:185], v[166:169], v[62:65]
	ds_read_b128 v[90:93], v0
	ds_read_b128 v[94:97], v0 offset:2048
	ds_read_b128 v[98:101], v0 offset:4096
	ds_read_b128 v[102:105], v0 offset:6144
	ds_read_b128 v[150:153], v144
	ds_read_b128 v[154:157], v144 offset:2048
	ds_read_b128 v[162:165], v144 offset:4096
	ds_read_b128 v[166:169], v144 offset:6144
	v_mfma_f32_16x16x32_bf16 v[2:5], v[202:205], v[186:189], v[2:5]
	v_mfma_f32_16x16x32_bf16 v[6:9], v[206:209], v[186:189], v[6:9]
	v_mfma_f32_16x16x32_bf16 v[10:13], v[232:235], v[186:189], v[10:13]
	v_mfma_f32_16x16x32_bf16 v[14:17], v[236:239], v[186:189], v[14:17]
	v_mfma_f32_16x16x32_bf16 v[30:33], v[236:239], v[190:193], v[30:33]
	v_mfma_f32_16x16x32_bf16 v[34:37], v[202:205], v[194:197], v[34:37]
	v_mfma_f32_16x16x32_bf16 v[18:21], v[202:205], v[190:193], v[18:21]
	v_mfma_f32_16x16x32_bf16 v[22:25], v[206:209], v[190:193], v[22:25]
	v_mfma_f32_16x16x32_bf16 v[26:29], v[232:235], v[190:193], v[26:29]
	v_mfma_f32_16x16x32_bf16 v[38:41], v[206:209], v[194:197], v[38:41]
	v_mfma_f32_16x16x32_bf16 v[42:45], v[232:235], v[194:197], v[42:45]
	v_mfma_f32_16x16x32_bf16 v[46:49], v[236:239], v[194:197], v[46:49]
	v_mfma_f32_16x16x32_bf16 v[50:53], v[202:205], v[198:201], v[50:53]
	v_mfma_f32_16x16x32_bf16 v[54:57], v[206:209], v[198:201], v[54:57]
	v_mfma_f32_16x16x32_bf16 v[58:61], v[232:235], v[198:201], v[58:61]
	v_mfma_f32_16x16x32_bf16 v[62:65], v[236:239], v[198:201], v[62:65]
	ds_read_b128 v[170:173], v143
	ds_read_b128 v[174:177], v143 offset:2048
	ds_read_b128 v[178:181], v143 offset:4096
	ds_read_b128 v[182:185], v143 offset:6144
	ds_read_b128 v[186:189], v145
	ds_read_b128 v[190:193], v145 offset:2048
	ds_read_b128 v[194:197], v145 offset:4096
	ds_read_b128 v[198:201], v145 offset:6144
	s_waitcnt lgkmcnt(8)
	s_nop 0
	s_waitcnt lgkmcnt(0)
	v_mfma_f32_16x16x32_bf16 v[2:5], v[150:153], v[90:93], v[2:5]
	s_waitcnt vmcnt(0)
	s_barrier
; DI unsigned pk2(float a, float b) { f32x2 v = {a, b}; bfv2 r = __builtin_convertvector(v, bfv2); return __builtin_bit_cast(unsigned, r); }
; DI float bf_lo(unsigned u) { return __uint_as_float(u << 16); }
; DI float bf_hi(unsigned u) { return __uint_as_float(u & 0xffff0000u); }
; DI void gemm_dma(f32x4 (&acc)[4][4], const bf16_t* Ap, int lda, const bf16_t* Bp, int ldb, int K, char* lds) {
;     ...
; #pragma unroll
;     for (int mi = 0; mi < 4; ++mi)
; #pragma unroll
;       for (int ni = 0; ni < 4; ++ni) acc[mi][ni] = __builtin_amdgcn_mfma_f32_16x16x32_bf16(bfr[ni], af[mi], acc[mi][ni], 0, 0, 0);
;     asm volatile("s_waitcnt lgkmcnt(0)" : "+v"(ag[0]), "+v"(ag[1]), "+v"(ag[2]), "+v"(ag[3]), "+v"(bg[0]), "+v"(bg[1]), "+v"(bg[2]), "+v"(bg[3]) :: "memory");
; #pragma unroll
;     for (int mi = 0; mi < 4; ++mi)
; #pragma unroll
;       for (int ni = 0; ni < 4; ++ni) acc[mi][ni] = __builtin_amdgcn_mfma_f32_16x16x32_bf16(bg[ni], ag[mi], acc[mi][ni], 0, 0, 0);
;   }
;   asm volatile("" ::: "memory");
;   __builtin_amdgcn_s_barrier();
; DI void phase_merge(const Params& p, int l, char* lds) {
;     ...
; #pragma unroll
;     for (int mi = 0; mi < 4; ++mi) {
;       const int R = mt * 128 + wm * 64 + mi * 16 + l15;
; #pragma unroll
;       for (int ni = 0; ni < 4; ++ni) {
;         const int c = nt * 128 + wn * 64 + ni * 16 + quad * 4;
;         const u32x2 g2 = *(const u32x2*)(p.z + (size_t)R * NZ + C_MA + c);
;         const f32x4 v2 = a1[mi][ni]; const u32x2 u1 = pk[mi][ni];
;         u32x2 o;
;         o[0] = pk2(bf_lo(u1[0]) + bf_lo(g2[0]) * v2[0], bf_hi(u1[0]) + bf_hi(g2[0]) * v2[1]);
;         o[1] = pk2(bf_lo(u1[1]) + bf_lo(g2[1]) * v2[2], bf_hi(u1[1]) + bf_hi(g2[1]) * v2[3]);
;         *(u32x2*)(p.hn + (size_t)R * DM + c) = o;
;       }
	v_mfma_f32_16x16x32_bf16 v[6:9], v[154:157], v[90:93], v[6:9]
	v_mfma_f32_16x16x32_bf16 v[10:13], v[162:165], v[90:93], v[10:13]
	v_mfma_f32_16x16x32_bf16 v[14:17], v[166:169], v[90:93], v[14:17]
	v_mfma_f32_16x16x32_bf16 v[30:33], v[166:169], v[94:97], v[30:33]
	v_mfma_f32_16x16x32_bf16 v[34:37], v[150:153], v[98:101], v[34:37]
	v_mfma_f32_16x16x32_bf16 v[18:21], v[150:153], v[94:97], v[18:21]
	v_mfma_f32_16x16x32_bf16 v[22:25], v[154:157], v[94:97], v[22:25]
	v_mfma_f32_16x16x32_bf16 v[26:29], v[162:165], v[94:97], v[26:29]
	v_mfma_f32_16x16x32_bf16 v[38:41], v[154:157], v[98:101], v[38:41]
	v_mfma_f32_16x16x32_bf16 v[42:45], v[162:165], v[98:101], v[42:45]
	v_mfma_f32_16x16x32_bf16 v[46:49], v[166:169], v[98:101], v[46:49]
	v_mfma_f32_16x16x32_bf16 v[50:53], v[150:153], v[102:105], v[50:53]
	v_mfma_f32_16x16x32_bf16 v[54:57], v[154:157], v[102:105], v[54:57]
	v_mfma_f32_16x16x32_bf16 v[58:61], v[162:165], v[102:105], v[58:61]
	v_mfma_f32_16x16x32_bf16 v[62:65], v[166:169], v[102:105], v[62:65]
	ds_read_b128 v[90:93], v146
	ds_read_b128 v[94:97], v146 offset:2048
	ds_read_b128 v[98:101], v146 offset:4096
	ds_read_b128 v[102:105], v146 offset:6144
	ds_read_b128 v[150:153], v147
	ds_read_b128 v[154:157], v147 offset:2048
	ds_read_b128 v[162:165], v147 offset:4096
	ds_read_b128 v[166:169], v147 offset:6144
	v_mfma_f32_16x16x32_bf16 v[2:5], v[186:189], v[170:173], v[2:5]
	v_mfma_f32_16x16x32_bf16 v[6:9], v[190:193], v[170:173], v[6:9]
	v_mfma_f32_16x16x32_bf16 v[10:13], v[194:197], v[170:173], v[10:13]
	v_mfma_f32_16x16x32_bf16 v[14:17], v[198:201], v[170:173], v[14:17]
	v_mfma_f32_16x16x32_bf16 v[30:33], v[198:201], v[174:177], v[30:33]
	v_mfma_f32_16x16x32_bf16 v[34:37], v[186:189], v[178:181], v[34:37]
	v_mfma_f32_16x16x32_bf16 v[18:21], v[186:189], v[174:177], v[18:21]
	v_mfma_f32_16x16x32_bf16 v[22:25], v[190:193], v[174:177], v[22:25]
	v_mfma_f32_16x16x32_bf16 v[26:29], v[194:197], v[174:177], v[26:29]
	v_mfma_f32_16x16x32_bf16 v[38:41], v[190:193], v[178:181], v[38:41]
	v_mfma_f32_16x16x32_bf16 v[42:45], v[194:197], v[178:181], v[42:45]
	v_mfma_f32_16x16x32_bf16 v[46:49], v[198:201], v[178:181], v[46:49]
	v_mfma_f32_16x16x32_bf16 v[50:53], v[186:189], v[182:185], v[50:53]
	v_mfma_f32_16x16x32_bf16 v[54:57], v[190:193], v[182:185], v[54:57]
	v_mfma_f32_16x16x32_bf16 v[58:61], v[194:197], v[182:185], v[58:61]
	v_mfma_f32_16x16x32_bf16 v[62:65], v[198:201], v[182:185], v[62:65]
	ds_read_b128 v[144:147], v148
	ds_read_b128 v[170:173], v148 offset:2048
	ds_read_b128 v[174:177], v148 offset:4096
	ds_read_b128 v[178:181], v148 offset:6144
	ds_read_b128 v[182:185], v149
	ds_read_b128 v[186:189], v149 offset:2048
	ds_read_b128 v[190:193], v149 offset:4096
	ds_read_b128 v[194:197], v149 offset:6144
	s_waitcnt lgkmcnt(8)
	s_nop 0
	s_waitcnt lgkmcnt(0)
	v_mfma_f32_16x16x32_bf16 v[2:5], v[150:153], v[90:93], v[2:5]
	s_barrier
	v_mfma_f32_16x16x32_bf16 v[6:9], v[154:157], v[90:93], v[6:9]
	v_mfma_f32_16x16x32_bf16 v[10:13], v[162:165], v[90:93], v[10:13]
	v_mfma_f32_16x16x32_bf16 v[14:17], v[166:169], v[90:93], v[14:17]
	v_mfma_f32_16x16x32_bf16 v[30:33], v[166:169], v[94:97], v[30:33]
	v_mfma_f32_16x16x32_bf16 v[90:93], v[150:153], v[98:101], v[34:37]
	v_mfma_f32_16x16x32_bf16 v[34:37], v[194:197], v[170:173], v[30:33]
	v_mfma_f32_16x16x32_bf16 v[30:33], v[182:185], v[174:177], v[90:93]
	s_nop 5
	v_lshl_add_u64 v[228:229], v[86:87], 0, v[70:71]
	global_load_dwordx2 v[214:215], v[228:229], off
	v_lshl_add_u64 v[228:229], v[86:87], 0, v[72:73]
	global_load_dwordx2 v[216:217], v[228:229], off
	v_lshl_add_u64 v[228:229], v[86:87], 0, v[68:69]
	global_load_dwordx2 v[222:223], v[228:229], off
	v_lshl_add_u64 v[228:229], v[86:87], 0, v[66:67]
	global_load_dwordx2 v[224:225], v[228:229], off
	v_lshl_add_u64 v[228:229], v[82:83], 0, s[36:37]
	v_lshl_add_u64 v[228:229], v[228:229], 0, v[70:71]
	global_load_dwordx2 v[226:227], v[228:229], off
	v_mfma_f32_16x16x32_bf16 v[18:21], v[150:153], v[94:97], v[18:21]
	v_lshlrev_b32_e32 v92, 16, v142
	v_and_b32_e32 v93, 0xffff0000, v142
	v_mfma_f32_16x16x32_bf16 v[22:25], v[154:157], v[94:97], v[22:25]
	v_mfma_f32_16x16x32_bf16 v[26:29], v[162:165], v[94:97], v[26:29]
	v_mfma_f32_16x16x32_bf16 v[94:97], v[154:157], v[98:101], v[38:41]
	v_mfma_f32_16x16x32_bf16 v[148:151], v[150:153], v[102:105], v[50:53]
	v_mfma_f32_16x16x32_bf16 v[152:155], v[154:157], v[102:105], v[54:57]
	v_mfma_f32_16x16x32_bf16 v[156:159], v[162:165], v[102:105], v[58:61]
	v_mfma_f32_16x16x32_bf16 v[102:105], v[166:169], v[102:105], v[62:65]
	v_mfma_f32_16x16x32_bf16 v[62:65], v[182:185], v[144:147], v[2:5]
	v_mfma_f32_16x16x32_bf16 v[38:41], v[190:193], v[170:173], v[26:29]
	v_mfma_f32_16x16x32_bf16 v[26:29], v[186:189], v[174:177], v[94:97]
	v_mfma_f32_16x16x32_bf16 v[58:61], v[186:189], v[144:147], v[6:9]
	s_waitcnt vmcnt(4)
	v_mov_b32_e32 v90, v214
	v_mov_b32_e32 v91, v215
	v_lshl_add_u64 v[228:229], v[82:83], 0, s[36:37]
	v_lshl_add_u64 v[228:229], v[228:229], 0, v[72:73]
	global_load_dwordx2 v[214:215], v[228:229], off
	s_nop 0
	v_lshlrev_b32_e32 v94, 16, v90
	v_and_b32_e32 v95, 0xffff0000, v90
	s_nop 0
	v_pk_fma_f32 v[62:63], v[62:63], v[94:95], v[92:93]
	v_lshlrev_b32_e32 v92, 16, v91
	v_cvt_pk_bf16_f32 v90, v62, v63
	v_lshlrev_b32_e32 v62, 16, v141
	v_and_b32_e32 v63, 0xffff0000, v141
	v_and_b32_e32 v93, 0xffff0000, v91
	v_pk_fma_f32 v[62:63], v[64:65], v[92:93], v[62:63]
	v_cvt_pk_bf16_f32 v91, v62, v63
	v_lshl_add_u64 v[62:63], s[8:9], 0, v[88:89]
	v_lshl_add_u64 v[62:63], v[62:63], 0, v[70:71]
	global_store_dwordx2 v[62:63], v[90:91], off
	v_lshlrev_b32_e32 v88, 16, v140
	v_and_b32_e32 v89, 0xffff0000, v140
	v_mfma_f32_16x16x32_bf16 v[54:57], v[190:193], v[144:147], v[10:13]
	s_waitcnt vmcnt(5)
; DI unsigned pk2(float a, float b) { f32x2 v = {a, b}; bfv2 r = __builtin_convertvector(v, bfv2); return __builtin_bit_cast(unsigned, r); }
; DI float bf_lo(unsigned u) { return __uint_as_float(u << 16); }
; DI float bf_hi(unsigned u) { return __uint_as_float(u & 0xffff0000u); }
; DI void phase_merge(const Params& p, int l, char* lds) {
;     ...
; #pragma unroll
;     for (int mi = 0; mi < 4; ++mi) {
;       const int R = mt * 128 + wm * 64 + mi * 16 + l15;
; #pragma unroll
;       for (int ni = 0; ni < 4; ++ni) {
;         const int c = nt * 128 + wn * 64 + ni * 16 + quad * 4;
;         const u32x2 g2 = *(const u32x2*)(p.z + (size_t)R * NZ + C_MA + c);
;         const f32x4 v2 = a1[mi][ni]; const u32x2 u1 = pk[mi][ni];
;         u32x2 o;
;         o[0] = pk2(bf_lo(u1[0]) + bf_lo(g2[0]) * v2[0], bf_hi(u1[0]) + bf_hi(g2[0]) * v2[1]);
;         o[1] = pk2(bf_lo(u1[1]) + bf_lo(g2[1]) * v2[2], bf_hi(u1[1]) + bf_hi(g2[1]) * v2[3]);
;         *(u32x2*)(p.hn + (size_t)R * DM + c) = o;
;       }
	v_mov_b32_e32 v64, v216
	v_mov_b32_e32 v65, v217
	v_lshl_add_u64 v[228:229], v[82:83], 0, s[36:37]
	v_lshl_add_u64 v[228:229], v[228:229], 0, v[68:69]
	global_load_dwordx2 v[216:217], v[228:229], off
	v_lshlrev_b32_e32 v90, 16, v64
	v_and_b32_e32 v91, 0xffff0000, v64
	v_pk_fma_f32 v[58:59], v[58:59], v[90:91], v[88:89]
	v_lshlrev_b32_e32 v88, 16, v139
	v_and_b32_e32 v89, 0xffff0000, v139
	v_lshlrev_b32_e32 v64, 16, v65
	v_and_b32_e32 v65, 0xffff0000, v65
	v_pk_fma_f32 v[60:61], v[60:61], v[64:65], v[88:89]
	v_cvt_pk_bf16_f32 v58, v58, v59
	v_cvt_pk_bf16_f32 v59, v60, v61
	global_store_dwordx2 v[62:63], v[58:59], off offset:32
	v_lshlrev_b32_e32 v60, 16, v135
	v_and_b32_e32 v61, 0xffff0000, v135
	v_mfma_f32_16x16x32_bf16 v[50:53], v[194:197], v[144:147], v[14:17]
	s_waitcnt vmcnt(6)
	v_mov_b32_e32 v58, v222
	v_mov_b32_e32 v59, v223
	v_lshl_add_u64 v[228:229], v[82:83], 0, s[36:37]
	v_lshl_add_u64 v[228:229], v[228:229], 0, v[66:67]
	global_load_dwordx2 v[222:223], v[228:229], off
	v_lshlrev_b32_e32 v64, 16, v58
	v_and_b32_e32 v65, 0xffff0000, v58
	v_pk_fma_f32 v[54:55], v[54:55], v[64:65], v[60:61]
	v_lshlrev_b32_e32 v60, 16, v134
	v_and_b32_e32 v61, 0xffff0000, v134
	v_lshlrev_b32_e32 v58, 16, v59
	v_and_b32_e32 v59, 0xffff0000, v59
	v_pk_fma_f32 v[56:57], v[56:57], v[58:59], v[60:61]
	v_cvt_pk_bf16_f32 v54, v54, v55
	v_cvt_pk_bf16_f32 v55, v56, v57
	global_store_dwordx2 v[62:63], v[54:55], off offset:64
	v_lshlrev_b32_e32 v56, 16, v133
	v_and_b32_e32 v57, 0xffff0000, v133
	v_mfma_f32_16x16x32_bf16 v[198:201], v[162:165], v[98:101], v[42:45]
	s_waitcnt vmcnt(7)
	v_mov_b32_e32 v54, v224
	v_mov_b32_e32 v55, v225
	v_lshl_add_u64 v[228:229], v[78:79], 0, s[36:37]
	v_lshl_add_u64 v[228:229], v[228:229], 0, v[70:71]
	global_load_dwordx2 v[224:225], v[228:229], off
	v_lshlrev_b32_e32 v58, 16, v54
	v_and_b32_e32 v59, 0xffff0000, v54
	v_pk_fma_f32 v[50:51], v[50:51], v[58:59], v[56:57]
	v_lshlrev_b32_e32 v56, 16, v132
	v_and_b32_e32 v57, 0xffff0000, v132
	v_lshlrev_b32_e32 v54, 16, v55
	v_and_b32_e32 v55, 0xffff0000, v55
	v_pk_fma_f32 v[52:53], v[52:53], v[54:55], v[56:57]
	v_cvt_pk_bf16_f32 v50, v50, v51
	v_cvt_pk_bf16_f32 v51, v52, v53
	global_store_dwordx2 v[62:63], v[50:51], off offset:96
	v_lshl_add_u64 v[50:51], v[82:83], 0, s[36:37]
	v_mfma_f32_16x16x32_bf16 v[98:101], v[166:169], v[98:101], v[46:49]
	v_lshlrev_b32_e32 v56, 16, v131
	v_and_b32_e32 v57, 0xffff0000, v131
	v_lshlrev_b64 v[52:53], 11, v[84:85]
	v_mfma_f32_16x16x32_bf16 v[46:49], v[182:185], v[170:173], v[18:21]
	s_waitcnt vmcnt(8)
	v_mov_b32_e32 v54, v226
	v_mov_b32_e32 v55, v227
	v_lshl_add_u64 v[228:229], v[78:79], 0, s[36:37]
	v_lshl_add_u64 v[228:229], v[228:229], 0, v[72:73]
	global_load_dwordx2 v[226:227], v[228:229], off
	v_lshlrev_b32_e32 v58, 16, v54
	v_and_b32_e32 v59, 0xffff0000, v54
	s_nop 4
	v_pk_fma_f32 v[46:47], v[46:47], v[58:59], v[56:57]
	v_lshlrev_b32_e32 v56, 16, v55
	v_cvt_pk_bf16_f32 v54, v46, v47
	v_lshlrev_b32_e32 v46, 16, v130
	v_and_b32_e32 v47, 0xffff0000, v130
	v_and_b32_e32 v57, 0xffff0000, v55
	v_pk_fma_f32 v[46:47], v[48:49], v[56:57], v[46:47]
	v_cvt_pk_bf16_f32 v55, v46, v47
	v_lshl_add_u64 v[46:47], s[8:9], 0, v[52:53]
	v_lshl_add_u64 v[46:47], v[46:47], 0, v[70:71]
	global_store_dwordx2 v[46:47], v[54:55], off
	v_mfma_f32_16x16x32_bf16 v[42:45], v[186:189], v[170:173], v[22:25]
	v_lshlrev_b32_e32 v52, 16, v129
	v_and_b32_e32 v53, 0xffff0000, v129
	s_waitcnt vmcnt(9)
	v_mov_b32_e32 v48, v214
	v_mov_b32_e32 v49, v215
	v_lshl_add_u64 v[228:229], v[78:79], 0, s[36:37]
	v_lshl_add_u64 v[228:229], v[228:229], 0, v[68:69]
	global_load_dwordx2 v[214:215], v[228:229], off
	v_lshlrev_b32_e32 v54, 16, v48
	v_and_b32_e32 v55, 0xffff0000, v48
	s_nop 2
	v_pk_fma_f32 v[42:43], v[42:43], v[54:55], v[52:53]
	v_lshlrev_b32_e32 v52, 16, v128
	v_and_b32_e32 v53, 0xffff0000, v128
	v_lshlrev_b32_e32 v48, 16, v49
	v_and_b32_e32 v49, 0xffff0000, v49
	v_pk_fma_f32 v[44:45], v[44:45], v[48:49], v[52:53]
	v_cvt_pk_bf16_f32 v42, v42, v43
	v_cvt_pk_bf16_f32 v43, v44, v45
	global_store_dwordx2 v[46:47], v[42:43], off offset:32
	v_lshlrev_b32_e32 v44, 16, v127
	v_and_b32_e32 v45, 0xffff0000, v127
	v_mfma_f32_16x16x32_bf16 v[22:25], v[190:193], v[174:177], v[198:201]
	s_waitcnt vmcnt(9)
	v_mov_b32_e32 v42, v216
	v_mov_b32_e32 v43, v217
	v_lshl_add_u64 v[228:229], v[78:79], 0, s[36:37]
	v_lshl_add_u64 v[228:229], v[228:229], 0, v[66:67]
	global_load_dwordx2 v[216:217], v[228:229], off
	v_lshlrev_b32_e32 v48, 16, v42
	v_and_b32_e32 v49, 0xffff0000, v42
	v_pk_fma_f32 v[38:39], v[38:39], v[48:49], v[44:45]
	v_lshlrev_b32_e32 v44, 16, v126
	v_and_b32_e32 v45, 0xffff0000, v126
	v_lshlrev_b32_e32 v42, 16, v43
	v_and_b32_e32 v43, 0xffff0000, v43
	v_pk_fma_f32 v[40:41], v[40:41], v[42:43], v[44:45]
	v_cvt_pk_bf16_f32 v38, v38, v39
	v_cvt_pk_bf16_f32 v39, v40, v41
	global_store_dwordx2 v[46:47], v[38:39], off offset:64
	v_lshlrev_b32_e32 v40, 16, v125
	v_and_b32_e32 v41, 0xffff0000, v125
	v_mfma_f32_16x16x32_bf16 v[18:21], v[194:197], v[174:177], v[98:101]
	s_waitcnt vmcnt(9)
	v_mov_b32_e32 v38, v222
	v_mov_b32_e32 v39, v223
	v_lshl_add_u64 v[228:229], v[74:75], 0, s[36:37]
	v_lshl_add_u64 v[228:229], v[228:229], 0, v[70:71]
	global_load_dwordx2 v[222:223], v[228:229], off
	v_lshlrev_b32_e32 v42, 16, v38
	v_and_b32_e32 v43, 0xffff0000, v38
	v_pk_fma_f32 v[34:35], v[34:35], v[42:43], v[40:41]
	v_lshlrev_b32_e32 v40, 16, v124
	v_and_b32_e32 v41, 0xffff0000, v124
	v_lshlrev_b32_e32 v38, 16, v39
	v_and_b32_e32 v39, 0xffff0000, v39
	v_pk_fma_f32 v[36:37], v[36:37], v[38:39], v[40:41]
	v_cvt_pk_bf16_f32 v34, v34, v35
	v_cvt_pk_bf16_f32 v35, v36, v37
	global_store_dwordx2 v[46:47], v[34:35], off offset:96
	v_lshl_add_u64 v[34:35], v[78:79], 0, s[36:37]
	v_lshlrev_b32_e32 v40, 16, v123
	v_and_b32_e32 v41, 0xffff0000, v123
	v_lshlrev_b64 v[36:37], 11, v[80:81]
	v_mfma_f32_16x16x32_bf16 v[14:17], v[182:185], v[178:181], v[148:151]
	s_waitcnt vmcnt(9)
; DI unsigned pk2(float a, float b) { f32x2 v = {a, b}; bfv2 r = __builtin_convertvector(v, bfv2); return __builtin_bit_cast(unsigned, r); }
; DI float bf_lo(unsigned u) { return __uint_as_float(u << 16); }
; DI float bf_hi(unsigned u) { return __uint_as_float(u & 0xffff0000u); }
; DI void phase_merge(const Params& p, int l, char* lds) {
;     ...
; #pragma unroll
;     for (int mi = 0; mi < 4; ++mi) {
;       const int R = mt * 128 + wm * 64 + mi * 16 + l15;
; #pragma unroll
;       for (int ni = 0; ni < 4; ++ni) {
;         const int c = nt * 128 + wn * 64 + ni * 16 + quad * 4;
;         const u32x2 g2 = *(const u32x2*)(p.z + (size_t)R * NZ + C_MA + c);
;         const f32x4 v2 = a1[mi][ni]; const u32x2 u1 = pk[mi][ni];
;         u32x2 o;
;         o[0] = pk2(bf_lo(u1[0]) + bf_lo(g2[0]) * v2[0], bf_hi(u1[0]) + bf_hi(g2[0]) * v2[1]);
;         o[1] = pk2(bf_lo(u1[1]) + bf_lo(g2[1]) * v2[2], bf_hi(u1[1]) + bf_hi(g2[1]) * v2[3]);
;         *(u32x2*)(p.hn + (size_t)R * DM + c) = o;
;       }
	v_mov_b32_e32 v38, v224
	v_mov_b32_e32 v39, v225
	v_lshl_add_u64 v[228:229], v[74:75], 0, s[36:37]
	v_lshl_add_u64 v[228:229], v[228:229], 0, v[72:73]
	global_load_dwordx2 v[224:225], v[228:229], off
	v_lshlrev_b32_e32 v42, 16, v38
	v_and_b32_e32 v43, 0xffff0000, v38
	v_pk_fma_f32 v[30:31], v[30:31], v[42:43], v[40:41]
	v_lshlrev_b32_e32 v40, 16, v39
	v_cvt_pk_bf16_f32 v38, v30, v31
	v_lshlrev_b32_e32 v30, 16, v122
	v_and_b32_e32 v31, 0xffff0000, v122
	v_and_b32_e32 v41, 0xffff0000, v39
	v_pk_fma_f32 v[30:31], v[32:33], v[40:41], v[30:31]
	v_cvt_pk_bf16_f32 v39, v30, v31
	v_lshl_add_u64 v[30:31], s[8:9], 0, v[36:37]
	v_lshl_add_u64 v[30:31], v[30:31], 0, v[70:71]
	global_store_dwordx2 v[30:31], v[38:39], off
	v_lshlrev_b32_e32 v36, 16, v121
	v_and_b32_e32 v37, 0xffff0000, v121
	v_mfma_f32_16x16x32_bf16 v[10:13], v[186:189], v[178:181], v[152:155]
	s_waitcnt vmcnt(9)
	v_mov_b32_e32 v32, v226
	v_mov_b32_e32 v33, v227
	v_lshl_add_u64 v[228:229], v[74:75], 0, s[36:37]
	v_lshl_add_u64 v[228:229], v[228:229], 0, v[68:69]
	global_load_dwordx2 v[226:227], v[228:229], off
	v_lshlrev_b32_e32 v38, 16, v32
	v_and_b32_e32 v39, 0xffff0000, v32
	v_pk_fma_f32 v[26:27], v[26:27], v[38:39], v[36:37]
	v_lshlrev_b32_e32 v36, 16, v120
	v_and_b32_e32 v37, 0xffff0000, v120
	v_lshlrev_b32_e32 v32, 16, v33
	v_and_b32_e32 v33, 0xffff0000, v33
	v_pk_fma_f32 v[28:29], v[28:29], v[32:33], v[36:37]
	v_cvt_pk_bf16_f32 v26, v26, v27
	v_cvt_pk_bf16_f32 v27, v28, v29
	global_store_dwordx2 v[30:31], v[26:27], off offset:32
	v_lshlrev_b32_e32 v28, 16, v119
	v_and_b32_e32 v29, 0xffff0000, v119
	v_mfma_f32_16x16x32_bf16 v[6:9], v[190:193], v[178:181], v[156:159]
	s_waitcnt vmcnt(9)
	v_mov_b32_e32 v26, v214
	v_mov_b32_e32 v27, v215
	v_lshl_add_u64 v[228:229], v[74:75], 0, s[36:37]
	v_lshl_add_u64 v[228:229], v[228:229], 0, v[66:67]
	global_load_dwordx2 v[214:215], v[228:229], off
	v_lshlrev_b32_e32 v32, 16, v26
	v_and_b32_e32 v33, 0xffff0000, v26
	v_pk_fma_f32 v[22:23], v[22:23], v[32:33], v[28:29]
	v_lshlrev_b32_e32 v28, 16, v118
	v_and_b32_e32 v29, 0xffff0000, v118
	v_lshlrev_b32_e32 v26, 16, v27
	v_and_b32_e32 v27, 0xffff0000, v27
	v_pk_fma_f32 v[24:25], v[24:25], v[26:27], v[28:29]
	v_cvt_pk_bf16_f32 v22, v22, v23
	v_cvt_pk_bf16_f32 v23, v24, v25
	global_store_dwordx2 v[30:31], v[22:23], off offset:64
	v_lshlrev_b32_e32 v24, 16, v117
	v_and_b32_e32 v25, 0xffff0000, v117
	v_mfma_f32_16x16x32_bf16 v[2:5], v[194:197], v[178:181], v[102:105]
	s_waitcnt vmcnt(9)
	v_mov_b32_e32 v22, v216
	v_mov_b32_e32 v23, v217
	v_lshlrev_b32_e32 v26, 16, v22
	v_and_b32_e32 v27, 0xffff0000, v22
	v_pk_fma_f32 v[18:19], v[18:19], v[26:27], v[24:25]
	v_lshlrev_b32_e32 v24, 16, v116
	v_and_b32_e32 v25, 0xffff0000, v116
	v_lshlrev_b32_e32 v22, 16, v23
	v_and_b32_e32 v23, 0xffff0000, v23
	v_pk_fma_f32 v[20:21], v[20:21], v[22:23], v[24:25]
	v_cvt_pk_bf16_f32 v18, v18, v19
	v_cvt_pk_bf16_f32 v19, v20, v21
	global_store_dwordx2 v[30:31], v[18:19], off offset:96
	v_lshl_add_u64 v[18:19], v[74:75], 0, s[36:37]
	v_lshlrev_b32_e32 v24, 16, v115
	v_and_b32_e32 v25, 0xffff0000, v115
	v_lshlrev_b64 v[20:21], 11, v[76:77]
	s_waitcnt vmcnt(8)
	v_mov_b32_e32 v22, v222
	v_mov_b32_e32 v23, v223
	v_lshlrev_b32_e32 v26, 16, v22
	v_and_b32_e32 v27, 0xffff0000, v22
	v_pk_fma_f32 v[14:15], v[14:15], v[26:27], v[24:25]
	v_lshlrev_b32_e32 v24, 16, v23
	v_cvt_pk_bf16_f32 v22, v14, v15
	v_lshlrev_b32_e32 v14, 16, v114
	v_and_b32_e32 v15, 0xffff0000, v114
	v_and_b32_e32 v25, 0xffff0000, v23
	v_pk_fma_f32 v[14:15], v[16:17], v[24:25], v[14:15]
	v_cvt_pk_bf16_f32 v23, v14, v15
	v_lshl_add_u64 v[14:15], s[8:9], 0, v[20:21]
	v_lshl_add_u64 v[14:15], v[14:15], 0, v[70:71]
	global_store_dwordx2 v[14:15], v[22:23], off
	v_lshlrev_b32_e32 v20, 16, v113
	v_and_b32_e32 v21, 0xffff0000, v113
	s_waitcnt vmcnt(7)
	v_mov_b32_e32 v16, v224
	v_mov_b32_e32 v17, v225
	v_lshlrev_b32_e32 v22, 16, v16
	v_and_b32_e32 v23, 0xffff0000, v16
	v_pk_fma_f32 v[10:11], v[10:11], v[22:23], v[20:21]
	v_lshlrev_b32_e32 v20, 16, v112
	v_and_b32_e32 v21, 0xffff0000, v112
	v_lshlrev_b32_e32 v16, 16, v17
	v_and_b32_e32 v17, 0xffff0000, v17
	v_pk_fma_f32 v[12:13], v[12:13], v[16:17], v[20:21]
	v_cvt_pk_bf16_f32 v10, v10, v11
	v_cvt_pk_bf16_f32 v11, v12, v13
	global_store_dwordx2 v[14:15], v[10:11], off offset:32
	v_lshlrev_b32_e32 v12, 16, v111
	v_and_b32_e32 v13, 0xffff0000, v111
	s_waitcnt vmcnt(6)
	v_mov_b32_e32 v10, v226
	v_mov_b32_e32 v11, v227
	v_lshlrev_b32_e32 v16, 16, v10
	v_and_b32_e32 v17, 0xffff0000, v10
	v_pk_fma_f32 v[6:7], v[6:7], v[16:17], v[12:13]
	v_lshlrev_b32_e32 v12, 16, v110
	v_and_b32_e32 v13, 0xffff0000, v110
	v_lshlrev_b32_e32 v10, 16, v11
	v_and_b32_e32 v11, 0xffff0000, v11
	v_pk_fma_f32 v[8:9], v[8:9], v[10:11], v[12:13]
	v_cvt_pk_bf16_f32 v6, v6, v7
	v_cvt_pk_bf16_f32 v7, v8, v9
	global_store_dwordx2 v[14:15], v[6:7], off offset:64
	v_lshlrev_b32_e32 v8, 16, v109
	v_and_b32_e32 v9, 0xffff0000, v109
	s_waitcnt vmcnt(5)
	v_mov_b32_e32 v6, v214
	v_mov_b32_e32 v7, v215
	v_lshlrev_b32_e32 v10, 16, v6
	v_and_b32_e32 v11, 0xffff0000, v6
	v_pk_fma_f32 v[2:3], v[2:3], v[10:11], v[8:9]
	v_lshlrev_b32_e32 v8, 16, v108
	v_and_b32_e32 v9, 0xffff0000, v108
	v_lshlrev_b32_e32 v6, 16, v7
	v_and_b32_e32 v7, 0xffff0000, v7
	v_pk_fma_f32 v[4:5], v[4:5], v[6:7], v[8:9]
	v_cvt_pk_bf16_f32 v2, v2, v3
	v_cvt_pk_bf16_f32 v3, v4, v5
	global_store_dwordx2 v[14:15], v[2:3], off offset:96
	s_cbranch_scc0 .LBB0_722
